# GEMM K-loop MFMA issue order changed to keep srcA constant for 4 consecutive MFMAs with serpentine srcB (operand-toggle reduction), bit-identical
# baseline (speedup 1.0000x reference)
; #define PG8_STAGE(bufoff, gbase, voff) do { _Pragma("unroll") for (int _i = 0; _i < 2; ++_i) \
;         __builtin_amdgcn_global_load_lds((const unsigned*)((const char*)(gbase) + (voff)[_i]), (PG8_LAS unsigned*)(lds + (bufoff) + ldsw + _i * 8192), 16, 0, 0); } while (0)
; #define PG8_LDA(dst, b, h) do { _Pragma("unroll") for (int m = 0; m < 4; ++m) _Pragma("unroll") for (int k = 0; k < 2; ++k) dst[m][k] = *(const PG8_LAS bf16x8*)(lds + PG8_SA(b, h) + aoff + m * 2048 + k * 1024); } while (0)
; #define PG8_LDB(dst, b, h) do { _Pragma("unroll") for (int n = 0; n < 2; ++n) _Pragma("unroll") for (int k = 0; k < 2; ++k) dst[n][k] = *(const PG8_LAS bf16x8*)(lds + PG8_SB(b, h) + boff + n * 2048 + k * 1024); } while (0)
; #define PG8_MMA(ai, bj, At, Bt) do { __builtin_amdgcn_s_setprio(1); _Pragma("unroll") for (int m = 0; m < 4; ++m) _Pragma("unroll") for (int n = 0; n < 2; ++n) _Pragma("unroll") for (int k = 0; k < 2; ++k) \
;         acc[ai][bj][m][n] = __builtin_amdgcn_mfma_f32_16x16x32_bf16(Bt[n][k], At[m][k], acc[ai][bj][m][n], 0, 0, 0); __builtin_amdgcn_s_setprio(0); } while (0)
; #define PG8_WAIT_V(n) asm volatile("s_waitcnt vmcnt(" #n ")" ::: "memory")
; #define PG8_WAIT_L(n) asm volatile("s_waitcnt lgkmcnt(" #n ")" ::: "memory")
; #define PG8_BAR __builtin_amdgcn_s_barrier()
; #define PG8_SCHED __builtin_amdgcn_sched_barrier(0)
; template <class Epi, class Sched, bool ALIGN_EPI = false, bool SP2 = false>
; __device__ __forceinline__ void gemm_phase(PG8_LAS unsigned char* lds, const Gemm g, const Sched& S, const Epi& E) {
;     ...
;             const bool last = (t == nt - 2);
;             const char* a1 = cA + (size_t)(t + 1) * kstep;
;             const char* a2 = last ? nA : cA + (size_t)(t + 2) * kstep; const char* b2 = last ? nB : cB + (size_t)(t + 2) * kstep;
;             const char* a3 = a2 + kstep; const char* b3 = b2 + kstep;
;             if (last && has_next) S.a_ready(nxt);
;             if constexpr (SP2) {
;             PG8_LDB(B0, 0, 0); PG8_LDB(B1, 0, 1); PG8_SCHED; PG8_LDA(At, 0, 0); PG8_STAGE(PG8_SA(1, 1), a1 + hstep, voffA);
;             PG8_WAIT_V(8); PG8_WAIT_L(0); PG8_BAR; PG8_MMA(0, 0, At, B0); PG8_MMA(0, 1, At, B1); PG8_BAR; PG8_SCHED;
;             PG8_LDA(At, 0, 1); PG8_STAGE(PG8_SB(0, 0), b2, voffB); PG8_STAGE(PG8_SB(0, 1), b2 + hstep, voffB); PG8_STAGE(PG8_SA(0, 0), a2, voffA);
.LBB0_93:
	ds_read_b128 v[146:149], v153
	ds_read_b128 v[156:159], v153 offset:1024
	ds_read_b128 v[160:163], v153 offset:2048
	ds_read_b128 v[164:167], v153 offset:3072
	ds_read_b128 v[168:171], v154
	ds_read_b128 v[172:175], v154 offset:1024
	ds_read_b128 v[176:179], v154 offset:2048
	ds_read_b128 v[184:187], v154 offset:3072
	s_add_u32 s48, s44, 0xfff80080
	s_addc_u32 s49, s45, -1
	s_cmp_eq_u32 s89, 28
	s_cselect_b32 s59, s25, s49
	s_cselect_b32 s58, s84, s48
	s_cselect_b32 s49, s13, s87
	s_cselect_b32 s48, s85, s86
	v_lshl_add_u64 v[180:181], s[44:45], 0, v[136:137]
	s_add_i32 m0, s35, 0xc000
	ds_read_b128 v[188:191], v155
	ds_read_b128 v[192:195], v155 offset:1024
	ds_read_b128 v[196:199], v155 offset:2048
	ds_read_b128 v[200:203], v155 offset:3072
	ds_read_b128 v[204:207], v155 offset:4096
	ds_read_b128 v[208:211], v155 offset:5120
	ds_read_b128 v[212:215], v155 offset:6144
	ds_read_b128 v[216:219], v155 offset:7168
	global_load_lds_dwordx4 v[180:181], off
	v_lshl_add_u64 v[180:181], s[44:45], 0, v[138:139]
	s_add_i32 m0, s35, 0xe000
	s_nop 0
	global_load_lds_dwordx4 v[180:181], off
	s_waitcnt vmcnt(8)
	s_waitcnt lgkmcnt(0)
	s_barrier
	s_setprio 1
	s_waitcnt lgkmcnt(0)
	v_mfma_f32_16x16x32_bf16 v[124:127], v[146:149], v[188:191], v[124:127]
	v_mfma_f32_16x16x32_bf16 v[108:111], v[146:149], v[196:199], v[108:111]
	v_mfma_f32_16x16x32_bf16 v[92:95], v[146:149], v[204:207], v[92:95]
	v_mfma_f32_16x16x32_bf16 v[76:79], v[146:149], v[212:215], v[76:79]
	v_mfma_f32_16x16x32_bf16 v[72:75], v[160:163], v[212:215], v[72:75]
	v_mfma_f32_16x16x32_bf16 v[88:91], v[160:163], v[204:207], v[88:91]
	v_mfma_f32_16x16x32_bf16 v[104:107], v[160:163], v[196:199], v[104:107]
	v_mfma_f32_16x16x32_bf16 v[120:123], v[160:163], v[188:191], v[120:123]
	v_mfma_f32_16x16x32_bf16 v[124:127], v[156:159], v[192:195], v[124:127]
	v_mfma_f32_16x16x32_bf16 v[108:111], v[156:159], v[200:203], v[108:111]
	v_mfma_f32_16x16x32_bf16 v[92:95], v[156:159], v[208:211], v[92:95]
	v_mfma_f32_16x16x32_bf16 v[76:79], v[156:159], v[216:219], v[76:79]
	v_mfma_f32_16x16x32_bf16 v[72:75], v[164:167], v[216:219], v[72:75]
	v_mfma_f32_16x16x32_bf16 v[88:91], v[164:167], v[208:211], v[88:91]
	v_mfma_f32_16x16x32_bf16 v[104:107], v[164:167], v[200:203], v[104:107]
	v_mfma_f32_16x16x32_bf16 v[120:123], v[164:167], v[192:195], v[120:123]
	s_setprio 0
	s_setprio 1
	v_mfma_f32_16x16x32_bf16 v[116:119], v[168:171], v[188:191], v[116:119]
	v_mfma_f32_16x16x32_bf16 v[100:103], v[168:171], v[196:199], v[100:103]
	v_mfma_f32_16x16x32_bf16 v[84:87], v[168:171], v[204:207], v[84:87]
	v_mfma_f32_16x16x32_bf16 v[68:71], v[168:171], v[212:215], v[68:71]
	v_mfma_f32_16x16x32_bf16 v[64:67], v[176:179], v[212:215], v[64:67]
	v_mfma_f32_16x16x32_bf16 v[80:83], v[176:179], v[204:207], v[80:83]
	v_mfma_f32_16x16x32_bf16 v[96:99], v[176:179], v[196:199], v[96:99]
	v_mfma_f32_16x16x32_bf16 v[112:115], v[176:179], v[188:191], v[112:115]
	v_mfma_f32_16x16x32_bf16 v[116:119], v[172:175], v[192:195], v[116:119]
	v_mfma_f32_16x16x32_bf16 v[100:103], v[172:175], v[200:203], v[100:103]
	v_mfma_f32_16x16x32_bf16 v[84:87], v[172:175], v[208:211], v[84:87]
	v_mfma_f32_16x16x32_bf16 v[68:71], v[172:175], v[216:219], v[68:71]
	v_mfma_f32_16x16x32_bf16 v[64:67], v[184:187], v[216:219], v[64:67]
	v_mfma_f32_16x16x32_bf16 v[80:83], v[184:187], v[208:211], v[80:83]
	v_mfma_f32_16x16x32_bf16 v[96:99], v[184:187], v[200:203], v[96:99]
	v_mfma_f32_16x16x32_bf16 v[112:115], v[184:187], v[192:195], v[112:115]
	s_setprio 0
	s_barrier
	s_add_i32 s90, s66, s29
	v_lshl_add_u64 v[180:181], s[48:49], 0, v[130:131]
	s_mov_b32 m0, s90
	ds_read_b128 v[188:191], v155 offset:16384
	ds_read_b128 v[192:195], v155 offset:17408
	ds_read_b128 v[196:199], v155 offset:18432
	ds_read_b128 v[200:203], v155 offset:19456
	ds_read_b128 v[204:207], v155 offset:20480
	ds_read_b128 v[208:211], v155 offset:21504
	ds_read_b128 v[212:215], v155 offset:22528
	ds_read_b128 v[216:219], v155 offset:23552
	global_load_lds_dwordx4 v[180:181], off
	s_add_i32 m0, s90, 0x2000
	s_add_u32 s92, s48, 0x80000
	v_lshl_add_u64 v[220:221], s[48:49], 0, v[134:135]
	s_addc_u32 s93, s49, 0
	s_add_i32 s90, s67, s29
	global_load_lds_dwordx4 v[220:221], off
	v_lshl_add_u64 v[222:223], s[92:93], 0, v[130:131]
	s_mov_b32 m0, s90
	v_lshl_add_u64 v[224:225], s[58:59], 0, v[132:133]
	global_load_lds_dwordx4 v[222:223], off
	v_lshl_add_u64 v[222:223], s[92:93], 0, v[134:135]
	s_add_i32 m0, s90, 0x2000
	s_nop 0
	global_load_lds_dwordx4 v[222:223], off
	v_lshl_add_u64 v[222:223], s[58:59], 0, v[128:129]
	s_mov_b32 m0, s35
	s_nop 0
	global_load_lds_dwordx4 v[222:223], off
	s_mov_b32 m0, s43
	s_nop 0
	global_load_lds_dwordx4 v[224:225], off
	s_waitcnt vmcnt(8)
	s_waitcnt lgkmcnt(0)
	s_barrier
; #define PG8_STAGE(bufoff, gbase, voff) do { _Pragma("unroll") for (int _i = 0; _i < 2; ++_i) \
;         __builtin_amdgcn_global_load_lds((const unsigned*)((const char*)(gbase) + (voff)[_i]), (PG8_LAS unsigned*)(lds + (bufoff) + ldsw + _i * 8192), 16, 0, 0); } while (0)
; #define PG8_LDA(dst, b, h) do { _Pragma("unroll") for (int m = 0; m < 4; ++m) _Pragma("unroll") for (int k = 0; k < 2; ++k) dst[m][k] = *(const PG8_LAS bf16x8*)(lds + PG8_SA(b, h) + aoff + m * 2048 + k * 1024); } while (0)
; #define PG8_LDB(dst, b, h) do { _Pragma("unroll") for (int n = 0; n < 2; ++n) _Pragma("unroll") for (int k = 0; k < 2; ++k) dst[n][k] = *(const PG8_LAS bf16x8*)(lds + PG8_SB(b, h) + boff + n * 2048 + k * 1024); } while (0)
; #define PG8_MMA(ai, bj, At, Bt) do { __builtin_amdgcn_s_setprio(1); _Pragma("unroll") for (int m = 0; m < 4; ++m) _Pragma("unroll") for (int n = 0; n < 2; ++n) _Pragma("unroll") for (int k = 0; k < 2; ++k) \
;         acc[ai][bj][m][n] = __builtin_amdgcn_mfma_f32_16x16x32_bf16(Bt[n][k], At[m][k], acc[ai][bj][m][n], 0, 0, 0); __builtin_amdgcn_s_setprio(0); } while (0)
; #define PG8_WAIT_V(n) asm volatile("s_waitcnt vmcnt(" #n ")" ::: "memory")
; #define PG8_WAIT_L(n) asm volatile("s_waitcnt lgkmcnt(" #n ")" ::: "memory")
; #define PG8_BAR __builtin_amdgcn_s_barrier()
; #define PG8_SCHED __builtin_amdgcn_sched_barrier(0)
; template <class Epi, class Sched, bool ALIGN_EPI = false, bool SP2 = false>
; __device__ __forceinline__ void gemm_phase(PG8_LAS unsigned char* lds, const Gemm g, const Sched& S, const Epi& E) {
;     ...
;             PG8_WAIT_V(8); PG8_WAIT_L(0); PG8_BAR; PG8_MMA(1, 0, At, B0); PG8_MMA(1, 1, At, B1); PG8_BAR; PG8_SCHED;
;             PG8_LDB(B0, 1, 0); PG8_LDB(B1, 1, 1); PG8_SCHED; PG8_LDA(At, 1, 0); PG8_STAGE(PG8_SA(0, 1), a2 + hstep, voffA);
;             PG8_WAIT_V(8); PG8_WAIT_L(0); PG8_BAR; PG8_MMA(0, 0, At, B0); PG8_MMA(0, 1, At, B1); PG8_BAR; PG8_SCHED;
;             PG8_LDA(At, 1, 1); PG8_STAGE(PG8_SB(1, 0), b3, voffB); PG8_STAGE(PG8_SB(1, 1), b3 + hstep, voffB); PG8_STAGE(PG8_SA(1, 0), a3, voffA);
	s_setprio 1
	s_waitcnt lgkmcnt(0)
	v_mfma_f32_16x16x32_bf16 v[60:63], v[146:149], v[188:191], v[60:63]
	v_mfma_f32_16x16x32_bf16 v[44:47], v[146:149], v[196:199], v[44:47]
	v_mfma_f32_16x16x32_bf16 v[28:31], v[146:149], v[204:207], v[28:31]
	v_mfma_f32_16x16x32_bf16 v[12:15], v[146:149], v[212:215], v[12:15]
	v_mfma_f32_16x16x32_bf16 v[8:11], v[160:163], v[212:215], v[8:11]
	v_mfma_f32_16x16x32_bf16 v[24:27], v[160:163], v[204:207], v[24:27]
	v_mfma_f32_16x16x32_bf16 v[40:43], v[160:163], v[196:199], v[40:43]
	v_mfma_f32_16x16x32_bf16 v[56:59], v[160:163], v[188:191], v[56:59]
	v_mfma_f32_16x16x32_bf16 v[60:63], v[156:159], v[192:195], v[60:63]
	v_mfma_f32_16x16x32_bf16 v[44:47], v[156:159], v[200:203], v[44:47]
	v_mfma_f32_16x16x32_bf16 v[28:31], v[156:159], v[208:211], v[28:31]
	v_mfma_f32_16x16x32_bf16 v[12:15], v[156:159], v[216:219], v[12:15]
	v_mfma_f32_16x16x32_bf16 v[8:11], v[164:167], v[216:219], v[8:11]
	v_mfma_f32_16x16x32_bf16 v[24:27], v[164:167], v[208:211], v[24:27]
	v_mfma_f32_16x16x32_bf16 v[40:43], v[164:167], v[200:203], v[40:43]
	v_mfma_f32_16x16x32_bf16 v[56:59], v[164:167], v[192:195], v[56:59]
	s_setprio 0
	s_setprio 1
	v_mfma_f32_16x16x32_bf16 v[52:55], v[168:171], v[188:191], v[52:55]
	v_mfma_f32_16x16x32_bf16 v[36:39], v[168:171], v[196:199], v[36:39]
	v_mfma_f32_16x16x32_bf16 v[20:23], v[168:171], v[204:207], v[20:23]
	v_mfma_f32_16x16x32_bf16 v[4:7], v[168:171], v[212:215], v[4:7]
	v_mfma_f32_16x16x32_bf16 v[0:3], v[176:179], v[212:215], v[0:3]
	v_mfma_f32_16x16x32_bf16 v[16:19], v[176:179], v[204:207], v[16:19]
	v_mfma_f32_16x16x32_bf16 v[32:35], v[176:179], v[196:199], v[32:35]
	v_mfma_f32_16x16x32_bf16 v[48:51], v[176:179], v[188:191], v[48:51]
	v_mfma_f32_16x16x32_bf16 v[52:55], v[172:175], v[192:195], v[52:55]
	v_mfma_f32_16x16x32_bf16 v[36:39], v[172:175], v[200:203], v[36:39]
	v_mfma_f32_16x16x32_bf16 v[20:23], v[172:175], v[208:211], v[20:23]
	v_mfma_f32_16x16x32_bf16 v[4:7], v[172:175], v[216:219], v[4:7]
	v_mfma_f32_16x16x32_bf16 v[0:3], v[184:187], v[216:219], v[0:3]
	v_mfma_f32_16x16x32_bf16 v[16:19], v[184:187], v[208:211], v[16:19]
	v_mfma_f32_16x16x32_bf16 v[32:35], v[184:187], v[200:203], v[32:35]
	v_mfma_f32_16x16x32_bf16 v[48:51], v[184:187], v[192:195], v[48:51]
	s_setprio 0
	s_barrier
	s_add_i32 s90, 0, 0x18000
	s_add_i32 s92, 0, 0x1c000
	v_add_u32_e32 v164, s90, v151
	v_add_u32_e32 v184, s92, v151
	ds_read_b128 v[146:149], v164
	ds_read_b128 v[156:159], v164 offset:1024
	ds_read_b128 v[160:163], v164 offset:2048
	ds_read_b128 v[164:167], v164 offset:3072
	ds_read_b128 v[168:171], v184
	ds_read_b128 v[172:175], v184 offset:1024
	ds_read_b128 v[176:179], v184 offset:2048
	ds_read_b128 v[184:187], v184 offset:3072
	s_add_u32 s58, s58, 0x80000
	s_addc_u32 s59, s59, 0
	s_mov_b32 m0, s60
	v_lshl_add_u64 v[226:227], s[58:59], 0, v[128:129]
	ds_read_b128 v[188:191], v155 offset:32768
	ds_read_b128 v[192:195], v155 offset:33792
	ds_read_b128 v[196:199], v155 offset:34816
	ds_read_b128 v[200:203], v155 offset:35840
	ds_read_b128 v[204:207], v155 offset:36864
	ds_read_b128 v[208:211], v155 offset:37888
	ds_read_b128 v[212:215], v155 offset:38912
	ds_read_b128 v[216:219], v155 offset:39936
	global_load_lds_dwordx4 v[226:227], off
	v_lshl_add_u64 v[226:227], s[58:59], 0, v[132:133]
	s_mov_b32 m0, s61
	s_nop 0
	global_load_lds_dwordx4 v[226:227], off
	s_waitcnt vmcnt(8)
	s_waitcnt lgkmcnt(0)
	s_barrier
	s_setprio 1
	s_waitcnt lgkmcnt(0)
	v_mfma_f32_16x16x32_bf16 v[124:127], v[146:149], v[188:191], v[124:127]
	v_mfma_f32_16x16x32_bf16 v[108:111], v[146:149], v[196:199], v[108:111]
	v_mfma_f32_16x16x32_bf16 v[92:95], v[146:149], v[204:207], v[92:95]
	v_mfma_f32_16x16x32_bf16 v[76:79], v[146:149], v[212:215], v[76:79]
	v_mfma_f32_16x16x32_bf16 v[72:75], v[160:163], v[212:215], v[72:75]
	v_mfma_f32_16x16x32_bf16 v[88:91], v[160:163], v[204:207], v[88:91]
	v_mfma_f32_16x16x32_bf16 v[104:107], v[160:163], v[196:199], v[104:107]
	v_mfma_f32_16x16x32_bf16 v[120:123], v[160:163], v[188:191], v[120:123]
	v_mfma_f32_16x16x32_bf16 v[124:127], v[156:159], v[192:195], v[124:127]
	v_mfma_f32_16x16x32_bf16 v[108:111], v[156:159], v[200:203], v[108:111]
	v_mfma_f32_16x16x32_bf16 v[92:95], v[156:159], v[208:211], v[92:95]
	v_mfma_f32_16x16x32_bf16 v[76:79], v[156:159], v[216:219], v[76:79]
	v_mfma_f32_16x16x32_bf16 v[72:75], v[164:167], v[216:219], v[72:75]
	v_mfma_f32_16x16x32_bf16 v[88:91], v[164:167], v[208:211], v[88:91]
	v_mfma_f32_16x16x32_bf16 v[104:107], v[164:167], v[200:203], v[104:107]
	v_mfma_f32_16x16x32_bf16 v[120:123], v[164:167], v[192:195], v[120:123]
	s_setprio 0
	s_setprio 1
	v_mfma_f32_16x16x32_bf16 v[116:119], v[168:171], v[188:191], v[116:119]
	v_mfma_f32_16x16x32_bf16 v[100:103], v[168:171], v[196:199], v[100:103]
	v_mfma_f32_16x16x32_bf16 v[84:87], v[168:171], v[204:207], v[84:87]
	v_mfma_f32_16x16x32_bf16 v[68:71], v[168:171], v[212:215], v[68:71]
	v_mfma_f32_16x16x32_bf16 v[64:67], v[176:179], v[212:215], v[64:67]
	v_mfma_f32_16x16x32_bf16 v[80:83], v[176:179], v[204:207], v[80:83]
	v_mfma_f32_16x16x32_bf16 v[96:99], v[176:179], v[196:199], v[96:99]
	v_mfma_f32_16x16x32_bf16 v[112:115], v[176:179], v[188:191], v[112:115]
	v_mfma_f32_16x16x32_bf16 v[116:119], v[172:175], v[192:195], v[116:119]
	v_mfma_f32_16x16x32_bf16 v[100:103], v[172:175], v[200:203], v[100:103]
	v_mfma_f32_16x16x32_bf16 v[84:87], v[172:175], v[208:211], v[84:87]
	v_mfma_f32_16x16x32_bf16 v[68:71], v[172:175], v[216:219], v[68:71]
	v_mfma_f32_16x16x32_bf16 v[64:67], v[184:187], v[216:219], v[64:67]
	v_mfma_f32_16x16x32_bf16 v[80:83], v[184:187], v[208:211], v[80:83]
	v_mfma_f32_16x16x32_bf16 v[96:99], v[184:187], v[200:203], v[96:99]
	v_mfma_f32_16x16x32_bf16 v[112:115], v[184:187], v[192:195], v[112:115]
	s_setprio 0
	s_barrier
; #define PG8_STAGE(bufoff, gbase, voff) do { _Pragma("unroll") for (int _i = 0; _i < 2; ++_i) \
;         __builtin_amdgcn_global_load_lds((const unsigned*)((const char*)(gbase) + (voff)[_i]), (PG8_LAS unsigned*)(lds + (bufoff) + ldsw + _i * 8192), 16, 0, 0); } while (0)
; #define PG8_LDA(dst, b, h) do { _Pragma("unroll") for (int m = 0; m < 4; ++m) _Pragma("unroll") for (int k = 0; k < 2; ++k) dst[m][k] = *(const PG8_LAS bf16x8*)(lds + PG8_SA(b, h) + aoff + m * 2048 + k * 1024); } while (0)
; #define PG8_WAIT_V(n) asm volatile("s_waitcnt vmcnt(" #n ")" ::: "memory")
; template <class Epi, class Sched, bool ALIGN_EPI = false, bool SP2 = false>
; __device__ __forceinline__ void gemm_phase(PG8_LAS unsigned char* lds, const Gemm g, const Sched& S, const Epi& E) {
;     ...
;             PG8_LDA(At, 1, 1); PG8_STAGE(PG8_SB(1, 0), b3, voffB); PG8_STAGE(PG8_SB(1, 1), b3 + hstep, voffB); PG8_STAGE(PG8_SA(1, 0), a3, voffA);
;             PG8_WAIT_V(8); PG8_WAIT_L(0); PG8_BAR; PG8_MMA(1, 0, At, B0); PG8_MMA(1, 1, At, B1); PG8_BAR; PG8_SCHED;
;             } else {
;             PG8_LDB(B0, 0, 0); PG8_SCHED; PG8_LDA(At, 0, 0); PG8_STAGE(PG8_SA(1, 1), a1 + hstep, voffA);
;             PG8_WAIT_L(8); PG8_BAR; PG8_WAIT_L(0); PG8_MMA(0, 0, At, B0); PG8_BAR; PG8_SCHED;
;             PG8_LDB(B1, 0, 1); PG8_STAGE(PG8_SB(0, 0), b2, voffB);
;             PG8_BAR; PG8_WAIT_L(0); PG8_MMA(0, 1, At, B1); PG8_BAR;
;             PG8_LDA(At, 0, 1); PG8_STAGE(PG8_SA(0, 0), a2, voffA);
;             PG8_BAR; PG8_WAIT_L(0); PG8_MMA(1, 0, At, B0); PG8_BAR; PG8_SCHED;
;             PG8_STAGE(PG8_SB(0, 1), b2 + hstep, voffB);
;             PG8_WAIT_V(6); PG8_BAR; PG8_MMA(1, 1, At, B1); PG8_BAR;
;             PG8_LDB(B0, 1, 0); PG8_SCHED; PG8_LDA(At, 1, 0); PG8_STAGE(PG8_SA(0, 1), a2 + hstep, voffA);
;             PG8_WAIT_L(8); PG8_BAR; PG8_WAIT_L(0); PG8_MMA(0, 0, At, B0); PG8_BAR; PG8_SCHED;
;             PG8_LDB(B1, 1, 1); PG8_STAGE(PG8_SB(1, 0), b3, voffB);
;             PG8_BAR; PG8_WAIT_L(0); PG8_MMA(0, 1, At, B1); PG8_BAR;
;             PG8_LDA(At, 1, 1); PG8_STAGE(PG8_SA(1, 0), a3, voffA);
;             PG8_BAR; PG8_WAIT_L(0); PG8_MMA(1, 0, At, B0); PG8_BAR; PG8_SCHED;
;             PG8_STAGE(PG8_SB(1, 1), b3 + hstep, voffB);
;             PG8_WAIT_V(6); PG8_BAR; PG8_MMA(1, 1, At, B1); PG8_BAR;
;             }
;         }
;         if constexpr (ALIGN_EPI) { if (wr == 0) PG8_BAR; }
	s_add_i32 s58, s90, s29
	v_lshl_add_u64 v[180:181], v[180:181], 0, s[8:9]
	s_mov_b32 m0, s58
	ds_read_b128 v[188:191], v155 offset:49152
	ds_read_b128 v[192:195], v155 offset:50176
	ds_read_b128 v[196:199], v155 offset:51200
	ds_read_b128 v[200:203], v155 offset:52224
	ds_read_b128 v[204:207], v155 offset:53248
	ds_read_b128 v[208:211], v155 offset:54272
	ds_read_b128 v[212:215], v155 offset:55296
	ds_read_b128 v[216:219], v155 offset:56320
	global_load_lds_dwordx4 v[180:181], off
	s_add_i32 m0, s58, 0x2000
	s_add_u32 s48, s48, 0x80080
	v_lshl_add_u64 v[180:181], v[220:221], 0, s[8:9]
	s_addc_u32 s49, s49, 0
	s_add_i32 s58, s92, s29
	global_load_lds_dwordx4 v[180:181], off
	v_lshl_add_u64 v[180:181], s[48:49], 0, v[130:131]
	s_mov_b32 m0, s58
	s_nop 0
	global_load_lds_dwordx4 v[180:181], off
	v_lshl_add_u64 v[180:181], s[48:49], 0, v[134:135]
	s_add_i32 m0, s58, 0x2000
	s_nop 0
	global_load_lds_dwordx4 v[180:181], off
	v_lshl_add_u64 v[180:181], v[222:223], 0, s[8:9]
	s_mov_b32 m0, s64
	s_nop 0
	global_load_lds_dwordx4 v[180:181], off
	v_lshl_add_u64 v[180:181], v[224:225], 0, s[8:9]
	s_mov_b32 m0, s65
	s_nop 0
	global_load_lds_dwordx4 v[180:181], off
	s_waitcnt vmcnt(8)
	s_waitcnt lgkmcnt(0)
	s_barrier
	s_setprio 1
	s_waitcnt lgkmcnt(0)
	v_mfma_f32_16x16x32_bf16 v[60:63], v[146:149], v[188:191], v[60:63]
	v_mfma_f32_16x16x32_bf16 v[44:47], v[146:149], v[196:199], v[44:47]
	v_mfma_f32_16x16x32_bf16 v[28:31], v[146:149], v[204:207], v[28:31]
	v_mfma_f32_16x16x32_bf16 v[12:15], v[146:149], v[212:215], v[12:15]
	v_mfma_f32_16x16x32_bf16 v[8:11], v[160:163], v[212:215], v[8:11]
	v_mfma_f32_16x16x32_bf16 v[24:27], v[160:163], v[204:207], v[24:27]
	v_mfma_f32_16x16x32_bf16 v[40:43], v[160:163], v[196:199], v[40:43]
	v_mfma_f32_16x16x32_bf16 v[56:59], v[160:163], v[188:191], v[56:59]
	v_mfma_f32_16x16x32_bf16 v[60:63], v[156:159], v[192:195], v[60:63]
	v_mfma_f32_16x16x32_bf16 v[44:47], v[156:159], v[200:203], v[44:47]
	v_mfma_f32_16x16x32_bf16 v[28:31], v[156:159], v[208:211], v[28:31]
	v_mfma_f32_16x16x32_bf16 v[12:15], v[156:159], v[216:219], v[12:15]
	v_mfma_f32_16x16x32_bf16 v[8:11], v[164:167], v[216:219], v[8:11]
	v_mfma_f32_16x16x32_bf16 v[24:27], v[164:167], v[208:211], v[24:27]
	v_mfma_f32_16x16x32_bf16 v[40:43], v[164:167], v[200:203], v[40:43]
	v_mfma_f32_16x16x32_bf16 v[56:59], v[164:167], v[192:195], v[56:59]
	s_setprio 0
	s_setprio 1
	v_mfma_f32_16x16x32_bf16 v[52:55], v[168:171], v[188:191], v[52:55]
	v_mfma_f32_16x16x32_bf16 v[36:39], v[168:171], v[196:199], v[36:39]
	v_mfma_f32_16x16x32_bf16 v[20:23], v[168:171], v[204:207], v[20:23]
	v_mfma_f32_16x16x32_bf16 v[4:7], v[168:171], v[212:215], v[4:7]
	v_mfma_f32_16x16x32_bf16 v[0:3], v[176:179], v[212:215], v[0:3]
	v_mfma_f32_16x16x32_bf16 v[16:19], v[176:179], v[204:207], v[16:19]
	v_mfma_f32_16x16x32_bf16 v[32:35], v[176:179], v[196:199], v[32:35]
	v_mfma_f32_16x16x32_bf16 v[48:51], v[176:179], v[188:191], v[48:51]
	v_mfma_f32_16x16x32_bf16 v[52:55], v[172:175], v[192:195], v[52:55]
	v_mfma_f32_16x16x32_bf16 v[36:39], v[172:175], v[200:203], v[36:39]
	v_mfma_f32_16x16x32_bf16 v[20:23], v[172:175], v[208:211], v[20:23]
	v_mfma_f32_16x16x32_bf16 v[4:7], v[172:175], v[216:219], v[4:7]
	v_mfma_f32_16x16x32_bf16 v[0:3], v[184:187], v[216:219], v[0:3]
	v_mfma_f32_16x16x32_bf16 v[16:19], v[184:187], v[208:211], v[16:19]
	v_mfma_f32_16x16x32_bf16 v[32:35], v[184:187], v[200:203], v[32:35]
	v_mfma_f32_16x16x32_bf16 v[48:51], v[184:187], v[192:195], v[48:51]
	s_setprio 0
	s_barrier
	s_add_i32 s89, s89, 2
	s_add_u32 s44, s44, 0x100
	s_addc_u32 s45, s45, 0
	s_add_u32 s86, s86, 0x100
	s_addc_u32 s87, s87, 0
	s_cmp_gt_u32 s89, 29
	s_cbranch_scc0 .LBB0_93
	s_and_b64 vcc, exec, s[10:11]
	s_cbranch_vccz .LBB0_96
	s_barrier

; #define PG8_STAGE(bufoff, gbase, voff) do { _Pragma("unroll") for (int _i = 0; _i < 2; ++_i) \
;         __builtin_amdgcn_global_load_lds((const unsigned*)((const char*)(gbase) + (voff)[_i]), (PG8_LAS unsigned*)(lds + (bufoff) + ldsw + _i * 8192), 16, 0, 0); } while (0)
; #define PG8_LDA(dst, b, h) do { _Pragma("unroll") for (int m = 0; m < 4; ++m) _Pragma("unroll") for (int k = 0; k < 2; ++k) dst[m][k] = *(const PG8_LAS bf16x8*)(lds + PG8_SA(b, h) + aoff + m * 2048 + k * 1024); } while (0)
; #define PG8_LDB(dst, b, h) do { _Pragma("unroll") for (int n = 0; n < 2; ++n) _Pragma("unroll") for (int k = 0; k < 2; ++k) dst[n][k] = *(const PG8_LAS bf16x8*)(lds + PG8_SB(b, h) + boff + n * 2048 + k * 1024); } while (0)
; #define PG8_MMA(ai, bj, At, Bt) do { __builtin_amdgcn_s_setprio(1); _Pragma("unroll") for (int m = 0; m < 4; ++m) _Pragma("unroll") for (int n = 0; n < 2; ++n) _Pragma("unroll") for (int k = 0; k < 2; ++k) \
;         acc[ai][bj][m][n] = __builtin_amdgcn_mfma_f32_16x16x32_bf16(Bt[n][k], At[m][k], acc[ai][bj][m][n], 0, 0, 0); __builtin_amdgcn_s_setprio(0); } while (0)
; #define PG8_WAIT_V(n) asm volatile("s_waitcnt vmcnt(" #n ")" ::: "memory")
; #define PG8_WAIT_L(n) asm volatile("s_waitcnt lgkmcnt(" #n ")" ::: "memory")
; #define PG8_BAR __builtin_amdgcn_s_barrier()
; #define PG8_SCHED __builtin_amdgcn_sched_barrier(0)
; template <class Epi, class Sched, bool ALIGN_EPI = false, bool SP2 = false>
; __device__ __forceinline__ void gemm_phase(PG8_LAS unsigned char* lds, const Gemm g, const Sched& S, const Epi& E) {
;     ...
;             const bool last = (t == nt - 2);
;             const char* a1 = cA + (size_t)(t + 1) * kstep;
;             const char* a2 = last ? nA : cA + (size_t)(t + 2) * kstep; const char* b2 = last ? nB : cB + (size_t)(t + 2) * kstep;
;             const char* a3 = a2 + kstep; const char* b3 = b2 + kstep;
;             if (last && has_next) S.a_ready(nxt);
;             if constexpr (SP2) {
;             PG8_LDB(B0, 0, 0); PG8_LDB(B1, 0, 1); PG8_SCHED; PG8_LDA(At, 0, 0); PG8_STAGE(PG8_SA(1, 1), a1 + hstep, voffA);
;             PG8_WAIT_V(8); PG8_WAIT_L(0); PG8_BAR; PG8_MMA(0, 0, At, B0); PG8_MMA(0, 1, At, B1); PG8_BAR; PG8_SCHED;
;             PG8_LDA(At, 0, 1); PG8_STAGE(PG8_SB(0, 0), b2, voffB); PG8_STAGE(PG8_SB(0, 1), b2 + hstep, voffB); PG8_STAGE(PG8_SA(0, 0), a2, voffA);
.LBB0_121:
	ds_read_b128 v[174:177], v166
	ds_read_b128 v[178:181], v166 offset:1024
	ds_read_b128 v[190:193], v166 offset:2048
	ds_read_b128 v[194:197], v166 offset:3072
	ds_read_b128 v[198:201], v167
	ds_read_b128 v[202:205], v167 offset:1024
	ds_read_b128 v[206:209], v167 offset:2048
	ds_read_b128 v[210:213], v167 offset:3072
	s_add_u32 s46, s10, 0x100
	s_addc_u32 s47, s11, 0
	s_add_u32 s58, s90, s10
	s_addc_u32 s59, s92, s11
	s_cmpk_eq_i32 s93, 0x54
	s_cselect_b32 s60, s38, s58
	s_cselect_b32 s58, 0, s46
	s_cselect_b32 s61, s39, s59
	s_cselect_b32 s59, 0, s47
	s_add_u32 s58, s26, s58
	s_addc_u32 s59, s27, s59
	v_lshl_add_u64 v[246:247], v[142:143], 0, s[10:11]
	s_add_i32 m0, s3, 0xc000
	ds_read_b128 v[214:217], v168
	ds_read_b128 v[218:221], v168 offset:1024
	ds_read_b128 v[222:225], v168 offset:2048
	ds_read_b128 v[226:229], v168 offset:3072
	ds_read_b128 v[230:233], v168 offset:4096
	ds_read_b128 v[234:237], v168 offset:5120
	ds_read_b128 v[238:241], v168 offset:6144
	ds_read_b128 v[242:245], v168 offset:7168
	global_load_lds_dwordx4 v[246:247], off
	v_lshl_add_u64 v[246:247], v[146:147], 0, s[10:11]
	s_add_i32 m0, s3, 0xe000
	s_nop 0
	global_load_lds_dwordx4 v[246:247], off
	s_waitcnt vmcnt(8)
	s_waitcnt lgkmcnt(0)
	s_barrier
	s_setprio 1
	s_waitcnt lgkmcnt(0)
	v_mfma_f32_16x16x32_bf16 v[56:59], v[174:177], v[214:217], v[56:59]
	v_mfma_f32_16x16x32_bf16 v[76:79], v[174:177], v[222:225], v[76:79]
	v_mfma_f32_16x16x32_bf16 v[96:99], v[174:177], v[230:233], v[96:99]
	v_mfma_f32_16x16x32_bf16 v[116:119], v[174:177], v[238:241], v[116:119]
	v_mfma_f32_16x16x32_bf16 v[120:123], v[190:193], v[238:241], v[120:123]
	v_mfma_f32_16x16x32_bf16 v[100:103], v[190:193], v[230:233], v[100:103]
	v_mfma_f32_16x16x32_bf16 v[80:83], v[190:193], v[222:225], v[80:83]
	v_mfma_f32_16x16x32_bf16 v[60:63], v[190:193], v[214:217], v[60:63]
	v_mfma_f32_16x16x32_bf16 v[56:59], v[178:181], v[218:221], v[56:59]
	v_mfma_f32_16x16x32_bf16 v[76:79], v[178:181], v[226:229], v[76:79]
	v_mfma_f32_16x16x32_bf16 v[96:99], v[178:181], v[234:237], v[96:99]
	v_mfma_f32_16x16x32_bf16 v[116:119], v[178:181], v[242:245], v[116:119]
	v_mfma_f32_16x16x32_bf16 v[120:123], v[194:197], v[242:245], v[120:123]
	v_mfma_f32_16x16x32_bf16 v[100:103], v[194:197], v[234:237], v[100:103]
	v_mfma_f32_16x16x32_bf16 v[80:83], v[194:197], v[226:229], v[80:83]
	v_mfma_f32_16x16x32_bf16 v[60:63], v[194:197], v[218:221], v[60:63]
	s_setprio 0
	s_setprio 1
	v_mfma_f32_16x16x32_bf16 v[64:67], v[198:201], v[214:217], v[64:67]
	v_mfma_f32_16x16x32_bf16 v[84:87], v[198:201], v[222:225], v[84:87]
	v_mfma_f32_16x16x32_bf16 v[104:107], v[198:201], v[230:233], v[104:107]
	v_mfma_f32_16x16x32_bf16 v[124:127], v[198:201], v[238:241], v[124:127]
	v_mfma_f32_16x16x32_bf16 v[112:115], v[206:209], v[238:241], v[112:115]
	v_mfma_f32_16x16x32_bf16 v[108:111], v[206:209], v[230:233], v[108:111]
	v_mfma_f32_16x16x32_bf16 v[92:95], v[206:209], v[222:225], v[92:95]
	v_mfma_f32_16x16x32_bf16 v[68:71], v[206:209], v[214:217], v[68:71]
	v_mfma_f32_16x16x32_bf16 v[64:67], v[202:205], v[218:221], v[64:67]
	v_mfma_f32_16x16x32_bf16 v[84:87], v[202:205], v[226:229], v[84:87]
	v_mfma_f32_16x16x32_bf16 v[104:107], v[202:205], v[234:237], v[104:107]
	v_mfma_f32_16x16x32_bf16 v[124:127], v[202:205], v[242:245], v[124:127]
	v_mfma_f32_16x16x32_bf16 v[112:115], v[210:213], v[242:245], v[112:115]
	v_mfma_f32_16x16x32_bf16 v[108:111], v[210:213], v[234:237], v[108:111]
	v_mfma_f32_16x16x32_bf16 v[92:95], v[210:213], v[226:229], v[92:95]
	v_mfma_f32_16x16x32_bf16 v[68:71], v[210:213], v[218:221], v[68:71]
	s_setprio 0
	s_barrier
	s_add_i32 s10, s79, s34
	v_lshl_add_u64 v[246:247], s[58:59], 0, v[128:129]
	s_mov_b32 m0, s10
	ds_read_b128 v[214:217], v168 offset:16384
	ds_read_b128 v[218:221], v168 offset:17408
	ds_read_b128 v[222:225], v168 offset:18432
	ds_read_b128 v[226:229], v168 offset:19456
	ds_read_b128 v[230:233], v168 offset:20480
	ds_read_b128 v[234:237], v168 offset:21504
	ds_read_b128 v[238:241], v168 offset:22528
	ds_read_b128 v[242:245], v168 offset:23552
	global_load_lds_dwordx4 v[246:247], off
	s_add_i32 m0, s10, 0x2000
	s_add_u32 s10, s58, 0x160000
	v_lshl_add_u64 v[248:249], s[58:59], 0, v[130:131]
	s_addc_u32 s11, s59, 0
	s_add_i32 s94, s84, s34
	global_load_lds_dwordx4 v[248:249], off
	v_lshl_add_u64 v[250:251], s[10:11], 0, v[128:129]
	s_mov_b32 m0, s94
	v_lshl_add_u64 v[252:253], s[60:61], 0, v[130:131]
	global_load_lds_dwordx4 v[250:251], off
	v_lshl_add_u64 v[250:251], s[10:11], 0, v[130:131]
	s_add_i32 m0, s94, 0x2000
	s_nop 0
	global_load_lds_dwordx4 v[250:251], off
	v_lshl_add_u64 v[250:251], s[60:61], 0, v[128:129]
	s_mov_b32 m0, s3
	s_nop 0
	global_load_lds_dwordx4 v[250:251], off
	s_mov_b32 m0, s28
	s_nop 0
	global_load_lds_dwordx4 v[252:253], off
	s_waitcnt vmcnt(8)
	s_waitcnt lgkmcnt(0)
	s_barrier
; #define PG8_STAGE(bufoff, gbase, voff) do { _Pragma("unroll") for (int _i = 0; _i < 2; ++_i) \
;         __builtin_amdgcn_global_load_lds((const unsigned*)((const char*)(gbase) + (voff)[_i]), (PG8_LAS unsigned*)(lds + (bufoff) + ldsw + _i * 8192), 16, 0, 0); } while (0)
; #define PG8_LDA(dst, b, h) do { _Pragma("unroll") for (int m = 0; m < 4; ++m) _Pragma("unroll") for (int k = 0; k < 2; ++k) dst[m][k] = *(const PG8_LAS bf16x8*)(lds + PG8_SA(b, h) + aoff + m * 2048 + k * 1024); } while (0)
; #define PG8_LDB(dst, b, h) do { _Pragma("unroll") for (int n = 0; n < 2; ++n) _Pragma("unroll") for (int k = 0; k < 2; ++k) dst[n][k] = *(const PG8_LAS bf16x8*)(lds + PG8_SB(b, h) + boff + n * 2048 + k * 1024); } while (0)
; #define PG8_MMA(ai, bj, At, Bt) do { __builtin_amdgcn_s_setprio(1); _Pragma("unroll") for (int m = 0; m < 4; ++m) _Pragma("unroll") for (int n = 0; n < 2; ++n) _Pragma("unroll") for (int k = 0; k < 2; ++k) \
;         acc[ai][bj][m][n] = __builtin_amdgcn_mfma_f32_16x16x32_bf16(Bt[n][k], At[m][k], acc[ai][bj][m][n], 0, 0, 0); __builtin_amdgcn_s_setprio(0); } while (0)
; #define PG8_WAIT_V(n) asm volatile("s_waitcnt vmcnt(" #n ")" ::: "memory")
; #define PG8_WAIT_L(n) asm volatile("s_waitcnt lgkmcnt(" #n ")" ::: "memory")
; #define PG8_BAR __builtin_amdgcn_s_barrier()
; #define PG8_SCHED __builtin_amdgcn_sched_barrier(0)
; template <class Epi, class Sched, bool ALIGN_EPI = false, bool SP2 = false>
; __device__ __forceinline__ void gemm_phase(PG8_LAS unsigned char* lds, const Gemm g, const Sched& S, const Epi& E) {
;     ...
;             PG8_WAIT_V(8); PG8_WAIT_L(0); PG8_BAR; PG8_MMA(1, 0, At, B0); PG8_MMA(1, 1, At, B1); PG8_BAR; PG8_SCHED;
;             PG8_LDB(B0, 1, 0); PG8_LDB(B1, 1, 1); PG8_SCHED; PG8_LDA(At, 1, 0); PG8_STAGE(PG8_SA(0, 1), a2 + hstep, voffA);
;             PG8_WAIT_V(8); PG8_WAIT_L(0); PG8_BAR; PG8_MMA(0, 0, At, B0); PG8_MMA(0, 1, At, B1); PG8_BAR; PG8_SCHED;
	s_setprio 1
	s_waitcnt lgkmcnt(0)
	v_mfma_f32_16x16x32_bf16 v[88:91], v[174:177], v[214:217], v[88:91]
	v_mfma_f32_16x16x32_bf16 v[44:47], v[174:177], v[222:225], v[44:47]
	v_mfma_f32_16x16x32_bf16 v[28:31], v[174:177], v[230:233], v[28:31]
	v_mfma_f32_16x16x32_bf16 v[12:15], v[174:177], v[238:241], v[12:15]
	v_mfma_f32_16x16x32_bf16 v[8:11], v[190:193], v[238:241], v[8:11]
	v_mfma_f32_16x16x32_bf16 v[24:27], v[190:193], v[230:233], v[24:27]
	v_mfma_f32_16x16x32_bf16 v[40:43], v[190:193], v[222:225], v[40:43]
	v_mfma_f32_16x16x32_bf16 v[72:75], v[190:193], v[214:217], v[72:75]
	v_mfma_f32_16x16x32_bf16 v[88:91], v[178:181], v[218:221], v[88:91]
	v_mfma_f32_16x16x32_bf16 v[44:47], v[178:181], v[226:229], v[44:47]
	v_mfma_f32_16x16x32_bf16 v[28:31], v[178:181], v[234:237], v[28:31]
	v_mfma_f32_16x16x32_bf16 v[12:15], v[178:181], v[242:245], v[12:15]
	v_mfma_f32_16x16x32_bf16 v[8:11], v[194:197], v[242:245], v[8:11]
	v_mfma_f32_16x16x32_bf16 v[24:27], v[194:197], v[234:237], v[24:27]
	v_mfma_f32_16x16x32_bf16 v[40:43], v[194:197], v[226:229], v[40:43]
	v_mfma_f32_16x16x32_bf16 v[72:75], v[194:197], v[218:221], v[72:75]
	s_setprio 0
	s_setprio 1
	v_mfma_f32_16x16x32_bf16 v[52:55], v[198:201], v[214:217], v[52:55]
	v_mfma_f32_16x16x32_bf16 v[36:39], v[198:201], v[222:225], v[36:39]
	v_mfma_f32_16x16x32_bf16 v[20:23], v[198:201], v[230:233], v[20:23]
	v_mfma_f32_16x16x32_bf16 v[4:7], v[198:201], v[238:241], v[4:7]
	v_mfma_f32_16x16x32_bf16 v[0:3], v[206:209], v[238:241], v[0:3]
	v_mfma_f32_16x16x32_bf16 v[16:19], v[206:209], v[230:233], v[16:19]
	v_mfma_f32_16x16x32_bf16 v[32:35], v[206:209], v[222:225], v[32:35]
	v_mfma_f32_16x16x32_bf16 v[48:51], v[206:209], v[214:217], v[48:51]
	v_mfma_f32_16x16x32_bf16 v[52:55], v[202:205], v[218:221], v[52:55]
	v_mfma_f32_16x16x32_bf16 v[36:39], v[202:205], v[226:229], v[36:39]
	v_mfma_f32_16x16x32_bf16 v[20:23], v[202:205], v[234:237], v[20:23]
	v_mfma_f32_16x16x32_bf16 v[4:7], v[202:205], v[242:245], v[4:7]
	v_mfma_f32_16x16x32_bf16 v[0:3], v[210:213], v[242:245], v[0:3]
	v_mfma_f32_16x16x32_bf16 v[16:19], v[210:213], v[234:237], v[16:19]
	v_mfma_f32_16x16x32_bf16 v[32:35], v[210:213], v[226:229], v[32:35]
	v_mfma_f32_16x16x32_bf16 v[48:51], v[210:213], v[218:221], v[48:51]
	s_setprio 0
	s_barrier
	s_add_i32 s94, 0, 0x18000
	v_add_u32_e32 v173, s94, v148
	s_add_i32 s95, 0, 0x1c000
	ds_read_b128 v[174:177], v173
	ds_read_b128 v[178:181], v173 offset:1024
	ds_read_b128 v[190:193], v173 offset:2048
	ds_read_b128 v[194:197], v173 offset:3072
	v_add_u32_e32 v173, s95, v148
	ds_read_b128 v[198:201], v173
	ds_read_b128 v[202:205], v173 offset:1024
	ds_read_b128 v[206:209], v173 offset:2048
	ds_read_b128 v[210:213], v173 offset:3072
	s_add_u32 s10, s60, 0x160000
	s_addc_u32 s11, s61, 0
	s_mov_b32 m0, s35
	v_lshl_add_u64 v[188:189], s[10:11], 0, v[128:129]
	ds_read_b128 v[214:217], v168 offset:32768
	ds_read_b128 v[218:221], v168 offset:33792
	ds_read_b128 v[222:225], v168 offset:34816
	ds_read_b128 v[226:229], v168 offset:35840
	ds_read_b128 v[230:233], v168 offset:36864
	ds_read_b128 v[234:237], v168 offset:37888
	ds_read_b128 v[238:241], v168 offset:38912
	ds_read_b128 v[242:245], v168 offset:39936
	global_load_lds_dwordx4 v[188:189], off
	v_lshl_add_u64 v[188:189], s[10:11], 0, v[130:131]
	s_mov_b32 m0, s62
	s_nop 0
	global_load_lds_dwordx4 v[188:189], off
	s_waitcnt vmcnt(8)
	s_waitcnt lgkmcnt(0)
	s_barrier
	s_setprio 1
	s_waitcnt lgkmcnt(0)
	v_mfma_f32_16x16x32_bf16 v[56:59], v[174:177], v[214:217], v[56:59]
	v_mfma_f32_16x16x32_bf16 v[76:79], v[174:177], v[222:225], v[76:79]
	v_mfma_f32_16x16x32_bf16 v[96:99], v[174:177], v[230:233], v[96:99]
	v_mfma_f32_16x16x32_bf16 v[116:119], v[174:177], v[238:241], v[116:119]
	v_mfma_f32_16x16x32_bf16 v[120:123], v[190:193], v[238:241], v[120:123]
	v_mfma_f32_16x16x32_bf16 v[100:103], v[190:193], v[230:233], v[100:103]
	v_mfma_f32_16x16x32_bf16 v[80:83], v[190:193], v[222:225], v[80:83]
	v_mfma_f32_16x16x32_bf16 v[60:63], v[190:193], v[214:217], v[60:63]
	v_mfma_f32_16x16x32_bf16 v[56:59], v[178:181], v[218:221], v[56:59]
	v_mfma_f32_16x16x32_bf16 v[76:79], v[178:181], v[226:229], v[76:79]
	v_mfma_f32_16x16x32_bf16 v[96:99], v[178:181], v[234:237], v[96:99]
	v_mfma_f32_16x16x32_bf16 v[116:119], v[178:181], v[242:245], v[116:119]
	v_mfma_f32_16x16x32_bf16 v[120:123], v[194:197], v[242:245], v[120:123]
	v_mfma_f32_16x16x32_bf16 v[100:103], v[194:197], v[234:237], v[100:103]
	v_mfma_f32_16x16x32_bf16 v[80:83], v[194:197], v[226:229], v[80:83]
	v_mfma_f32_16x16x32_bf16 v[60:63], v[194:197], v[218:221], v[60:63]
	s_setprio 0
	s_setprio 1
	v_mfma_f32_16x16x32_bf16 v[64:67], v[198:201], v[214:217], v[64:67]
	v_mfma_f32_16x16x32_bf16 v[84:87], v[198:201], v[222:225], v[84:87]
	v_mfma_f32_16x16x32_bf16 v[104:107], v[198:201], v[230:233], v[104:107]
	v_mfma_f32_16x16x32_bf16 v[124:127], v[198:201], v[238:241], v[124:127]
	v_mfma_f32_16x16x32_bf16 v[112:115], v[206:209], v[238:241], v[112:115]
	v_mfma_f32_16x16x32_bf16 v[108:111], v[206:209], v[230:233], v[108:111]
	v_mfma_f32_16x16x32_bf16 v[92:95], v[206:209], v[222:225], v[92:95]
	v_mfma_f32_16x16x32_bf16 v[68:71], v[206:209], v[214:217], v[68:71]
	v_mfma_f32_16x16x32_bf16 v[64:67], v[202:205], v[218:221], v[64:67]
	v_mfma_f32_16x16x32_bf16 v[84:87], v[202:205], v[226:229], v[84:87]
	v_mfma_f32_16x16x32_bf16 v[104:107], v[202:205], v[234:237], v[104:107]
	v_mfma_f32_16x16x32_bf16 v[124:127], v[202:205], v[242:245], v[124:127]
	v_mfma_f32_16x16x32_bf16 v[112:115], v[210:213], v[242:245], v[112:115]
	v_mfma_f32_16x16x32_bf16 v[108:111], v[210:213], v[234:237], v[108:111]
	v_mfma_f32_16x16x32_bf16 v[92:95], v[210:213], v[226:229], v[92:95]
	v_mfma_f32_16x16x32_bf16 v[68:71], v[210:213], v[218:221], v[68:71]
	s_setprio 0
	s_barrier
; #define PG8_STAGE(bufoff, gbase, voff) do { _Pragma("unroll") for (int _i = 0; _i < 2; ++_i) \
;         __builtin_amdgcn_global_load_lds((const unsigned*)((const char*)(gbase) + (voff)[_i]), (PG8_LAS unsigned*)(lds + (bufoff) + ldsw + _i * 8192), 16, 0, 0); } while (0)
; #define PG8_LDA(dst, b, h) do { _Pragma("unroll") for (int m = 0; m < 4; ++m) _Pragma("unroll") for (int k = 0; k < 2; ++k) dst[m][k] = *(const PG8_LAS bf16x8*)(lds + PG8_SA(b, h) + aoff + m * 2048 + k * 1024); } while (0)
; #define PG8_WAIT_V(n) asm volatile("s_waitcnt vmcnt(" #n ")" ::: "memory")
; template <class Epi, class Sched, bool ALIGN_EPI = false, bool SP2 = false>
; __device__ __forceinline__ void gemm_phase(PG8_LAS unsigned char* lds, const Gemm g, const Sched& S, const Epi& E) {
;     ...
;             PG8_LDA(At, 1, 1); PG8_STAGE(PG8_SB(1, 0), b3, voffB); PG8_STAGE(PG8_SB(1, 1), b3 + hstep, voffB); PG8_STAGE(PG8_SA(1, 0), a3, voffA);
;             PG8_WAIT_V(8); PG8_WAIT_L(0); PG8_BAR; PG8_MMA(1, 0, At, B0); PG8_MMA(1, 1, At, B1); PG8_BAR; PG8_SCHED;
;             } else {
;             PG8_LDB(B0, 0, 0); PG8_SCHED; PG8_LDA(At, 0, 0); PG8_STAGE(PG8_SA(1, 1), a1 + hstep, voffA);
;             PG8_WAIT_L(8); PG8_BAR; PG8_WAIT_L(0); PG8_MMA(0, 0, At, B0); PG8_BAR; PG8_SCHED;
;             PG8_LDB(B1, 0, 1); PG8_STAGE(PG8_SB(0, 0), b2, voffB);
;             PG8_BAR; PG8_WAIT_L(0); PG8_MMA(0, 1, At, B1); PG8_BAR;
;             PG8_LDA(At, 0, 1); PG8_STAGE(PG8_SA(0, 0), a2, voffA);
;             PG8_BAR; PG8_WAIT_L(0); PG8_MMA(1, 0, At, B0); PG8_BAR; PG8_SCHED;
;             PG8_STAGE(PG8_SB(0, 1), b2 + hstep, voffB);
;             PG8_WAIT_V(6); PG8_BAR; PG8_MMA(1, 1, At, B1); PG8_BAR;
;             PG8_LDB(B0, 1, 0); PG8_SCHED; PG8_LDA(At, 1, 0); PG8_STAGE(PG8_SA(0, 1), a2 + hstep, voffA);
;             PG8_WAIT_L(8); PG8_BAR; PG8_WAIT_L(0); PG8_MMA(0, 0, At, B0); PG8_BAR; PG8_SCHED;
;             PG8_LDB(B1, 1, 1); PG8_STAGE(PG8_SB(1, 0), b3, voffB);
;             PG8_BAR; PG8_WAIT_L(0); PG8_MMA(0, 1, At, B1); PG8_BAR;
;             PG8_LDA(At, 1, 1); PG8_STAGE(PG8_SA(1, 0), a3, voffA);
;             PG8_BAR; PG8_WAIT_L(0); PG8_MMA(1, 0, At, B0); PG8_BAR; PG8_SCHED;
;             PG8_STAGE(PG8_SB(1, 1), b3 + hstep, voffB);
;             PG8_WAIT_V(6); PG8_BAR; PG8_MMA(1, 1, At, B1); PG8_BAR;
;             }
;         }
;         if constexpr (ALIGN_EPI) { if (wr == 0) PG8_BAR; }
	s_add_i32 s10, s94, s34
	v_lshl_add_u64 v[188:189], v[246:247], 0, s[44:45]
	s_mov_b32 m0, s10
	ds_read_b128 v[214:217], v168 offset:49152
	ds_read_b128 v[218:221], v168 offset:50176
	ds_read_b128 v[222:225], v168 offset:51200
	ds_read_b128 v[226:229], v168 offset:52224
	ds_read_b128 v[230:233], v168 offset:53248
	ds_read_b128 v[234:237], v168 offset:54272
	ds_read_b128 v[238:241], v168 offset:55296
	ds_read_b128 v[242:245], v168 offset:56320
	global_load_lds_dwordx4 v[188:189], off
	s_add_i32 m0, s10, 0x2000
	s_add_u32 s10, s58, 0x160080
	v_lshl_add_u64 v[188:189], v[248:249], 0, s[44:45]
	s_addc_u32 s11, s59, 0
	s_add_i32 s58, s95, s34
	global_load_lds_dwordx4 v[188:189], off
	v_lshl_add_u64 v[188:189], s[10:11], 0, v[128:129]
	s_mov_b32 m0, s58
	s_nop 0
	global_load_lds_dwordx4 v[188:189], off
	v_lshl_add_u64 v[188:189], s[10:11], 0, v[130:131]
	s_add_i32 m0, s58, 0x2000
	s_nop 0
	global_load_lds_dwordx4 v[188:189], off
	v_lshl_add_u64 v[188:189], v[250:251], 0, s[44:45]
	s_mov_b32 m0, s65
	s_nop 0
	global_load_lds_dwordx4 v[188:189], off
	v_lshl_add_u64 v[188:189], v[252:253], 0, s[44:45]
	s_mov_b32 m0, s66
	s_nop 0
	global_load_lds_dwordx4 v[188:189], off
	s_waitcnt vmcnt(8)
	s_waitcnt lgkmcnt(0)
	s_barrier
	s_setprio 1
	s_waitcnt lgkmcnt(0)
	v_mfma_f32_16x16x32_bf16 v[88:91], v[174:177], v[214:217], v[88:91]
	v_mfma_f32_16x16x32_bf16 v[44:47], v[174:177], v[222:225], v[44:47]
	v_mfma_f32_16x16x32_bf16 v[28:31], v[174:177], v[230:233], v[28:31]
	v_mfma_f32_16x16x32_bf16 v[12:15], v[174:177], v[238:241], v[12:15]
	v_mfma_f32_16x16x32_bf16 v[8:11], v[190:193], v[238:241], v[8:11]
	v_mfma_f32_16x16x32_bf16 v[24:27], v[190:193], v[230:233], v[24:27]
	v_mfma_f32_16x16x32_bf16 v[40:43], v[190:193], v[222:225], v[40:43]
	v_mfma_f32_16x16x32_bf16 v[72:75], v[190:193], v[214:217], v[72:75]
	v_mfma_f32_16x16x32_bf16 v[88:91], v[178:181], v[218:221], v[88:91]
	v_mfma_f32_16x16x32_bf16 v[44:47], v[178:181], v[226:229], v[44:47]
	v_mfma_f32_16x16x32_bf16 v[28:31], v[178:181], v[234:237], v[28:31]
	v_mfma_f32_16x16x32_bf16 v[12:15], v[178:181], v[242:245], v[12:15]
	v_mfma_f32_16x16x32_bf16 v[8:11], v[194:197], v[242:245], v[8:11]
	v_mfma_f32_16x16x32_bf16 v[24:27], v[194:197], v[234:237], v[24:27]
	v_mfma_f32_16x16x32_bf16 v[40:43], v[194:197], v[226:229], v[40:43]
	v_mfma_f32_16x16x32_bf16 v[72:75], v[194:197], v[218:221], v[72:75]
	s_setprio 0
	s_setprio 1
	v_mfma_f32_16x16x32_bf16 v[52:55], v[198:201], v[214:217], v[52:55]
	v_mfma_f32_16x16x32_bf16 v[36:39], v[198:201], v[222:225], v[36:39]
	v_mfma_f32_16x16x32_bf16 v[20:23], v[198:201], v[230:233], v[20:23]
	v_mfma_f32_16x16x32_bf16 v[4:7], v[198:201], v[238:241], v[4:7]
	v_mfma_f32_16x16x32_bf16 v[0:3], v[206:209], v[238:241], v[0:3]
	v_mfma_f32_16x16x32_bf16 v[16:19], v[206:209], v[230:233], v[16:19]
	v_mfma_f32_16x16x32_bf16 v[32:35], v[206:209], v[222:225], v[32:35]
	v_mfma_f32_16x16x32_bf16 v[48:51], v[206:209], v[214:217], v[48:51]
	v_mfma_f32_16x16x32_bf16 v[52:55], v[202:205], v[218:221], v[52:55]
	v_mfma_f32_16x16x32_bf16 v[36:39], v[202:205], v[226:229], v[36:39]
	v_mfma_f32_16x16x32_bf16 v[20:23], v[202:205], v[234:237], v[20:23]
	v_mfma_f32_16x16x32_bf16 v[4:7], v[202:205], v[242:245], v[4:7]
	v_mfma_f32_16x16x32_bf16 v[0:3], v[210:213], v[242:245], v[0:3]
	v_mfma_f32_16x16x32_bf16 v[16:19], v[210:213], v[234:237], v[16:19]
	v_mfma_f32_16x16x32_bf16 v[32:35], v[210:213], v[226:229], v[32:35]
	v_mfma_f32_16x16x32_bf16 v[48:51], v[210:213], v[218:221], v[48:51]
	s_setprio 0
	s_barrier
	s_add_i32 s93, s93, 2
	s_cmpk_gt_u32 s93, 0x55
	s_mov_b64 s[10:11], s[46:47]
	s_cbranch_scc0 .LBB0_121
	s_and_b64 vcc, exec, s[48:49]
	s_cbranch_vccz .LBB0_124
	s_barrier

;     __device__ __forceinline__ bool next(int i, Unit& u) const { if (i >= 5) return false; const int x = c & 7, k = c >> 3; u.pm = 32 * i + 4 * x + (k >> 3); u.pn = k & 7; return true; }
; #define PG8_STAGE(bufoff, gbase, voff) do { _Pragma("unroll") for (int _i = 0; _i < 2; ++_i) \
;         __builtin_amdgcn_global_load_lds((const unsigned*)((const char*)(gbase) + (voff)[_i]), (PG8_LAS unsigned*)(lds + (bufoff) + ldsw + _i * 8192), 16, 0, 0); } while (0)
; #define PG8_LDA(dst, b, h) do { _Pragma("unroll") for (int m = 0; m < 4; ++m) _Pragma("unroll") for (int k = 0; k < 2; ++k) dst[m][k] = *(const PG8_LAS bf16x8*)(lds + PG8_SA(b, h) + aoff + m * 2048 + k * 1024); } while (0)
; #define PG8_LDB(dst, b, h) do { _Pragma("unroll") for (int n = 0; n < 2; ++n) _Pragma("unroll") for (int k = 0; k < 2; ++k) dst[n][k] = *(const PG8_LAS bf16x8*)(lds + PG8_SB(b, h) + boff + n * 2048 + k * 1024); } while (0)
; #define PG8_WAIT_V(n) asm volatile("s_waitcnt vmcnt(" #n ")" ::: "memory")
; #define PG8_WAIT_L(n) asm volatile("s_waitcnt lgkmcnt(" #n ")" ::: "memory")
; #define PG8_BAR __builtin_amdgcn_s_barrier()
; template <class Epi, class Sched, bool ALIGN_EPI = false, bool SP2 = false>
; __device__ __forceinline__ void gemm_phase(PG8_LAS unsigned char* lds, const Gemm g, const Sched& S, const Epi& E) {
;     ...
;         const bool has_next = S.next(ui + 1, nxt);
;         const char* nA = has_next ? (const char*)g.A + (size_t)nxt.pm * tstep : cA; const char* nB = has_next ? (const char*)g.Bt + (size_t)nxt.pn * tstep : cB;
;         for (int t = 0; t < nt; t += 2) {
;             const bool last = (t == nt - 2);
;             const char* a1 = cA + (size_t)(t + 1) * kstep;
;             const char* a2 = last ? nA : cA + (size_t)(t + 2) * kstep; const char* b2 = last ? nB : cB + (size_t)(t + 2) * kstep;
;             const char* a3 = a2 + kstep; const char* b3 = b2 + kstep;
;             if (last && has_next) S.a_ready(nxt);
;             if constexpr (SP2) {
;             PG8_LDB(B0, 0, 0); PG8_LDB(B1, 0, 1); PG8_SCHED; PG8_LDA(At, 0, 0); PG8_STAGE(PG8_SA(1, 1), a1 + hstep, voffA);
;             PG8_WAIT_V(8); PG8_WAIT_L(0); PG8_BAR; PG8_MMA(0, 0, At, B0); PG8_MMA(0, 1, At, B1); PG8_BAR; PG8_SCHED;
;             PG8_LDA(At, 0, 1); PG8_STAGE(PG8_SB(0, 0), b2, voffB); PG8_STAGE(PG8_SB(0, 1), b2 + hstep, voffB); PG8_STAGE(PG8_SA(0, 0), a2, voffA);
.LBB0_181:
	ds_read_b128 v[0:3], v147
	ds_read_b128 v[4:7], v147 offset:1024
	ds_read_b128 v[8:11], v147 offset:2048
	ds_read_b128 v[12:15], v147 offset:3072
	ds_read_b128 v[16:19], v148
	ds_read_b128 v[20:23], v148 offset:1024
	ds_read_b128 v[24:27], v148 offset:2048
	ds_read_b128 v[28:31], v148 offset:3072
	s_ashr_i32 s41, s40, 31
	s_lshl_b64 s[42:43], s[40:41], 17
	s_add_u32 s42, s28, s42
	s_addc_u32 s43, s29, s43
	s_and_b64 s[44:45], s[0:1], exec
	s_cselect_b32 s63, s43, s49
	s_cselect_b32 s62, s42, s48
	s_ashr_i32 s39, s38, 31
	s_lshl_b64 s[44:45], s[38:39], 17
	s_add_u32 s44, s82, s44
	s_addc_u32 s45, s83, s45
	s_and_b64 s[58:59], s[0:1], exec
	s_cselect_b32 s59, s45, s61
	s_cselect_b32 s58, s44, s60
	s_add_u32 s86, s48, 0x10080
	s_addc_u32 s87, s49, 0
	s_add_i32 s92, s35, 0xc000
	v_lshl_add_u64 v[64:65], s[86:87], 0, v[130:131]
	s_mov_b32 m0, s92
	s_add_i32 s39, s35, 0xe000
	ds_read_b128 v[32:35], v149
	ds_read_b128 v[36:39], v149 offset:1024
	ds_read_b128 v[40:43], v149 offset:2048
	ds_read_b128 v[44:47], v149 offset:3072
	ds_read_b128 v[48:51], v149 offset:4096
	ds_read_b128 v[52:55], v149 offset:5120
	ds_read_b128 v[56:59], v149 offset:6144
	ds_read_b128 v[60:63], v149 offset:7168
	global_load_lds_dwordx4 v[64:65], off
	v_lshl_add_u64 v[64:65], s[86:87], 0, v[128:129]
	s_mov_b32 m0, s39
	s_nop 0
	global_load_lds_dwordx4 v[64:65], off
	s_waitcnt vmcnt(8)
	s_waitcnt lgkmcnt(0)
	s_barrier
	s_setprio 1
	s_waitcnt lgkmcnt(0)
	v_mfma_f32_16x16x32_bf16 v[64:67], v[0:3], v[32:35], 0
	v_mfma_f32_16x16x32_bf16 v[68:71], v[8:11], v[32:35], 0
	v_mfma_f32_16x16x32_bf16 v[72:75], v[0:3], v[40:43], 0
	v_mfma_f32_16x16x32_bf16 v[76:79], v[8:11], v[40:43], 0
	v_mfma_f32_16x16x32_bf16 v[80:83], v[0:3], v[48:51], 0
	v_mfma_f32_16x16x32_bf16 v[84:87], v[8:11], v[48:51], 0
	v_mfma_f32_16x16x32_bf16 v[88:91], v[0:3], v[56:59], 0
	v_mfma_f32_16x16x32_bf16 v[92:95], v[8:11], v[56:59], 0
	v_mfma_f32_16x16x32_bf16 v[64:67], v[4:7], v[36:39], v[64:67]
	v_mfma_f32_16x16x32_bf16 v[68:71], v[12:15], v[36:39], v[68:71]
	v_mfma_f32_16x16x32_bf16 v[72:75], v[4:7], v[44:47], v[72:75]
	v_mfma_f32_16x16x32_bf16 v[76:79], v[12:15], v[44:47], v[76:79]
	v_mfma_f32_16x16x32_bf16 v[80:83], v[4:7], v[52:55], v[80:83]
	v_mfma_f32_16x16x32_bf16 v[84:87], v[12:15], v[52:55], v[84:87]
	v_mfma_f32_16x16x32_bf16 v[88:91], v[4:7], v[60:63], v[88:91]
	v_mfma_f32_16x16x32_bf16 v[92:95], v[12:15], v[60:63], v[92:95]
	s_setprio 0
	s_setprio 1
	v_mfma_f32_16x16x32_bf16 v[96:99], v[16:19], v[32:35], 0
	v_mfma_f32_16x16x32_bf16 v[32:35], v[24:27], v[32:35], 0
	v_mfma_f32_16x16x32_bf16 v[96:99], v[20:23], v[36:39], v[96:99]
	v_mfma_f32_16x16x32_bf16 v[32:35], v[28:31], v[36:39], v[32:35]
	v_mfma_f32_16x16x32_bf16 v[36:39], v[16:19], v[40:43], 0
	v_mfma_f32_16x16x32_bf16 v[40:43], v[24:27], v[40:43], 0
	v_mfma_f32_16x16x32_bf16 v[36:39], v[20:23], v[44:47], v[36:39]
	v_mfma_f32_16x16x32_bf16 v[40:43], v[28:31], v[44:47], v[40:43]
	v_mfma_f32_16x16x32_bf16 v[44:47], v[16:19], v[48:51], 0
	v_mfma_f32_16x16x32_bf16 v[48:51], v[24:27], v[48:51], 0
	v_mfma_f32_16x16x32_bf16 v[44:47], v[20:23], v[52:55], v[44:47]
	v_mfma_f32_16x16x32_bf16 v[48:51], v[28:31], v[52:55], v[48:51]
	v_mfma_f32_16x16x32_bf16 v[52:55], v[16:19], v[56:59], 0
	v_mfma_f32_16x16x32_bf16 v[56:59], v[24:27], v[56:59], 0
	v_mfma_f32_16x16x32_bf16 v[52:55], v[20:23], v[60:63], v[52:55]
	v_mfma_f32_16x16x32_bf16 v[56:59], v[28:31], v[60:63], v[56:59]
	s_setprio 0
	s_barrier
	s_add_i32 s89, s79, s3
	v_lshl_add_u64 v[140:141], s[60:61], 0, v[130:131]
	s_add_i32 s41, s89, 0x2000
	v_lshl_add_u64 v[136:137], v[140:141], 0, s[12:13]
	s_mov_b32 m0, s89
	v_lshl_add_u64 v[180:181], s[60:61], 0, v[128:129]
	s_add_u32 s96, s60, 0x10100
	ds_read_b128 v[60:63], v149 offset:16384
	ds_read_b128 v[100:103], v149 offset:17408
	ds_read_b128 v[104:107], v149 offset:18432
	ds_read_b128 v[108:111], v149 offset:19456
	ds_read_b128 v[112:115], v149 offset:20480
	ds_read_b128 v[116:119], v149 offset:21504
	ds_read_b128 v[120:123], v149 offset:22528
	ds_read_b128 v[124:127], v149 offset:23552
	global_load_lds_dwordx4 v[136:137], off
	v_lshl_add_u64 v[136:137], v[180:181], 0, s[12:13]
	s_mov_b32 m0, s41
	s_addc_u32 s97, s61, 0
	s_add_i32 s86, s84, s3
	global_load_lds_dwordx4 v[136:137], off
	v_lshl_add_u64 v[136:137], s[96:97], 0, v[130:131]
	s_mov_b32 m0, s86
	s_add_i32 s87, s86, 0x2000
	global_load_lds_dwordx4 v[136:137], off
	v_lshl_add_u64 v[136:137], s[96:97], 0, v[128:129]
	s_mov_b32 m0, s87
	v_lshl_add_u64 v[188:189], s[48:49], 0, v[130:131]
	global_load_lds_dwordx4 v[136:137], off
	v_lshl_add_u64 v[136:137], v[188:189], 0, s[12:13]
	s_mov_b32 m0, s35
	v_lshl_add_u64 v[222:223], s[48:49], 0, v[128:129]
	global_load_lds_dwordx4 v[136:137], off
	v_lshl_add_u64 v[136:137], v[222:223], 0, s[12:13]
	s_mov_b32 m0, s47
	s_nop 0
	global_load_lds_dwordx4 v[136:137], off
	s_waitcnt vmcnt(8)
	s_waitcnt lgkmcnt(0)
	s_barrier
; #define PG8_STAGE(bufoff, gbase, voff) do { _Pragma("unroll") for (int _i = 0; _i < 2; ++_i) \
;         __builtin_amdgcn_global_load_lds((const unsigned*)((const char*)(gbase) + (voff)[_i]), (PG8_LAS unsigned*)(lds + (bufoff) + ldsw + _i * 8192), 16, 0, 0); } while (0)
; #define PG8_LDA(dst, b, h) do { _Pragma("unroll") for (int m = 0; m < 4; ++m) _Pragma("unroll") for (int k = 0; k < 2; ++k) dst[m][k] = *(const PG8_LAS bf16x8*)(lds + PG8_SA(b, h) + aoff + m * 2048 + k * 1024); } while (0)
; #define PG8_LDB(dst, b, h) do { _Pragma("unroll") for (int n = 0; n < 2; ++n) _Pragma("unroll") for (int k = 0; k < 2; ++k) dst[n][k] = *(const PG8_LAS bf16x8*)(lds + PG8_SB(b, h) + boff + n * 2048 + k * 1024); } while (0)
; #define PG8_MMA(ai, bj, At, Bt) do { __builtin_amdgcn_s_setprio(1); _Pragma("unroll") for (int m = 0; m < 4; ++m) _Pragma("unroll") for (int n = 0; n < 2; ++n) _Pragma("unroll") for (int k = 0; k < 2; ++k) \
;         acc[ai][bj][m][n] = __builtin_amdgcn_mfma_f32_16x16x32_bf16(Bt[n][k], At[m][k], acc[ai][bj][m][n], 0, 0, 0); __builtin_amdgcn_s_setprio(0); } while (0)
; #define PG8_WAIT_V(n) asm volatile("s_waitcnt vmcnt(" #n ")" ::: "memory")
; #define PG8_WAIT_L(n) asm volatile("s_waitcnt lgkmcnt(" #n ")" ::: "memory")
; #define PG8_BAR __builtin_amdgcn_s_barrier()
; #define PG8_SCHED __builtin_amdgcn_sched_barrier(0)
; template <class Epi, class Sched, bool ALIGN_EPI = false, bool SP2 = false>
; __device__ __forceinline__ void gemm_phase(PG8_LAS unsigned char* lds, const Gemm g, const Sched& S, const Epi& E) {
;     ...
;             PG8_WAIT_V(8); PG8_WAIT_L(0); PG8_BAR; PG8_MMA(1, 0, At, B0); PG8_MMA(1, 1, At, B1); PG8_BAR; PG8_SCHED;
;             PG8_LDB(B0, 1, 0); PG8_LDB(B1, 1, 1); PG8_SCHED; PG8_LDA(At, 1, 0); PG8_STAGE(PG8_SA(0, 1), a2 + hstep, voffA);
;             PG8_WAIT_V(8); PG8_WAIT_L(0); PG8_BAR; PG8_MMA(0, 0, At, B0); PG8_MMA(0, 1, At, B1); PG8_BAR; PG8_SCHED;
	s_setprio 1
	s_waitcnt lgkmcnt(0)
	v_mfma_f32_16x16x32_bf16 v[136:139], v[0:3], v[60:63], 0
	v_mfma_f32_16x16x32_bf16 v[156:159], v[0:3], v[104:107], 0
	v_mfma_f32_16x16x32_bf16 v[164:167], v[0:3], v[112:115], 0
	v_mfma_f32_16x16x32_bf16 v[0:3], v[0:3], v[120:123], 0
	v_mfma_f32_16x16x32_bf16 v[136:139], v[4:7], v[100:103], v[136:139]
	v_mfma_f32_16x16x32_bf16 v[156:159], v[4:7], v[108:111], v[156:159]
	v_mfma_f32_16x16x32_bf16 v[164:167], v[4:7], v[116:119], v[164:167]
	v_mfma_f32_16x16x32_bf16 v[0:3], v[4:7], v[124:127], v[0:3]
	v_mfma_f32_16x16x32_bf16 v[4:7], v[8:11], v[120:123], 0
	v_mfma_f32_16x16x32_bf16 v[152:155], v[8:11], v[60:63], 0
	v_mfma_f32_16x16x32_bf16 v[160:163], v[8:11], v[104:107], 0
	v_mfma_f32_16x16x32_bf16 v[168:171], v[8:11], v[112:115], 0
	v_mfma_f32_16x16x32_bf16 v[4:7], v[12:15], v[124:127], v[4:7]
	v_mfma_f32_16x16x32_bf16 v[152:155], v[12:15], v[100:103], v[152:155]
	v_mfma_f32_16x16x32_bf16 v[160:163], v[12:15], v[108:111], v[160:163]
	v_mfma_f32_16x16x32_bf16 v[168:171], v[12:15], v[116:119], v[168:171]
	s_setprio 0
	s_setprio 1
	v_mfma_f32_16x16x32_bf16 v[8:11], v[16:19], v[60:63], 0
	v_mfma_f32_16x16x32_bf16 v[12:15], v[24:27], v[60:63], 0
	v_mfma_f32_16x16x32_bf16 v[8:11], v[20:23], v[100:103], v[8:11]
	v_mfma_f32_16x16x32_bf16 v[12:15], v[28:31], v[100:103], v[12:15]
	v_mfma_f32_16x16x32_bf16 v[60:63], v[16:19], v[104:107], 0
	v_mfma_f32_16x16x32_bf16 v[100:103], v[24:27], v[104:107], 0
	v_mfma_f32_16x16x32_bf16 v[104:107], v[16:19], v[112:115], 0
	v_mfma_f32_16x16x32_bf16 v[16:19], v[16:19], v[120:123], 0
	v_mfma_f32_16x16x32_bf16 v[60:63], v[20:23], v[108:111], v[60:63]
	v_mfma_f32_16x16x32_bf16 v[100:103], v[28:31], v[108:111], v[100:103]
	v_mfma_f32_16x16x32_bf16 v[104:107], v[20:23], v[116:119], v[104:107]
	v_mfma_f32_16x16x32_bf16 v[108:111], v[24:27], v[112:115], 0
	v_mfma_f32_16x16x32_bf16 v[16:19], v[20:23], v[124:127], v[16:19]
	v_mfma_f32_16x16x32_bf16 v[20:23], v[24:27], v[120:123], 0
	v_mfma_f32_16x16x32_bf16 v[108:111], v[28:31], v[116:119], v[108:111]
	v_mfma_f32_16x16x32_bf16 v[20:23], v[28:31], v[124:127], v[20:23]
	s_setprio 0
	s_barrier
	s_add_i32 s93, 0, 0x18000
	s_add_i32 s94, 0, 0x1c000
	v_add_u32_e32 v226, s93, v143
	v_add_u32_e32 v227, s94, v143
	ds_read_b128 v[24:27], v226
	ds_read_b128 v[28:31], v226 offset:1024
	ds_read_b128 v[112:115], v226 offset:2048
	ds_read_b128 v[116:119], v226 offset:3072
	ds_read_b128 v[120:123], v227
	ds_read_b128 v[124:127], v227 offset:1024
	ds_read_b128 v[172:175], v227 offset:2048
	ds_read_b128 v[176:179], v227 offset:3072
	s_add_u32 s96, s48, 0x10100
	s_addc_u32 s97, s49, 0
	s_mov_b32 m0, s64
	v_lshl_add_u64 v[224:225], s[96:97], 0, v[130:131]
	ds_read_b128 v[190:193], v149 offset:32768
	ds_read_b128 v[194:197], v149 offset:33792
	ds_read_b128 v[198:201], v149 offset:34816
	ds_read_b128 v[202:205], v149 offset:35840
	ds_read_b128 v[206:209], v149 offset:36864
	ds_read_b128 v[210:213], v149 offset:37888
	ds_read_b128 v[214:217], v149 offset:38912
	ds_read_b128 v[218:221], v149 offset:39936
	global_load_lds_dwordx4 v[224:225], off
	v_lshl_add_u64 v[224:225], s[96:97], 0, v[128:129]
	s_mov_b32 m0, s65
	s_nop 0
	global_load_lds_dwordx4 v[224:225], off
	s_waitcnt vmcnt(8)
	s_waitcnt lgkmcnt(0)
	s_barrier
	s_setprio 1
	s_waitcnt lgkmcnt(0)
	v_mfma_f32_16x16x32_bf16 v[64:67], v[24:27], v[190:193], v[64:67]
	v_mfma_f32_16x16x32_bf16 v[72:75], v[24:27], v[198:201], v[72:75]
	v_mfma_f32_16x16x32_bf16 v[80:83], v[24:27], v[206:209], v[80:83]
	v_mfma_f32_16x16x32_bf16 v[88:91], v[24:27], v[214:217], v[88:91]
	v_mfma_f32_16x16x32_bf16 v[92:95], v[112:115], v[214:217], v[92:95]
	v_mfma_f32_16x16x32_bf16 v[84:87], v[112:115], v[206:209], v[84:87]
	v_mfma_f32_16x16x32_bf16 v[76:79], v[112:115], v[198:201], v[76:79]
	v_mfma_f32_16x16x32_bf16 v[68:71], v[112:115], v[190:193], v[68:71]
	v_mfma_f32_16x16x32_bf16 v[64:67], v[28:31], v[194:197], v[64:67]
	v_mfma_f32_16x16x32_bf16 v[72:75], v[28:31], v[202:205], v[72:75]
	v_mfma_f32_16x16x32_bf16 v[80:83], v[28:31], v[210:213], v[80:83]
	v_mfma_f32_16x16x32_bf16 v[88:91], v[28:31], v[218:221], v[88:91]
	v_mfma_f32_16x16x32_bf16 v[92:95], v[116:119], v[218:221], v[92:95]
	v_mfma_f32_16x16x32_bf16 v[84:87], v[116:119], v[210:213], v[84:87]
	v_mfma_f32_16x16x32_bf16 v[76:79], v[116:119], v[202:205], v[76:79]
	v_mfma_f32_16x16x32_bf16 v[68:71], v[116:119], v[194:197], v[68:71]
	s_setprio 0
	s_setprio 1
	v_mfma_f32_16x16x32_bf16 v[96:99], v[120:123], v[190:193], v[96:99]
	v_mfma_f32_16x16x32_bf16 v[36:39], v[120:123], v[198:201], v[36:39]
	v_mfma_f32_16x16x32_bf16 v[44:47], v[120:123], v[206:209], v[44:47]
	v_mfma_f32_16x16x32_bf16 v[52:55], v[120:123], v[214:217], v[52:55]
	v_mfma_f32_16x16x32_bf16 v[56:59], v[172:175], v[214:217], v[56:59]
	v_mfma_f32_16x16x32_bf16 v[48:51], v[172:175], v[206:209], v[48:51]
	v_mfma_f32_16x16x32_bf16 v[40:43], v[172:175], v[198:201], v[40:43]
	v_mfma_f32_16x16x32_bf16 v[32:35], v[172:175], v[190:193], v[32:35]
	v_mfma_f32_16x16x32_bf16 v[96:99], v[124:127], v[194:197], v[96:99]
	v_mfma_f32_16x16x32_bf16 v[36:39], v[124:127], v[202:205], v[36:39]
	v_mfma_f32_16x16x32_bf16 v[44:47], v[124:127], v[210:213], v[44:47]
	v_mfma_f32_16x16x32_bf16 v[52:55], v[124:127], v[218:221], v[52:55]
	v_mfma_f32_16x16x32_bf16 v[56:59], v[176:179], v[218:221], v[56:59]
	v_mfma_f32_16x16x32_bf16 v[48:51], v[176:179], v[210:213], v[48:51]
	v_mfma_f32_16x16x32_bf16 v[40:43], v[176:179], v[202:205], v[40:43]
	v_mfma_f32_16x16x32_bf16 v[32:35], v[176:179], v[194:197], v[32:35]
	s_setprio 0
	s_barrier
; #define PG8_STAGE(bufoff, gbase, voff) do { _Pragma("unroll") for (int _i = 0; _i < 2; ++_i) \
;         __builtin_amdgcn_global_load_lds((const unsigned*)((const char*)(gbase) + (voff)[_i]), (PG8_LAS unsigned*)(lds + (bufoff) + ldsw + _i * 8192), 16, 0, 0); } while (0)
; #define PG8_LDA(dst, b, h) do { _Pragma("unroll") for (int m = 0; m < 4; ++m) _Pragma("unroll") for (int k = 0; k < 2; ++k) dst[m][k] = *(const PG8_LAS bf16x8*)(lds + PG8_SA(b, h) + aoff + m * 2048 + k * 1024); } while (0)
; #define PG8_LDB(dst, b, h) do { _Pragma("unroll") for (int n = 0; n < 2; ++n) _Pragma("unroll") for (int k = 0; k < 2; ++k) dst[n][k] = *(const PG8_LAS bf16x8*)(lds + PG8_SB(b, h) + boff + n * 2048 + k * 1024); } while (0)
; #define PG8_MMA(ai, bj, At, Bt) do { __builtin_amdgcn_s_setprio(1); _Pragma("unroll") for (int m = 0; m < 4; ++m) _Pragma("unroll") for (int n = 0; n < 2; ++n) _Pragma("unroll") for (int k = 0; k < 2; ++k) \
;         acc[ai][bj][m][n] = __builtin_amdgcn_mfma_f32_16x16x32_bf16(Bt[n][k], At[m][k], acc[ai][bj][m][n], 0, 0, 0); __builtin_amdgcn_s_setprio(0); } while (0)
; #define PG8_WAIT_V(n) asm volatile("s_waitcnt vmcnt(" #n ")" ::: "memory")
; template <class Epi, class Sched, bool ALIGN_EPI = false, bool SP2 = false>
; __device__ __forceinline__ void gemm_phase(PG8_LAS unsigned char* lds, const Gemm g, const Sched& S, const Epi& E) {
;     ...
;             PG8_LDB(B0, 0, 0); PG8_LDB(B1, 0, 1); PG8_SCHED; PG8_LDA(At, 0, 0); PG8_STAGE(PG8_SA(1, 1), a1 + hstep, voffA);
;             PG8_WAIT_V(8); PG8_WAIT_L(0); PG8_BAR; PG8_MMA(0, 0, At, B0); PG8_MMA(0, 1, At, B1); PG8_BAR; PG8_SCHED;
;             PG8_LDA(At, 0, 1); PG8_STAGE(PG8_SB(0, 0), b2, voffB); PG8_STAGE(PG8_SB(0, 1), b2 + hstep, voffB); PG8_STAGE(PG8_SA(0, 0), a2, voffA);
;             PG8_WAIT_V(8); PG8_WAIT_L(0); PG8_BAR; PG8_MMA(1, 0, At, B0); PG8_MMA(1, 1, At, B1); PG8_BAR; PG8_SCHED;
;             PG8_LDB(B0, 1, 0); PG8_LDB(B1, 1, 1); PG8_SCHED; PG8_LDA(At, 1, 0); PG8_STAGE(PG8_SA(0, 1), a2 + hstep, voffA);
;             PG8_WAIT_V(8); PG8_WAIT_L(0); PG8_BAR; PG8_MMA(0, 0, At, B0); PG8_MMA(0, 1, At, B1); PG8_BAR; PG8_SCHED;
;             PG8_LDA(At, 1, 1); PG8_STAGE(PG8_SB(1, 0), b3, voffB); PG8_STAGE(PG8_SB(1, 1), b3 + hstep, voffB); PG8_STAGE(PG8_SA(1, 0), a3, voffA);
;             PG8_WAIT_V(8); PG8_WAIT_L(0); PG8_BAR; PG8_MMA(1, 0, At, B0); PG8_MMA(1, 1, At, B1); PG8_BAR; PG8_SCHED;
	s_add_i32 s93, s93, s3
	s_add_i32 s90, s93, 0x2000
	v_lshl_add_u64 v[140:141], v[140:141], 0, s[36:37]
	s_mov_b32 m0, s93
	s_add_u32 s96, s60, 0x10180
	ds_read_b128 v[190:193], v149 offset:49152
	ds_read_b128 v[194:197], v149 offset:50176
	ds_read_b128 v[198:201], v149 offset:51200
	ds_read_b128 v[202:205], v149 offset:52224
	ds_read_b128 v[206:209], v149 offset:53248
	ds_read_b128 v[210:213], v149 offset:54272
	ds_read_b128 v[214:217], v149 offset:55296
	ds_read_b128 v[218:221], v149 offset:56320
	global_load_lds_dwordx4 v[140:141], off
	v_lshl_add_u64 v[140:141], v[180:181], 0, s[36:37]
	s_mov_b32 m0, s90
	s_addc_u32 s97, s61, 0
	s_add_i32 s60, s94, s3
	global_load_lds_dwordx4 v[140:141], off
	v_lshl_add_u64 v[140:141], s[96:97], 0, v[130:131]
	s_mov_b32 m0, s60
	s_add_i32 s61, s60, 0x2000
	global_load_lds_dwordx4 v[140:141], off
	v_lshl_add_u64 v[140:141], s[96:97], 0, v[128:129]
	s_mov_b32 m0, s61
	s_nop 0
	global_load_lds_dwordx4 v[140:141], off
	v_lshl_add_u64 v[140:141], v[188:189], 0, s[36:37]
	s_mov_b32 m0, s66
	s_nop 0
	global_load_lds_dwordx4 v[140:141], off
	v_lshl_add_u64 v[140:141], v[222:223], 0, s[36:37]
	s_mov_b32 m0, s67
	s_nop 0
	global_load_lds_dwordx4 v[140:141], off
	s_waitcnt vmcnt(8)
	s_waitcnt lgkmcnt(0)
	s_barrier
	s_setprio 1
	s_waitcnt lgkmcnt(0)
	v_mfma_f32_16x16x32_bf16 v[0:3], v[24:27], v[214:217], v[0:3]
	v_mfma_f32_16x16x32_bf16 v[136:139], v[24:27], v[190:193], v[136:139]
	v_mfma_f32_16x16x32_bf16 v[156:159], v[24:27], v[198:201], v[156:159]
	v_mfma_f32_16x16x32_bf16 v[164:167], v[24:27], v[206:209], v[164:167]
	v_mfma_f32_16x16x32_bf16 v[168:171], v[112:115], v[206:209], v[168:171]
	v_mfma_f32_16x16x32_bf16 v[160:163], v[112:115], v[198:201], v[160:163]
	v_mfma_f32_16x16x32_bf16 v[152:155], v[112:115], v[190:193], v[152:155]
	v_mfma_f32_16x16x32_bf16 v[4:7], v[112:115], v[214:217], v[4:7]
	v_mfma_f32_16x16x32_bf16 v[0:3], v[28:31], v[218:221], v[0:3]
	v_mfma_f32_16x16x32_bf16 v[136:139], v[28:31], v[194:197], v[136:139]
	v_mfma_f32_16x16x32_bf16 v[156:159], v[28:31], v[202:205], v[156:159]
	v_mfma_f32_16x16x32_bf16 v[164:167], v[28:31], v[210:213], v[164:167]
	v_mfma_f32_16x16x32_bf16 v[168:171], v[116:119], v[210:213], v[168:171]
	v_mfma_f32_16x16x32_bf16 v[160:163], v[116:119], v[202:205], v[160:163]
	v_mfma_f32_16x16x32_bf16 v[152:155], v[116:119], v[194:197], v[152:155]
	v_mfma_f32_16x16x32_bf16 v[4:7], v[116:119], v[218:221], v[4:7]
	s_setprio 0
	s_setprio 1
	v_mfma_f32_16x16x32_bf16 v[8:11], v[120:123], v[190:193], v[8:11]
	v_mfma_f32_16x16x32_bf16 v[12:15], v[172:175], v[190:193], v[12:15]
	v_mfma_f32_16x16x32_bf16 v[24:27], v[120:123], v[198:201], v[60:63]
	v_mfma_f32_16x16x32_bf16 v[28:31], v[172:175], v[198:201], v[100:103]
	v_mfma_f32_16x16x32_bf16 v[60:63], v[120:123], v[206:209], v[104:107]
	v_mfma_f32_16x16x32_bf16 v[100:103], v[172:175], v[206:209], v[108:111]
	v_mfma_f32_16x16x32_bf16 v[16:19], v[120:123], v[214:217], v[16:19]
	v_mfma_f32_16x16x32_bf16 v[20:23], v[172:175], v[214:217], v[20:23]
	v_mfma_f32_16x16x32_bf16 v[8:11], v[124:127], v[194:197], v[8:11]
	v_mfma_f32_16x16x32_bf16 v[12:15], v[176:179], v[194:197], v[12:15]
	v_mfma_f32_16x16x32_bf16 v[24:27], v[124:127], v[202:205], v[24:27]
	v_mfma_f32_16x16x32_bf16 v[28:31], v[176:179], v[202:205], v[28:31]
	v_mfma_f32_16x16x32_bf16 v[60:63], v[124:127], v[210:213], v[60:63]
	v_mfma_f32_16x16x32_bf16 v[100:103], v[176:179], v[210:213], v[100:103]
	v_mfma_f32_16x16x32_bf16 v[16:19], v[124:127], v[218:221], v[16:19]
	v_mfma_f32_16x16x32_bf16 v[20:23], v[176:179], v[218:221], v[20:23]
	s_setprio 0
	s_barrier
	ds_read_b128 v[104:107], v147
	ds_read_b128 v[108:111], v147 offset:1024
	ds_read_b128 v[112:115], v147 offset:2048
	ds_read_b128 v[116:119], v147 offset:3072
	ds_read_b128 v[120:123], v148
	ds_read_b128 v[124:127], v148 offset:1024
	ds_read_b128 v[172:175], v148 offset:2048
	ds_read_b128 v[176:179], v148 offset:3072
	s_add_u32 s48, s48, 0x10180
	s_addc_u32 s49, s49, 0
	s_mov_b32 m0, s92
	v_lshl_add_u64 v[140:141], s[48:49], 0, v[130:131]
	ds_read_b128 v[190:193], v149
	ds_read_b128 v[194:197], v149 offset:1024
	ds_read_b128 v[198:201], v149 offset:2048
	ds_read_b128 v[202:205], v149 offset:3072
	ds_read_b128 v[206:209], v149 offset:4096
	ds_read_b128 v[210:213], v149 offset:5120
	ds_read_b128 v[214:217], v149 offset:6144
	ds_read_b128 v[218:221], v149 offset:7168
	global_load_lds_dwordx4 v[140:141], off
	v_lshl_add_u64 v[140:141], s[48:49], 0, v[128:129]
	s_mov_b32 m0, s39
	s_nop 0
	global_load_lds_dwordx4 v[140:141], off
	s_waitcnt vmcnt(8)
	s_waitcnt lgkmcnt(0)
	s_barrier
; #define PG8_STAGE(bufoff, gbase, voff) do { _Pragma("unroll") for (int _i = 0; _i < 2; ++_i) \
;         __builtin_amdgcn_global_load_lds((const unsigned*)((const char*)(gbase) + (voff)[_i]), (PG8_LAS unsigned*)(lds + (bufoff) + ldsw + _i * 8192), 16, 0, 0); } while (0)
; #define PG8_LDA(dst, b, h) do { _Pragma("unroll") for (int m = 0; m < 4; ++m) _Pragma("unroll") for (int k = 0; k < 2; ++k) dst[m][k] = *(const PG8_LAS bf16x8*)(lds + PG8_SA(b, h) + aoff + m * 2048 + k * 1024); } while (0)
; #define PG8_LDB(dst, b, h) do { _Pragma("unroll") for (int n = 0; n < 2; ++n) _Pragma("unroll") for (int k = 0; k < 2; ++k) dst[n][k] = *(const PG8_LAS bf16x8*)(lds + PG8_SB(b, h) + boff + n * 2048 + k * 1024); } while (0)
; #define PG8_MMA(ai, bj, At, Bt) do { __builtin_amdgcn_s_setprio(1); _Pragma("unroll") for (int m = 0; m < 4; ++m) _Pragma("unroll") for (int n = 0; n < 2; ++n) _Pragma("unroll") for (int k = 0; k < 2; ++k) \
;         acc[ai][bj][m][n] = __builtin_amdgcn_mfma_f32_16x16x32_bf16(Bt[n][k], At[m][k], acc[ai][bj][m][n], 0, 0, 0); __builtin_amdgcn_s_setprio(0); } while (0)
; #define PG8_WAIT_V(n) asm volatile("s_waitcnt vmcnt(" #n ")" ::: "memory")
; #define PG8_WAIT_L(n) asm volatile("s_waitcnt lgkmcnt(" #n ")" ::: "memory")
; #define PG8_BAR __builtin_amdgcn_s_barrier()
; #define PG8_SCHED __builtin_amdgcn_sched_barrier(0)
; template <class Epi, class Sched, bool ALIGN_EPI = false, bool SP2 = false>
; __device__ __forceinline__ void gemm_phase(PG8_LAS unsigned char* lds, const Gemm g, const Sched& S, const Epi& E) {
;     ...
;             PG8_LDB(B0, 0, 0); PG8_LDB(B1, 0, 1); PG8_SCHED; PG8_LDA(At, 0, 0); PG8_STAGE(PG8_SA(1, 1), a1 + hstep, voffA);
;             PG8_WAIT_V(8); PG8_WAIT_L(0); PG8_BAR; PG8_MMA(0, 0, At, B0); PG8_MMA(0, 1, At, B1); PG8_BAR; PG8_SCHED;
;             PG8_LDA(At, 0, 1); PG8_STAGE(PG8_SB(0, 0), b2, voffB); PG8_STAGE(PG8_SB(0, 1), b2 + hstep, voffB); PG8_STAGE(PG8_SA(0, 0), a2, voffA);
;             PG8_WAIT_V(8); PG8_WAIT_L(0); PG8_BAR; PG8_MMA(1, 0, At, B0); PG8_MMA(1, 1, At, B1); PG8_BAR; PG8_SCHED;
	s_setprio 1
	s_waitcnt lgkmcnt(0)
	v_mfma_f32_16x16x32_bf16 v[64:67], v[104:107], v[190:193], v[64:67]
	v_mfma_f32_16x16x32_bf16 v[72:75], v[104:107], v[198:201], v[72:75]
	v_mfma_f32_16x16x32_bf16 v[80:83], v[104:107], v[206:209], v[80:83]
	v_mfma_f32_16x16x32_bf16 v[88:91], v[104:107], v[214:217], v[88:91]
	v_mfma_f32_16x16x32_bf16 v[92:95], v[112:115], v[214:217], v[92:95]
	v_mfma_f32_16x16x32_bf16 v[84:87], v[112:115], v[206:209], v[84:87]
	v_mfma_f32_16x16x32_bf16 v[76:79], v[112:115], v[198:201], v[76:79]
	v_mfma_f32_16x16x32_bf16 v[68:71], v[112:115], v[190:193], v[68:71]
	v_mfma_f32_16x16x32_bf16 v[64:67], v[108:111], v[194:197], v[64:67]
	v_mfma_f32_16x16x32_bf16 v[72:75], v[108:111], v[202:205], v[72:75]
	v_mfma_f32_16x16x32_bf16 v[80:83], v[108:111], v[210:213], v[80:83]
	v_mfma_f32_16x16x32_bf16 v[88:91], v[108:111], v[218:221], v[88:91]
	v_mfma_f32_16x16x32_bf16 v[92:95], v[116:119], v[218:221], v[92:95]
	v_mfma_f32_16x16x32_bf16 v[84:87], v[116:119], v[210:213], v[84:87]
	v_mfma_f32_16x16x32_bf16 v[76:79], v[116:119], v[202:205], v[76:79]
	v_mfma_f32_16x16x32_bf16 v[68:71], v[116:119], v[194:197], v[68:71]
	s_setprio 0
	s_setprio 1
	v_mfma_f32_16x16x32_bf16 v[32:35], v[172:175], v[190:193], v[32:35]
	v_mfma_f32_16x16x32_bf16 v[36:39], v[120:123], v[198:201], v[36:39]
	v_mfma_f32_16x16x32_bf16 v[40:43], v[172:175], v[198:201], v[40:43]
	v_mfma_f32_16x16x32_bf16 v[44:47], v[120:123], v[206:209], v[44:47]
	v_mfma_f32_16x16x32_bf16 v[48:51], v[172:175], v[206:209], v[48:51]
	v_mfma_f32_16x16x32_bf16 v[52:55], v[120:123], v[214:217], v[52:55]
	v_mfma_f32_16x16x32_bf16 v[56:59], v[172:175], v[214:217], v[56:59]
	v_mfma_f32_16x16x32_bf16 v[96:99], v[120:123], v[190:193], v[96:99]
	v_mfma_f32_16x16x32_bf16 v[32:35], v[176:179], v[194:197], v[32:35]
	v_mfma_f32_16x16x32_bf16 v[36:39], v[124:127], v[202:205], v[36:39]
	v_mfma_f32_16x16x32_bf16 v[40:43], v[176:179], v[202:205], v[40:43]
	v_mfma_f32_16x16x32_bf16 v[44:47], v[124:127], v[210:213], v[44:47]
	v_mfma_f32_16x16x32_bf16 v[48:51], v[176:179], v[210:213], v[48:51]
	v_mfma_f32_16x16x32_bf16 v[52:55], v[124:127], v[218:221], v[52:55]
	v_mfma_f32_16x16x32_bf16 v[56:59], v[176:179], v[218:221], v[56:59]
	v_mfma_f32_16x16x32_bf16 v[222:225], v[124:127], v[194:197], v[96:99]
	s_setprio 0
	s_barrier
	s_mov_b32 m0, s89
	v_lshl_add_u64 v[140:141], s[58:59], 0, v[130:131]
	s_add_u32 s48, s58, 0x10000
	ds_read_b128 v[96:99], v149 offset:16384
	ds_read_b128 v[190:193], v149 offset:17408
	ds_read_b128 v[194:197], v149 offset:18432
	ds_read_b128 v[198:201], v149 offset:19456
	ds_read_b128 v[202:205], v149 offset:20480
	ds_read_b128 v[206:209], v149 offset:21504
	ds_read_b128 v[210:213], v149 offset:22528
	ds_read_b128 v[214:217], v149 offset:23552
	global_load_lds_dwordx4 v[140:141], off
	v_lshl_add_u64 v[180:181], s[58:59], 0, v[128:129]
	s_mov_b32 m0, s41
	s_addc_u32 s49, s59, 0
	global_load_lds_dwordx4 v[180:181], off
	v_lshl_add_u64 v[188:189], s[48:49], 0, v[130:131]
	s_mov_b32 m0, s86
	v_lshl_add_u64 v[250:251], s[62:63], 0, v[128:129]
	global_load_lds_dwordx4 v[188:189], off
	v_lshl_add_u64 v[188:189], s[48:49], 0, v[128:129]
	s_mov_b32 m0, s87
	s_nop 0
	global_load_lds_dwordx4 v[188:189], off
	v_lshl_add_u64 v[188:189], s[62:63], 0, v[130:131]
	s_mov_b32 m0, s35
	s_nop 0
	global_load_lds_dwordx4 v[188:189], off
	s_mov_b32 m0, s47
	s_nop 0
	global_load_lds_dwordx4 v[250:251], off
	s_waitcnt vmcnt(8)
	s_waitcnt lgkmcnt(0)
	s_barrier
	s_setprio 1
	s_waitcnt lgkmcnt(0)
	v_mfma_f32_16x16x32_bf16 v[0:3], v[104:107], v[210:213], v[0:3]
	v_mfma_f32_16x16x32_bf16 v[136:139], v[104:107], v[96:99], v[136:139]
	v_mfma_f32_16x16x32_bf16 v[156:159], v[104:107], v[194:197], v[156:159]
	v_mfma_f32_16x16x32_bf16 v[164:167], v[104:107], v[202:205], v[164:167]
	v_mfma_f32_16x16x32_bf16 v[168:171], v[112:115], v[202:205], v[168:171]
	v_mfma_f32_16x16x32_bf16 v[160:163], v[112:115], v[194:197], v[160:163]
	v_mfma_f32_16x16x32_bf16 v[152:155], v[112:115], v[96:99], v[152:155]
	v_mfma_f32_16x16x32_bf16 v[4:7], v[112:115], v[210:213], v[4:7]
	v_mfma_f32_16x16x32_bf16 v[0:3], v[108:111], v[214:217], v[0:3]
	v_mfma_f32_16x16x32_bf16 v[136:139], v[108:111], v[190:193], v[136:139]
	v_mfma_f32_16x16x32_bf16 v[156:159], v[108:111], v[198:201], v[156:159]
	v_mfma_f32_16x16x32_bf16 v[164:167], v[108:111], v[206:209], v[164:167]
	v_mfma_f32_16x16x32_bf16 v[168:171], v[116:119], v[206:209], v[168:171]
	v_mfma_f32_16x16x32_bf16 v[160:163], v[116:119], v[198:201], v[160:163]
	v_mfma_f32_16x16x32_bf16 v[152:155], v[116:119], v[190:193], v[152:155]
	v_mfma_f32_16x16x32_bf16 v[4:7], v[116:119], v[214:217], v[4:7]
	s_setprio 0
	s_setprio 1
	v_mfma_f32_16x16x32_bf16 v[8:11], v[120:123], v[96:99], v[8:11]
	v_mfma_f32_16x16x32_bf16 v[12:15], v[172:175], v[96:99], v[12:15]
	v_mfma_f32_16x16x32_bf16 v[24:27], v[120:123], v[194:197], v[24:27]
	v_mfma_f32_16x16x32_bf16 v[28:31], v[172:175], v[194:197], v[28:31]
	v_mfma_f32_16x16x32_bf16 v[60:63], v[120:123], v[202:205], v[60:63]
	v_mfma_f32_16x16x32_bf16 v[16:19], v[120:123], v[210:213], v[16:19]
	v_mfma_f32_16x16x32_bf16 v[8:11], v[124:127], v[190:193], v[8:11]
	v_mfma_f32_16x16x32_bf16 v[12:15], v[176:179], v[190:193], v[12:15]
	v_mfma_f32_16x16x32_bf16 v[24:27], v[124:127], v[198:201], v[24:27]
	v_mfma_f32_16x16x32_bf16 v[28:31], v[176:179], v[198:201], v[28:31]
	v_mfma_f32_16x16x32_bf16 v[190:193], v[124:127], v[206:209], v[60:63]
	v_mfma_f32_16x16x32_bf16 v[60:63], v[172:175], v[202:205], v[100:103]
	v_mfma_f32_16x16x32_bf16 v[198:201], v[124:127], v[214:217], v[16:19]
	v_mfma_f32_16x16x32_bf16 v[16:19], v[172:175], v[210:213], v[20:23]
	v_mfma_f32_16x16x32_bf16 v[194:197], v[176:179], v[206:209], v[60:63]
	v_mfma_f32_16x16x32_bf16 v[172:175], v[176:179], v[214:217], v[16:19]
	s_setprio 0
	s_barrier
; #define PG8_STAGE(bufoff, gbase, voff) do { _Pragma("unroll") for (int _i = 0; _i < 2; ++_i) \
;         __builtin_amdgcn_global_load_lds((const unsigned*)((const char*)(gbase) + (voff)[_i]), (PG8_LAS unsigned*)(lds + (bufoff) + ldsw + _i * 8192), 16, 0, 0); } while (0)
; #define PG8_BAR __builtin_amdgcn_s_barrier()
; template <class Epi, class Sched, bool ALIGN_EPI = false, bool SP2 = false>
; __device__ __forceinline__ void gemm_phase(PG8_LAS unsigned char* lds, const Gemm g, const Sched& S, const Epi& E) {
;     ...
;             PG8_LDB(B0, 1, 0); PG8_LDB(B1, 1, 1); PG8_SCHED; PG8_LDA(At, 1, 0); PG8_STAGE(PG8_SA(0, 1), a2 + hstep, voffA);
;             PG8_WAIT_V(8); PG8_WAIT_L(0); PG8_BAR; PG8_MMA(0, 0, At, B0); PG8_MMA(0, 1, At, B1); PG8_BAR; PG8_SCHED;
;             PG8_LDA(At, 1, 1); PG8_STAGE(PG8_SB(1, 0), b3, voffB); PG8_STAGE(PG8_SB(1, 1), b3 + hstep, voffB); PG8_STAGE(PG8_SA(1, 0), a3, voffA);
;             PG8_WAIT_V(8); PG8_WAIT_L(0); PG8_BAR; PG8_MMA(1, 0, At, B0); PG8_MMA(1, 1, At, B1); PG8_BAR; PG8_SCHED;
;             } else {
;             PG8_LDB(B0, 0, 0); PG8_SCHED; PG8_LDA(At, 0, 0); PG8_STAGE(PG8_SA(1, 1), a1 + hstep, voffA);
;             PG8_WAIT_L(8); PG8_BAR; PG8_WAIT_L(0); PG8_MMA(0, 0, At, B0); PG8_BAR; PG8_SCHED;
;             PG8_LDB(B1, 0, 1); PG8_STAGE(PG8_SB(0, 0), b2, voffB);
;             PG8_BAR; PG8_WAIT_L(0); PG8_MMA(0, 1, At, B1); PG8_BAR;
;             PG8_LDA(At, 0, 1); PG8_STAGE(PG8_SA(0, 0), a2, voffA);
;             PG8_BAR; PG8_WAIT_L(0); PG8_MMA(1, 0, At, B0); PG8_BAR; PG8_SCHED;
;             PG8_STAGE(PG8_SB(0, 1), b2 + hstep, voffB);
;             PG8_WAIT_V(6); PG8_BAR; PG8_MMA(1, 1, At, B1); PG8_BAR;
;             PG8_LDB(B0, 1, 0); PG8_SCHED; PG8_LDA(At, 1, 0); PG8_STAGE(PG8_SA(0, 1), a2 + hstep, voffA);
;             PG8_WAIT_L(8); PG8_BAR; PG8_WAIT_L(0); PG8_MMA(0, 0, At, B0); PG8_BAR; PG8_SCHED;
;             PG8_LDB(B1, 1, 1); PG8_STAGE(PG8_SB(1, 0), b3, voffB);
;             PG8_BAR; PG8_WAIT_L(0); PG8_MMA(0, 1, At, B1); PG8_BAR;
;             PG8_LDA(At, 1, 1); PG8_STAGE(PG8_SA(1, 0), a3, voffA);
;             PG8_BAR; PG8_WAIT_L(0); PG8_MMA(1, 0, At, B0); PG8_BAR; PG8_SCHED;
;             PG8_STAGE(PG8_SB(1, 1), b3 + hstep, voffB);
;             PG8_WAIT_V(6); PG8_BAR; PG8_MMA(1, 1, At, B1); PG8_BAR;
;             }
;         }
;         if constexpr (ALIGN_EPI) { if (wr == 0) PG8_BAR; }
	s_nop 1
	ds_read_b128 v[60:63], v226
	ds_read_b128 v[176:179], v226 offset:1024
	ds_read_b128 v[202:205], v226 offset:2048
	ds_read_b128 v[206:209], v226 offset:3072
	ds_read_b128 v[210:213], v227
	ds_read_b128 v[214:217], v227 offset:1024
	ds_read_b128 v[218:221], v227 offset:2048
	ds_read_b128 v[226:229], v227 offset:3072
	s_add_u32 s48, s62, 0x10000
	s_addc_u32 s49, s63, 0
	s_mov_b32 m0, s64
	v_lshl_add_u64 v[96:97], s[48:49], 0, v[130:131]
	ds_read_b128 v[16:19], v149 offset:32768
	ds_read_b128 v[20:23], v149 offset:33792
	ds_read_b128 v[104:107], v149 offset:34816
	ds_read_b128 v[230:233], v149 offset:35840
	ds_read_b128 v[234:237], v149 offset:36864
	ds_read_b128 v[238:241], v149 offset:37888
	ds_read_b128 v[242:245], v149 offset:38912
	ds_read_b128 v[246:249], v149 offset:39936
	global_load_lds_dwordx4 v[96:97], off
	v_lshl_add_u64 v[96:97], s[48:49], 0, v[128:129]
	s_mov_b32 m0, s65
	s_nop 0
	global_load_lds_dwordx4 v[96:97], off
	s_waitcnt vmcnt(8)
	s_waitcnt lgkmcnt(0)
	s_barrier
	s_setprio 1
	s_waitcnt lgkmcnt(0)
	v_mfma_f32_16x16x32_bf16 v[64:67], v[60:63], v[16:19], v[64:67]
	v_mfma_f32_16x16x32_bf16 v[112:115], v[176:179], v[20:23], v[64:67]
	v_mfma_f32_16x16x32_bf16 v[64:67], v[202:205], v[16:19], v[68:71]
	v_mfma_f32_16x16x32_bf16 v[116:119], v[206:209], v[20:23], v[64:67]
	v_mfma_f32_16x16x32_bf16 v[64:67], v[60:63], v[104:107], v[72:75]
	v_mfma_f32_16x16x32_bf16 v[96:99], v[176:179], v[230:233], v[64:67]
	v_mfma_f32_16x16x32_bf16 v[64:67], v[202:205], v[104:107], v[76:79]
	v_mfma_f32_16x16x32_bf16 v[100:103], v[206:209], v[230:233], v[64:67]
	v_mfma_f32_16x16x32_bf16 v[64:67], v[60:63], v[234:237], v[80:83]
	v_mfma_f32_16x16x32_bf16 v[80:83], v[176:179], v[238:241], v[64:67]
	v_mfma_f32_16x16x32_bf16 v[64:67], v[202:205], v[234:237], v[84:87]
	v_mfma_f32_16x16x32_bf16 v[84:87], v[206:209], v[238:241], v[64:67]
	v_mfma_f32_16x16x32_bf16 v[64:67], v[60:63], v[242:245], v[88:91]
	v_mfma_f32_16x16x32_bf16 v[68:71], v[202:205], v[242:245], v[92:95]
	v_mfma_f32_16x16x32_bf16 v[64:67], v[176:179], v[246:249], v[64:67]
	v_mfma_f32_16x16x32_bf16 v[68:71], v[206:209], v[246:249], v[68:71]
	s_setprio 0
	s_setprio 1
	v_mfma_f32_16x16x32_bf16 v[72:75], v[210:213], v[16:19], v[222:225]
	v_mfma_f32_16x16x32_bf16 v[16:19], v[218:221], v[16:19], v[32:35]
	v_mfma_f32_16x16x32_bf16 v[120:123], v[226:229], v[20:23], v[16:19]
	v_mfma_f32_16x16x32_bf16 v[16:19], v[210:213], v[104:107], v[36:39]
	v_mfma_f32_16x16x32_bf16 v[108:111], v[214:217], v[230:233], v[16:19]
	v_mfma_f32_16x16x32_bf16 v[16:19], v[218:221], v[104:107], v[40:43]
	v_mfma_f32_16x16x32_bf16 v[104:107], v[226:229], v[230:233], v[16:19]
	v_mfma_f32_16x16x32_bf16 v[16:19], v[210:213], v[234:237], v[44:47]
	v_mfma_f32_16x16x32_bf16 v[92:95], v[214:217], v[238:241], v[16:19]
	v_mfma_f32_16x16x32_bf16 v[16:19], v[218:221], v[234:237], v[48:51]
	v_mfma_f32_16x16x32_bf16 v[88:91], v[226:229], v[238:241], v[16:19]
	v_mfma_f32_16x16x32_bf16 v[16:19], v[210:213], v[242:245], v[52:55]
	v_mfma_f32_16x16x32_bf16 v[76:79], v[214:217], v[246:249], v[16:19]
	v_mfma_f32_16x16x32_bf16 v[16:19], v[218:221], v[242:245], v[56:59]
	v_mfma_f32_16x16x32_bf16 v[124:127], v[214:217], v[20:23], v[72:75]
	v_mfma_f32_16x16x32_bf16 v[72:75], v[226:229], v[246:249], v[16:19]
	s_setprio 0
	s_barrier
	s_mov_b32 m0, s93
	s_nop 2
	v_lshl_add_u64 v[16:17], v[140:141], 0, s[6:7]
	s_add_u32 s48, s58, 0x10080
	ds_read_b128 v[40:43], v149 offset:49152
	ds_read_b128 v[44:47], v149 offset:50176
	ds_read_b128 v[222:225], v149 offset:51200
	ds_read_b128 v[230:233], v149 offset:52224
	ds_read_b128 v[234:237], v149 offset:53248
	ds_read_b128 v[238:241], v149 offset:54272
	ds_read_b128 v[242:245], v149 offset:55296
	ds_read_b128 v[246:249], v149 offset:56320
	global_load_lds_dwordx4 v[16:17], off
	v_lshl_add_u64 v[16:17], v[180:181], 0, s[6:7]
	s_mov_b32 m0, s90
	s_addc_u32 s49, s59, 0
	global_load_lds_dwordx4 v[16:17], off
	v_lshl_add_u64 v[16:17], s[48:49], 0, v[130:131]
	s_mov_b32 m0, s60
	s_nop 0
	global_load_lds_dwordx4 v[16:17], off
	v_lshl_add_u64 v[16:17], s[48:49], 0, v[128:129]
	s_mov_b32 m0, s61
	s_nop 0
	global_load_lds_dwordx4 v[16:17], off
	v_lshl_add_u64 v[16:17], v[188:189], 0, s[6:7]
	s_mov_b32 m0, s66
	s_nop 0
	global_load_lds_dwordx4 v[16:17], off
	v_lshl_add_u64 v[16:17], v[250:251], 0, s[6:7]
	s_mov_b32 m0, s67
	s_nop 0
	global_load_lds_dwordx4 v[16:17], off
	s_waitcnt vmcnt(8)
	s_waitcnt lgkmcnt(0)
	s_barrier
	s_setprio 1
	s_waitcnt lgkmcnt(0)
	v_mfma_f32_16x16x32_bf16 v[16:19], v[60:63], v[40:43], v[136:139]
	v_mfma_f32_16x16x32_bf16 v[48:51], v[176:179], v[44:47], v[16:19]
	v_mfma_f32_16x16x32_bf16 v[16:19], v[202:205], v[40:43], v[152:155]
	v_mfma_f32_16x16x32_bf16 v[52:55], v[206:209], v[44:47], v[16:19]
	v_mfma_f32_16x16x32_bf16 v[16:19], v[60:63], v[222:225], v[156:159]
	v_mfma_f32_16x16x32_bf16 v[32:35], v[176:179], v[230:233], v[16:19]
	v_mfma_f32_16x16x32_bf16 v[16:19], v[202:205], v[222:225], v[160:163]
	v_mfma_f32_16x16x32_bf16 v[36:39], v[206:209], v[230:233], v[16:19]
	v_mfma_f32_16x16x32_bf16 v[16:19], v[60:63], v[234:237], v[164:167]
	v_mfma_f32_16x16x32_bf16 v[20:23], v[202:205], v[234:237], v[168:171]
	v_mfma_f32_16x16x32_bf16 v[0:3], v[60:63], v[242:245], v[0:3]
	v_mfma_f32_16x16x32_bf16 v[4:7], v[202:205], v[242:245], v[4:7]
	v_mfma_f32_16x16x32_bf16 v[16:19], v[176:179], v[238:241], v[16:19]
	v_mfma_f32_16x16x32_bf16 v[20:23], v[206:209], v[238:241], v[20:23]
	v_mfma_f32_16x16x32_bf16 v[0:3], v[176:179], v[246:249], v[0:3]
	v_mfma_f32_16x16x32_bf16 v[4:7], v[206:209], v[246:249], v[4:7]
	s_setprio 0
	s_setprio 1
	v_mfma_f32_16x16x32_bf16 v[8:11], v[210:213], v[40:43], v[8:11]
	v_mfma_f32_16x16x32_bf16 v[60:63], v[214:217], v[44:47], v[8:11]
	v_mfma_f32_16x16x32_bf16 v[8:11], v[218:221], v[40:43], v[12:15]
	v_mfma_f32_16x16x32_bf16 v[56:59], v[226:229], v[44:47], v[8:11]
	v_mfma_f32_16x16x32_bf16 v[8:11], v[210:213], v[222:225], v[24:27]
	v_mfma_f32_16x16x32_bf16 v[44:47], v[214:217], v[230:233], v[8:11]
	v_mfma_f32_16x16x32_bf16 v[8:11], v[218:221], v[222:225], v[28:31]
	v_mfma_f32_16x16x32_bf16 v[40:43], v[226:229], v[230:233], v[8:11]
	v_mfma_f32_16x16x32_bf16 v[8:11], v[210:213], v[234:237], v[190:193]
	v_mfma_f32_16x16x32_bf16 v[28:31], v[214:217], v[238:241], v[8:11]
	v_mfma_f32_16x16x32_bf16 v[8:11], v[218:221], v[234:237], v[194:197]
	v_mfma_f32_16x16x32_bf16 v[24:27], v[226:229], v[238:241], v[8:11]
	v_mfma_f32_16x16x32_bf16 v[8:11], v[210:213], v[242:245], v[198:201]
	v_mfma_f32_16x16x32_bf16 v[12:15], v[218:221], v[242:245], v[172:175]
	v_mfma_f32_16x16x32_bf16 v[8:11], v[214:217], v[246:249], v[8:11]
	v_mfma_f32_16x16x32_bf16 v[12:15], v[226:229], v[246:249], v[12:15]
	s_setprio 0
	s_barrier
	s_andn2_b64 vcc, exec, s[8:9]
	s_cbranch_vccnz .LBB0_183
	s_barrier

; #define PG8_STAGE(bufoff, gbase, voff) do { _Pragma("unroll") for (int _i = 0; _i < 2; ++_i) \
;         __builtin_amdgcn_global_load_lds((const unsigned*)((const char*)(gbase) + (voff)[_i]), (PG8_LAS unsigned*)(lds + (bufoff) + ldsw + _i * 8192), 16, 0, 0); } while (0)
; #define PG8_LDA(dst, b, h) do { _Pragma("unroll") for (int m = 0; m < 4; ++m) _Pragma("unroll") for (int k = 0; k < 2; ++k) dst[m][k] = *(const PG8_LAS bf16x8*)(lds + PG8_SA(b, h) + aoff + m * 2048 + k * 1024); } while (0)
; #define PG8_LDB(dst, b, h) do { _Pragma("unroll") for (int n = 0; n < 2; ++n) _Pragma("unroll") for (int k = 0; k < 2; ++k) dst[n][k] = *(const PG8_LAS bf16x8*)(lds + PG8_SB(b, h) + boff + n * 2048 + k * 1024); } while (0)
; #define PG8_MMA(ai, bj, At, Bt) do { __builtin_amdgcn_s_setprio(1); _Pragma("unroll") for (int m = 0; m < 4; ++m) _Pragma("unroll") for (int n = 0; n < 2; ++n) _Pragma("unroll") for (int k = 0; k < 2; ++k) \
;         acc[ai][bj][m][n] = __builtin_amdgcn_mfma_f32_16x16x32_bf16(Bt[n][k], At[m][k], acc[ai][bj][m][n], 0, 0, 0); __builtin_amdgcn_s_setprio(0); } while (0)
; #define PG8_WAIT_V(n) asm volatile("s_waitcnt vmcnt(" #n ")" ::: "memory")
; #define PG8_WAIT_L(n) asm volatile("s_waitcnt lgkmcnt(" #n ")" ::: "memory")
; #define PG8_BAR __builtin_amdgcn_s_barrier()
; #define PG8_SCHED __builtin_amdgcn_sched_barrier(0)
; template <class Epi, class Sched, bool ALIGN_EPI = false, bool SP2 = false>
; __device__ __forceinline__ void gemm_phase(PG8_LAS unsigned char* lds, const Gemm g, const Sched& S, const Epi& E) {
;     ...
;             const bool last = (t == nt - 2);
;             const char* a1 = cA + (size_t)(t + 1) * kstep;
;             const char* a2 = last ? nA : cA + (size_t)(t + 2) * kstep; const char* b2 = last ? nB : cB + (size_t)(t + 2) * kstep;
;             const char* a3 = a2 + kstep; const char* b3 = b2 + kstep;
;             if (last && has_next) S.a_ready(nxt);
;             if constexpr (SP2) {
;             PG8_LDB(B0, 0, 0); PG8_LDB(B1, 0, 1); PG8_SCHED; PG8_LDA(At, 0, 0); PG8_STAGE(PG8_SA(1, 1), a1 + hstep, voffA);
;             PG8_WAIT_V(8); PG8_WAIT_L(0); PG8_BAR; PG8_MMA(0, 0, At, B0); PG8_MMA(0, 1, At, B1); PG8_BAR; PG8_SCHED;
;             PG8_LDA(At, 0, 1); PG8_STAGE(PG8_SB(0, 0), b2, voffB); PG8_STAGE(PG8_SB(0, 1), b2 + hstep, voffB); PG8_STAGE(PG8_SA(0, 0), a2, voffA);
.LBB0_199:
	ds_read_b128 v[146:149], v162
	ds_read_b128 v[172:175], v162 offset:1024
	ds_read_b128 v[176:179], v162 offset:2048
	ds_read_b128 v[190:193], v162 offset:3072
	ds_read_b128 v[194:197], v163
	ds_read_b128 v[198:201], v163 offset:1024
	ds_read_b128 v[202:205], v163 offset:2048
	ds_read_b128 v[206:209], v163 offset:3072
	s_add_u32 s60, s58, 0xfff80080
	s_addc_u32 s61, s59, -1
	s_cmp_eq_u32 s94, 28
	s_cselect_b32 s63, s9, s61
	s_cselect_b32 s62, s43, s60
	s_cselect_b32 s61, s41, s93
	s_cselect_b32 s60, s90, s92
	v_lshl_add_u64 v[150:151], s[58:59], 0, v[136:137]
	s_add_i32 m0, s28, 0xc000
	ds_read_b128 v[210:213], v164
	ds_read_b128 v[214:217], v164 offset:1024
	ds_read_b128 v[218:221], v164 offset:2048
	ds_read_b128 v[222:225], v164 offset:3072
	ds_read_b128 v[226:229], v164 offset:4096
	ds_read_b128 v[230:233], v164 offset:5120
	ds_read_b128 v[234:237], v164 offset:6144
	ds_read_b128 v[238:241], v164 offset:7168
	global_load_lds_dwordx4 v[150:151], off
	v_lshl_add_u64 v[150:151], s[58:59], 0, v[138:139]
	s_add_i32 m0, s28, 0xe000
	s_nop 0
	global_load_lds_dwordx4 v[150:151], off
	s_waitcnt vmcnt(8)
	s_waitcnt lgkmcnt(0)
	s_barrier
	s_setprio 1
	s_waitcnt lgkmcnt(0)
	v_mfma_f32_16x16x32_bf16 v[124:127], v[146:149], v[210:213], v[124:127]
	v_mfma_f32_16x16x32_bf16 v[108:111], v[146:149], v[218:221], v[108:111]
	v_mfma_f32_16x16x32_bf16 v[92:95], v[146:149], v[226:229], v[92:95]
	v_mfma_f32_16x16x32_bf16 v[76:79], v[146:149], v[234:237], v[76:79]
	v_mfma_f32_16x16x32_bf16 v[72:75], v[176:179], v[234:237], v[72:75]
	v_mfma_f32_16x16x32_bf16 v[88:91], v[176:179], v[226:229], v[88:91]
	v_mfma_f32_16x16x32_bf16 v[104:107], v[176:179], v[218:221], v[104:107]
	v_mfma_f32_16x16x32_bf16 v[120:123], v[176:179], v[210:213], v[120:123]
	v_mfma_f32_16x16x32_bf16 v[124:127], v[172:175], v[214:217], v[124:127]
	v_mfma_f32_16x16x32_bf16 v[108:111], v[172:175], v[222:225], v[108:111]
	v_mfma_f32_16x16x32_bf16 v[92:95], v[172:175], v[230:233], v[92:95]
	v_mfma_f32_16x16x32_bf16 v[76:79], v[172:175], v[238:241], v[76:79]
	v_mfma_f32_16x16x32_bf16 v[72:75], v[190:193], v[238:241], v[72:75]
	v_mfma_f32_16x16x32_bf16 v[88:91], v[190:193], v[230:233], v[88:91]
	v_mfma_f32_16x16x32_bf16 v[104:107], v[190:193], v[222:225], v[104:107]
	v_mfma_f32_16x16x32_bf16 v[120:123], v[190:193], v[214:217], v[120:123]
	s_setprio 0
	s_setprio 1
	v_mfma_f32_16x16x32_bf16 v[116:119], v[194:197], v[210:213], v[116:119]
	v_mfma_f32_16x16x32_bf16 v[100:103], v[194:197], v[218:221], v[100:103]
	v_mfma_f32_16x16x32_bf16 v[84:87], v[194:197], v[226:229], v[84:87]
	v_mfma_f32_16x16x32_bf16 v[68:71], v[194:197], v[234:237], v[68:71]
	v_mfma_f32_16x16x32_bf16 v[64:67], v[202:205], v[234:237], v[64:67]
	v_mfma_f32_16x16x32_bf16 v[80:83], v[202:205], v[226:229], v[80:83]
	v_mfma_f32_16x16x32_bf16 v[96:99], v[202:205], v[218:221], v[96:99]
	v_mfma_f32_16x16x32_bf16 v[112:115], v[202:205], v[210:213], v[112:115]
	v_mfma_f32_16x16x32_bf16 v[116:119], v[198:201], v[214:217], v[116:119]
	v_mfma_f32_16x16x32_bf16 v[100:103], v[198:201], v[222:225], v[100:103]
	v_mfma_f32_16x16x32_bf16 v[84:87], v[198:201], v[230:233], v[84:87]
	v_mfma_f32_16x16x32_bf16 v[68:71], v[198:201], v[238:241], v[68:71]
	v_mfma_f32_16x16x32_bf16 v[64:67], v[206:209], v[238:241], v[64:67]
	v_mfma_f32_16x16x32_bf16 v[80:83], v[206:209], v[230:233], v[80:83]
	v_mfma_f32_16x16x32_bf16 v[96:99], v[206:209], v[222:225], v[96:99]
	v_mfma_f32_16x16x32_bf16 v[112:115], v[206:209], v[214:217], v[112:115]
	s_setprio 0
	s_barrier
	s_add_i32 s95, s84, s3
	v_lshl_add_u64 v[150:151], s[60:61], 0, v[130:131]
	s_mov_b32 m0, s95
	ds_read_b128 v[210:213], v164 offset:16384
	ds_read_b128 v[214:217], v164 offset:17408
	ds_read_b128 v[218:221], v164 offset:18432
	ds_read_b128 v[222:225], v164 offset:19456
	ds_read_b128 v[226:229], v164 offset:20480
	ds_read_b128 v[230:233], v164 offset:21504
	ds_read_b128 v[234:237], v164 offset:22528
	ds_read_b128 v[238:241], v164 offset:23552
	global_load_lds_dwordx4 v[150:151], off
	s_add_i32 m0, s95, 0x2000
	s_add_u32 s96, s60, 0x80000
	v_lshl_add_u64 v[180:181], s[60:61], 0, v[134:135]
	s_addc_u32 s97, s61, 0
	s_add_i32 s95, s85, s3
	global_load_lds_dwordx4 v[180:181], off
	v_lshl_add_u64 v[188:189], s[96:97], 0, v[130:131]
	s_mov_b32 m0, s95
	v_lshl_add_u64 v[242:243], s[62:63], 0, v[132:133]
	global_load_lds_dwordx4 v[188:189], off
	v_lshl_add_u64 v[188:189], s[96:97], 0, v[134:135]
	s_add_i32 m0, s95, 0x2000
	s_nop 0
	global_load_lds_dwordx4 v[188:189], off
	v_lshl_add_u64 v[188:189], s[62:63], 0, v[128:129]
	s_mov_b32 m0, s28
	s_nop 0
	global_load_lds_dwordx4 v[188:189], off
	s_mov_b32 m0, s29
	s_nop 0
	global_load_lds_dwordx4 v[242:243], off
	s_waitcnt vmcnt(8)
	s_waitcnt lgkmcnt(0)
	s_barrier
; #define PG8_STAGE(bufoff, gbase, voff) do { _Pragma("unroll") for (int _i = 0; _i < 2; ++_i) \
;         __builtin_amdgcn_global_load_lds((const unsigned*)((const char*)(gbase) + (voff)[_i]), (PG8_LAS unsigned*)(lds + (bufoff) + ldsw + _i * 8192), 16, 0, 0); } while (0)
; #define PG8_LDA(dst, b, h) do { _Pragma("unroll") for (int m = 0; m < 4; ++m) _Pragma("unroll") for (int k = 0; k < 2; ++k) dst[m][k] = *(const PG8_LAS bf16x8*)(lds + PG8_SA(b, h) + aoff + m * 2048 + k * 1024); } while (0)
; #define PG8_LDB(dst, b, h) do { _Pragma("unroll") for (int n = 0; n < 2; ++n) _Pragma("unroll") for (int k = 0; k < 2; ++k) dst[n][k] = *(const PG8_LAS bf16x8*)(lds + PG8_SB(b, h) + boff + n * 2048 + k * 1024); } while (0)
; #define PG8_MMA(ai, bj, At, Bt) do { __builtin_amdgcn_s_setprio(1); _Pragma("unroll") for (int m = 0; m < 4; ++m) _Pragma("unroll") for (int n = 0; n < 2; ++n) _Pragma("unroll") for (int k = 0; k < 2; ++k) \
;         acc[ai][bj][m][n] = __builtin_amdgcn_mfma_f32_16x16x32_bf16(Bt[n][k], At[m][k], acc[ai][bj][m][n], 0, 0, 0); __builtin_amdgcn_s_setprio(0); } while (0)
; #define PG8_WAIT_V(n) asm volatile("s_waitcnt vmcnt(" #n ")" ::: "memory")
; #define PG8_WAIT_L(n) asm volatile("s_waitcnt lgkmcnt(" #n ")" ::: "memory")
; #define PG8_BAR __builtin_amdgcn_s_barrier()
; #define PG8_SCHED __builtin_amdgcn_sched_barrier(0)
; template <class Epi, class Sched, bool ALIGN_EPI = false, bool SP2 = false>
; __device__ __forceinline__ void gemm_phase(PG8_LAS unsigned char* lds, const Gemm g, const Sched& S, const Epi& E) {
;     ...
;             PG8_WAIT_V(8); PG8_WAIT_L(0); PG8_BAR; PG8_MMA(1, 0, At, B0); PG8_MMA(1, 1, At, B1); PG8_BAR; PG8_SCHED;
;             PG8_LDB(B0, 1, 0); PG8_LDB(B1, 1, 1); PG8_SCHED; PG8_LDA(At, 1, 0); PG8_STAGE(PG8_SA(0, 1), a2 + hstep, voffA);
;             PG8_WAIT_V(8); PG8_WAIT_L(0); PG8_BAR; PG8_MMA(0, 0, At, B0); PG8_MMA(0, 1, At, B1); PG8_BAR; PG8_SCHED;
;             PG8_LDA(At, 1, 1); PG8_STAGE(PG8_SB(1, 0), b3, voffB); PG8_STAGE(PG8_SB(1, 1), b3 + hstep, voffB); PG8_STAGE(PG8_SA(1, 0), a3, voffA);
	s_setprio 1
	s_waitcnt lgkmcnt(0)
	v_mfma_f32_16x16x32_bf16 v[60:63], v[146:149], v[210:213], v[60:63]
	v_mfma_f32_16x16x32_bf16 v[44:47], v[146:149], v[218:221], v[44:47]
	v_mfma_f32_16x16x32_bf16 v[28:31], v[146:149], v[226:229], v[28:31]
	v_mfma_f32_16x16x32_bf16 v[12:15], v[146:149], v[234:237], v[12:15]
	v_mfma_f32_16x16x32_bf16 v[8:11], v[176:179], v[234:237], v[8:11]
	v_mfma_f32_16x16x32_bf16 v[24:27], v[176:179], v[226:229], v[24:27]
	v_mfma_f32_16x16x32_bf16 v[40:43], v[176:179], v[218:221], v[40:43]
	v_mfma_f32_16x16x32_bf16 v[56:59], v[176:179], v[210:213], v[56:59]
	v_mfma_f32_16x16x32_bf16 v[60:63], v[172:175], v[214:217], v[60:63]
	v_mfma_f32_16x16x32_bf16 v[44:47], v[172:175], v[222:225], v[44:47]
	v_mfma_f32_16x16x32_bf16 v[28:31], v[172:175], v[230:233], v[28:31]
	v_mfma_f32_16x16x32_bf16 v[12:15], v[172:175], v[238:241], v[12:15]
	v_mfma_f32_16x16x32_bf16 v[8:11], v[190:193], v[238:241], v[8:11]
	v_mfma_f32_16x16x32_bf16 v[24:27], v[190:193], v[230:233], v[24:27]
	v_mfma_f32_16x16x32_bf16 v[40:43], v[190:193], v[222:225], v[40:43]
	v_mfma_f32_16x16x32_bf16 v[56:59], v[190:193], v[214:217], v[56:59]
	s_setprio 0
	s_setprio 1
	v_mfma_f32_16x16x32_bf16 v[52:55], v[194:197], v[210:213], v[52:55]
	v_mfma_f32_16x16x32_bf16 v[36:39], v[194:197], v[218:221], v[36:39]
	v_mfma_f32_16x16x32_bf16 v[20:23], v[194:197], v[226:229], v[20:23]
	v_mfma_f32_16x16x32_bf16 v[4:7], v[194:197], v[234:237], v[4:7]
	v_mfma_f32_16x16x32_bf16 v[0:3], v[202:205], v[234:237], v[0:3]
	v_mfma_f32_16x16x32_bf16 v[16:19], v[202:205], v[226:229], v[16:19]
	v_mfma_f32_16x16x32_bf16 v[32:35], v[202:205], v[218:221], v[32:35]
	v_mfma_f32_16x16x32_bf16 v[48:51], v[202:205], v[210:213], v[48:51]
	v_mfma_f32_16x16x32_bf16 v[52:55], v[198:201], v[214:217], v[52:55]
	v_mfma_f32_16x16x32_bf16 v[36:39], v[198:201], v[222:225], v[36:39]
	v_mfma_f32_16x16x32_bf16 v[20:23], v[198:201], v[230:233], v[20:23]
	v_mfma_f32_16x16x32_bf16 v[4:7], v[198:201], v[238:241], v[4:7]
	v_mfma_f32_16x16x32_bf16 v[0:3], v[206:209], v[238:241], v[0:3]
	v_mfma_f32_16x16x32_bf16 v[16:19], v[206:209], v[230:233], v[16:19]
	v_mfma_f32_16x16x32_bf16 v[32:35], v[206:209], v[222:225], v[32:35]
	v_mfma_f32_16x16x32_bf16 v[48:51], v[206:209], v[214:217], v[48:51]
	s_setprio 0
	s_barrier
	s_add_i32 s95, 0, 0x18000
	v_add_u32_e32 v171, s95, v160
	s_add_i32 s96, 0, 0x1c000
	ds_read_b128 v[146:149], v171
	ds_read_b128 v[172:175], v171 offset:1024
	ds_read_b128 v[176:179], v171 offset:2048
	ds_read_b128 v[190:193], v171 offset:3072
	v_add_u32_e32 v171, s96, v160
	ds_read_b128 v[194:197], v171
	ds_read_b128 v[198:201], v171 offset:1024
	ds_read_b128 v[202:205], v171 offset:2048
	ds_read_b128 v[206:209], v171 offset:3072
	s_add_u32 s62, s62, 0x80000
	s_addc_u32 s63, s63, 0
	s_mov_b32 m0, s34
	v_lshl_add_u64 v[244:245], s[62:63], 0, v[128:129]
	ds_read_b128 v[210:213], v164 offset:32768
	ds_read_b128 v[214:217], v164 offset:33792
	ds_read_b128 v[218:221], v164 offset:34816
	ds_read_b128 v[222:225], v164 offset:35840
	ds_read_b128 v[226:229], v164 offset:36864
	ds_read_b128 v[230:233], v164 offset:37888
	ds_read_b128 v[234:237], v164 offset:38912
	ds_read_b128 v[238:241], v164 offset:39936
	global_load_lds_dwordx4 v[244:245], off
	v_lshl_add_u64 v[244:245], s[62:63], 0, v[132:133]
	s_mov_b32 m0, s35
	s_nop 0
	global_load_lds_dwordx4 v[244:245], off
	s_waitcnt vmcnt(8)
	s_waitcnt lgkmcnt(0)
	s_barrier
	s_setprio 1
	s_waitcnt lgkmcnt(0)
	v_mfma_f32_16x16x32_bf16 v[124:127], v[146:149], v[210:213], v[124:127]
	v_mfma_f32_16x16x32_bf16 v[108:111], v[146:149], v[218:221], v[108:111]
	v_mfma_f32_16x16x32_bf16 v[92:95], v[146:149], v[226:229], v[92:95]
	v_mfma_f32_16x16x32_bf16 v[76:79], v[146:149], v[234:237], v[76:79]
	v_mfma_f32_16x16x32_bf16 v[72:75], v[176:179], v[234:237], v[72:75]
	v_mfma_f32_16x16x32_bf16 v[88:91], v[176:179], v[226:229], v[88:91]
	v_mfma_f32_16x16x32_bf16 v[104:107], v[176:179], v[218:221], v[104:107]
	v_mfma_f32_16x16x32_bf16 v[120:123], v[176:179], v[210:213], v[120:123]
	v_mfma_f32_16x16x32_bf16 v[124:127], v[172:175], v[214:217], v[124:127]
	v_mfma_f32_16x16x32_bf16 v[108:111], v[172:175], v[222:225], v[108:111]
	v_mfma_f32_16x16x32_bf16 v[92:95], v[172:175], v[230:233], v[92:95]
	v_mfma_f32_16x16x32_bf16 v[76:79], v[172:175], v[238:241], v[76:79]
	v_mfma_f32_16x16x32_bf16 v[72:75], v[190:193], v[238:241], v[72:75]
	v_mfma_f32_16x16x32_bf16 v[88:91], v[190:193], v[230:233], v[88:91]
	v_mfma_f32_16x16x32_bf16 v[104:107], v[190:193], v[222:225], v[104:107]
	v_mfma_f32_16x16x32_bf16 v[120:123], v[190:193], v[214:217], v[120:123]
	s_setprio 0
	s_setprio 1
	v_mfma_f32_16x16x32_bf16 v[116:119], v[194:197], v[210:213], v[116:119]
	v_mfma_f32_16x16x32_bf16 v[100:103], v[194:197], v[218:221], v[100:103]
	v_mfma_f32_16x16x32_bf16 v[84:87], v[194:197], v[226:229], v[84:87]
	v_mfma_f32_16x16x32_bf16 v[68:71], v[194:197], v[234:237], v[68:71]
	v_mfma_f32_16x16x32_bf16 v[64:67], v[202:205], v[234:237], v[64:67]
	v_mfma_f32_16x16x32_bf16 v[80:83], v[202:205], v[226:229], v[80:83]
	v_mfma_f32_16x16x32_bf16 v[96:99], v[202:205], v[218:221], v[96:99]
	v_mfma_f32_16x16x32_bf16 v[112:115], v[202:205], v[210:213], v[112:115]
	v_mfma_f32_16x16x32_bf16 v[116:119], v[198:201], v[214:217], v[116:119]
	v_mfma_f32_16x16x32_bf16 v[100:103], v[198:201], v[222:225], v[100:103]
	v_mfma_f32_16x16x32_bf16 v[84:87], v[198:201], v[230:233], v[84:87]
	v_mfma_f32_16x16x32_bf16 v[68:71], v[198:201], v[238:241], v[68:71]
	v_mfma_f32_16x16x32_bf16 v[64:67], v[206:209], v[238:241], v[64:67]
	v_mfma_f32_16x16x32_bf16 v[80:83], v[206:209], v[230:233], v[80:83]
	v_mfma_f32_16x16x32_bf16 v[96:99], v[206:209], v[222:225], v[96:99]
	v_mfma_f32_16x16x32_bf16 v[112:115], v[206:209], v[214:217], v[112:115]
	s_setprio 0
	s_barrier
; #define PG8_STAGE(bufoff, gbase, voff) do { _Pragma("unroll") for (int _i = 0; _i < 2; ++_i) \
;         __builtin_amdgcn_global_load_lds((const unsigned*)((const char*)(gbase) + (voff)[_i]), (PG8_LAS unsigned*)(lds + (bufoff) + ldsw + _i * 8192), 16, 0, 0); } while (0)
; #define PG8_LDA(dst, b, h) do { _Pragma("unroll") for (int m = 0; m < 4; ++m) _Pragma("unroll") for (int k = 0; k < 2; ++k) dst[m][k] = *(const PG8_LAS bf16x8*)(lds + PG8_SA(b, h) + aoff + m * 2048 + k * 1024); } while (0)
; #define PG8_WAIT_V(n) asm volatile("s_waitcnt vmcnt(" #n ")" ::: "memory")
; template <class Epi, class Sched, bool ALIGN_EPI = false, bool SP2 = false>
; __device__ __forceinline__ void gemm_phase(PG8_LAS unsigned char* lds, const Gemm g, const Sched& S, const Epi& E) {
;     ...
;             PG8_LDA(At, 1, 1); PG8_STAGE(PG8_SB(1, 0), b3, voffB); PG8_STAGE(PG8_SB(1, 1), b3 + hstep, voffB); PG8_STAGE(PG8_SA(1, 0), a3, voffA);
;             PG8_WAIT_V(8); PG8_WAIT_L(0); PG8_BAR; PG8_MMA(1, 0, At, B0); PG8_MMA(1, 1, At, B1); PG8_BAR; PG8_SCHED;
;             } else {
;             PG8_LDB(B0, 0, 0); PG8_SCHED; PG8_LDA(At, 0, 0); PG8_STAGE(PG8_SA(1, 1), a1 + hstep, voffA);
;             PG8_WAIT_L(8); PG8_BAR; PG8_WAIT_L(0); PG8_MMA(0, 0, At, B0); PG8_BAR; PG8_SCHED;
;             PG8_LDB(B1, 0, 1); PG8_STAGE(PG8_SB(0, 0), b2, voffB);
;             PG8_BAR; PG8_WAIT_L(0); PG8_MMA(0, 1, At, B1); PG8_BAR;
;             PG8_LDA(At, 0, 1); PG8_STAGE(PG8_SA(0, 0), a2, voffA);
;             PG8_BAR; PG8_WAIT_L(0); PG8_MMA(1, 0, At, B0); PG8_BAR; PG8_SCHED;
;             PG8_STAGE(PG8_SB(0, 1), b2 + hstep, voffB);
;             PG8_WAIT_V(6); PG8_BAR; PG8_MMA(1, 1, At, B1); PG8_BAR;
;             PG8_LDB(B0, 1, 0); PG8_SCHED; PG8_LDA(At, 1, 0); PG8_STAGE(PG8_SA(0, 1), a2 + hstep, voffA);
;             PG8_WAIT_L(8); PG8_BAR; PG8_WAIT_L(0); PG8_MMA(0, 0, At, B0); PG8_BAR; PG8_SCHED;
;             PG8_LDB(B1, 1, 1); PG8_STAGE(PG8_SB(1, 0), b3, voffB);
;             PG8_BAR; PG8_WAIT_L(0); PG8_MMA(0, 1, At, B1); PG8_BAR;
;             PG8_LDA(At, 1, 1); PG8_STAGE(PG8_SA(1, 0), a3, voffA);
;             PG8_BAR; PG8_WAIT_L(0); PG8_MMA(1, 0, At, B0); PG8_BAR; PG8_SCHED;
;             PG8_STAGE(PG8_SB(1, 1), b3 + hstep, voffB);
;             PG8_WAIT_V(6); PG8_BAR; PG8_MMA(1, 1, At, B1); PG8_BAR;
;             }
;         }
;         if constexpr (ALIGN_EPI) { if (wr == 0) PG8_BAR; }
	s_add_i32 s62, s95, s3
	v_lshl_add_u64 v[150:151], v[150:151], 0, s[36:37]
	s_mov_b32 m0, s62
	ds_read_b128 v[210:213], v164 offset:49152
	ds_read_b128 v[214:217], v164 offset:50176
	ds_read_b128 v[218:221], v164 offset:51200
	ds_read_b128 v[222:225], v164 offset:52224
	ds_read_b128 v[226:229], v164 offset:53248
	ds_read_b128 v[230:233], v164 offset:54272
	ds_read_b128 v[234:237], v164 offset:55296
	ds_read_b128 v[238:241], v164 offset:56320
	global_load_lds_dwordx4 v[150:151], off
	s_add_i32 m0, s62, 0x2000
	s_add_u32 s60, s60, 0x80080
	v_lshl_add_u64 v[150:151], v[180:181], 0, s[36:37]
	s_addc_u32 s61, s61, 0
	s_add_i32 s62, s96, s3
	global_load_lds_dwordx4 v[150:151], off
	v_lshl_add_u64 v[150:151], s[60:61], 0, v[130:131]
	s_mov_b32 m0, s62
	s_nop 0
	global_load_lds_dwordx4 v[150:151], off
	v_lshl_add_u64 v[150:151], s[60:61], 0, v[134:135]
	s_add_i32 m0, s62, 0x2000
	s_nop 0
	global_load_lds_dwordx4 v[150:151], off
	v_lshl_add_u64 v[150:151], v[188:189], 0, s[36:37]
	s_mov_b32 m0, s65
	s_nop 0
	global_load_lds_dwordx4 v[150:151], off
	v_lshl_add_u64 v[150:151], v[242:243], 0, s[36:37]
	s_mov_b32 m0, s66
	s_nop 0
	global_load_lds_dwordx4 v[150:151], off
	s_waitcnt vmcnt(8)
	s_waitcnt lgkmcnt(0)
	s_barrier
	s_setprio 1
	s_waitcnt lgkmcnt(0)
	v_mfma_f32_16x16x32_bf16 v[60:63], v[146:149], v[210:213], v[60:63]
	v_mfma_f32_16x16x32_bf16 v[44:47], v[146:149], v[218:221], v[44:47]
	v_mfma_f32_16x16x32_bf16 v[28:31], v[146:149], v[226:229], v[28:31]
	v_mfma_f32_16x16x32_bf16 v[12:15], v[146:149], v[234:237], v[12:15]
	v_mfma_f32_16x16x32_bf16 v[8:11], v[176:179], v[234:237], v[8:11]
	v_mfma_f32_16x16x32_bf16 v[24:27], v[176:179], v[226:229], v[24:27]
	v_mfma_f32_16x16x32_bf16 v[40:43], v[176:179], v[218:221], v[40:43]
	v_mfma_f32_16x16x32_bf16 v[56:59], v[176:179], v[210:213], v[56:59]
	v_mfma_f32_16x16x32_bf16 v[60:63], v[172:175], v[214:217], v[60:63]
	v_mfma_f32_16x16x32_bf16 v[44:47], v[172:175], v[222:225], v[44:47]
	v_mfma_f32_16x16x32_bf16 v[28:31], v[172:175], v[230:233], v[28:31]
	v_mfma_f32_16x16x32_bf16 v[12:15], v[172:175], v[238:241], v[12:15]
	v_mfma_f32_16x16x32_bf16 v[8:11], v[190:193], v[238:241], v[8:11]
	v_mfma_f32_16x16x32_bf16 v[24:27], v[190:193], v[230:233], v[24:27]
	v_mfma_f32_16x16x32_bf16 v[40:43], v[190:193], v[222:225], v[40:43]
	v_mfma_f32_16x16x32_bf16 v[56:59], v[190:193], v[214:217], v[56:59]
	s_setprio 0
	s_setprio 1
	v_mfma_f32_16x16x32_bf16 v[52:55], v[194:197], v[210:213], v[52:55]
	v_mfma_f32_16x16x32_bf16 v[36:39], v[194:197], v[218:221], v[36:39]
	v_mfma_f32_16x16x32_bf16 v[20:23], v[194:197], v[226:229], v[20:23]
	v_mfma_f32_16x16x32_bf16 v[4:7], v[194:197], v[234:237], v[4:7]
	v_mfma_f32_16x16x32_bf16 v[0:3], v[202:205], v[234:237], v[0:3]
	v_mfma_f32_16x16x32_bf16 v[16:19], v[202:205], v[226:229], v[16:19]
	v_mfma_f32_16x16x32_bf16 v[32:35], v[202:205], v[218:221], v[32:35]
	v_mfma_f32_16x16x32_bf16 v[48:51], v[202:205], v[210:213], v[48:51]
	v_mfma_f32_16x16x32_bf16 v[52:55], v[198:201], v[214:217], v[52:55]
	v_mfma_f32_16x16x32_bf16 v[36:39], v[198:201], v[222:225], v[36:39]
	v_mfma_f32_16x16x32_bf16 v[20:23], v[198:201], v[230:233], v[20:23]
	v_mfma_f32_16x16x32_bf16 v[4:7], v[198:201], v[238:241], v[4:7]
	v_mfma_f32_16x16x32_bf16 v[0:3], v[206:209], v[238:241], v[0:3]
	v_mfma_f32_16x16x32_bf16 v[16:19], v[206:209], v[230:233], v[16:19]
	v_mfma_f32_16x16x32_bf16 v[32:35], v[206:209], v[222:225], v[32:35]
	v_mfma_f32_16x16x32_bf16 v[48:51], v[206:209], v[214:217], v[48:51]
	s_setprio 0
	s_barrier
	s_add_i32 s94, s94, 2
	s_add_u32 s58, s58, 0x100
	s_addc_u32 s59, s59, 0
	s_add_u32 s92, s92, 0x100
	s_addc_u32 s93, s93, 0
	s_cmp_gt_u32 s94, 29
	s_cbranch_scc0 .LBB0_199
	s_and_b64 vcc, exec, s[38:39]
	s_cbranch_vccz .LBB0_202
	s_barrier

; #define PG8_STAGE(bufoff, gbase, voff) do { _Pragma("unroll") for (int _i = 0; _i < 2; ++_i) \
;         __builtin_amdgcn_global_load_lds((const unsigned*)((const char*)(gbase) + (voff)[_i]), (PG8_LAS unsigned*)(lds + (bufoff) + ldsw + _i * 8192), 16, 0, 0); } while (0)
; #define PG8_LDA(dst, b, h) do { _Pragma("unroll") for (int m = 0; m < 4; ++m) _Pragma("unroll") for (int k = 0; k < 2; ++k) dst[m][k] = *(const PG8_LAS bf16x8*)(lds + PG8_SA(b, h) + aoff + m * 2048 + k * 1024); } while (0)
; #define PG8_LDB(dst, b, h) do { _Pragma("unroll") for (int n = 0; n < 2; ++n) _Pragma("unroll") for (int k = 0; k < 2; ++k) dst[n][k] = *(const PG8_LAS bf16x8*)(lds + PG8_SB(b, h) + boff + n * 2048 + k * 1024); } while (0)
; #define PG8_MMA(ai, bj, At, Bt) do { __builtin_amdgcn_s_setprio(1); _Pragma("unroll") for (int m = 0; m < 4; ++m) _Pragma("unroll") for (int n = 0; n < 2; ++n) _Pragma("unroll") for (int k = 0; k < 2; ++k) \
;         acc[ai][bj][m][n] = __builtin_amdgcn_mfma_f32_16x16x32_bf16(Bt[n][k], At[m][k], acc[ai][bj][m][n], 0, 0, 0); __builtin_amdgcn_s_setprio(0); } while (0)
; #define PG8_WAIT_V(n) asm volatile("s_waitcnt vmcnt(" #n ")" ::: "memory")
; #define PG8_WAIT_L(n) asm volatile("s_waitcnt lgkmcnt(" #n ")" ::: "memory")
; #define PG8_BAR __builtin_amdgcn_s_barrier()
; #define PG8_SCHED __builtin_amdgcn_sched_barrier(0)
; template <class Epi, class Sched, bool ALIGN_EPI = false, bool SP2 = false>
; __device__ __forceinline__ void gemm_phase(PG8_LAS unsigned char* lds, const Gemm g, const Sched& S, const Epi& E) {
;     ...
;             const bool last = (t == nt - 2);
;             const char* a1 = cA + (size_t)(t + 1) * kstep;
;             const char* a2 = last ? nA : cA + (size_t)(t + 2) * kstep; const char* b2 = last ? nB : cB + (size_t)(t + 2) * kstep;
;             const char* a3 = a2 + kstep; const char* b3 = b2 + kstep;
;             if (last && has_next) S.a_ready(nxt);
;             if constexpr (SP2) {
;             PG8_LDB(B0, 0, 0); PG8_LDB(B1, 0, 1); PG8_SCHED; PG8_LDA(At, 0, 0); PG8_STAGE(PG8_SA(1, 1), a1 + hstep, voffA);
;             PG8_WAIT_V(8); PG8_WAIT_L(0); PG8_BAR; PG8_MMA(0, 0, At, B0); PG8_MMA(0, 1, At, B1); PG8_BAR; PG8_SCHED;
;             PG8_LDA(At, 0, 1); PG8_STAGE(PG8_SB(0, 0), b2, voffB); PG8_STAGE(PG8_SB(0, 1), b2 + hstep, voffB); PG8_STAGE(PG8_SA(0, 0), a2, voffA);
.LBB0_251:
	ds_read_b128 v[146:149], v152
	ds_read_b128 v[156:159], v152 offset:1024
	ds_read_b128 v[160:163], v152 offset:2048
	ds_read_b128 v[164:167], v152 offset:3072
	ds_read_b128 v[168:171], v154
	ds_read_b128 v[172:175], v154 offset:1024
	ds_read_b128 v[176:179], v154 offset:2048
	ds_read_b128 v[190:193], v154 offset:3072
	s_add_u32 s46, s44, 0xfff80080
	s_addc_u32 s47, s45, -1
	s_cmp_eq_u32 s82, 28
	s_cselect_b32 s49, s37, s47
	s_cselect_b32 s48, s77, s46
	s_cselect_b32 s47, s13, s81
	s_cselect_b32 s46, s79, s80
	v_lshl_add_u64 v[180:181], s[44:45], 0, v[136:137]
	s_add_i32 m0, s35, 0xc000
	ds_read_b128 v[194:197], v155
	ds_read_b128 v[198:201], v155 offset:1024
	ds_read_b128 v[202:205], v155 offset:2048
	ds_read_b128 v[206:209], v155 offset:3072
	ds_read_b128 v[210:213], v155 offset:4096
	ds_read_b128 v[214:217], v155 offset:5120
	ds_read_b128 v[218:221], v155 offset:6144
	ds_read_b128 v[222:225], v155 offset:7168
	global_load_lds_dwordx4 v[180:181], off
	v_lshl_add_u64 v[180:181], s[44:45], 0, v[138:139]
	s_add_i32 m0, s35, 0xe000
	s_nop 0
	global_load_lds_dwordx4 v[180:181], off
	s_waitcnt vmcnt(8)
	s_waitcnt lgkmcnt(0)
	s_barrier
	s_setprio 1
	s_waitcnt lgkmcnt(0)
	v_mfma_f32_16x16x32_bf16 v[124:127], v[146:149], v[194:197], v[124:127]
	v_mfma_f32_16x16x32_bf16 v[116:119], v[146:149], v[202:205], v[116:119]
	v_mfma_f32_16x16x32_bf16 v[100:103], v[146:149], v[210:213], v[100:103]
	v_mfma_f32_16x16x32_bf16 v[84:87], v[146:149], v[218:221], v[84:87]
	v_mfma_f32_16x16x32_bf16 v[76:79], v[160:163], v[218:221], v[76:79]
	v_mfma_f32_16x16x32_bf16 v[92:95], v[160:163], v[210:213], v[92:95]
	v_mfma_f32_16x16x32_bf16 v[108:111], v[160:163], v[202:205], v[108:111]
	v_mfma_f32_16x16x32_bf16 v[120:123], v[160:163], v[194:197], v[120:123]
	v_mfma_f32_16x16x32_bf16 v[124:127], v[156:159], v[198:201], v[124:127]
	v_mfma_f32_16x16x32_bf16 v[116:119], v[156:159], v[206:209], v[116:119]
	v_mfma_f32_16x16x32_bf16 v[100:103], v[156:159], v[214:217], v[100:103]
	v_mfma_f32_16x16x32_bf16 v[84:87], v[156:159], v[222:225], v[84:87]
	v_mfma_f32_16x16x32_bf16 v[76:79], v[164:167], v[222:225], v[76:79]
	v_mfma_f32_16x16x32_bf16 v[92:95], v[164:167], v[214:217], v[92:95]
	v_mfma_f32_16x16x32_bf16 v[108:111], v[164:167], v[206:209], v[108:111]
	v_mfma_f32_16x16x32_bf16 v[120:123], v[164:167], v[198:201], v[120:123]
	s_setprio 0
	s_setprio 1
	v_mfma_f32_16x16x32_bf16 v[112:115], v[168:171], v[194:197], v[112:115]
	v_mfma_f32_16x16x32_bf16 v[96:99], v[168:171], v[202:205], v[96:99]
	v_mfma_f32_16x16x32_bf16 v[80:83], v[168:171], v[210:213], v[80:83]
	v_mfma_f32_16x16x32_bf16 v[68:71], v[168:171], v[218:221], v[68:71]
	v_mfma_f32_16x16x32_bf16 v[64:67], v[176:179], v[218:221], v[64:67]
	v_mfma_f32_16x16x32_bf16 v[72:75], v[176:179], v[210:213], v[72:75]
	v_mfma_f32_16x16x32_bf16 v[88:91], v[176:179], v[202:205], v[88:91]
	v_mfma_f32_16x16x32_bf16 v[104:107], v[176:179], v[194:197], v[104:107]
	v_mfma_f32_16x16x32_bf16 v[112:115], v[172:175], v[198:201], v[112:115]
	v_mfma_f32_16x16x32_bf16 v[96:99], v[172:175], v[206:209], v[96:99]
	v_mfma_f32_16x16x32_bf16 v[80:83], v[172:175], v[214:217], v[80:83]
	v_mfma_f32_16x16x32_bf16 v[68:71], v[172:175], v[222:225], v[68:71]
	v_mfma_f32_16x16x32_bf16 v[64:67], v[190:193], v[222:225], v[64:67]
	v_mfma_f32_16x16x32_bf16 v[72:75], v[190:193], v[214:217], v[72:75]
	v_mfma_f32_16x16x32_bf16 v[88:91], v[190:193], v[206:209], v[88:91]
	v_mfma_f32_16x16x32_bf16 v[104:107], v[190:193], v[198:201], v[104:107]
	s_setprio 0
	s_barrier
	s_add_i32 s83, s65, s29
	v_lshl_add_u64 v[180:181], s[46:47], 0, v[130:131]
	s_mov_b32 m0, s83
	ds_read_b128 v[194:197], v155 offset:16384
	ds_read_b128 v[198:201], v155 offset:17408
	ds_read_b128 v[202:205], v155 offset:18432
	ds_read_b128 v[206:209], v155 offset:19456
	ds_read_b128 v[210:213], v155 offset:20480
	ds_read_b128 v[214:217], v155 offset:21504
	ds_read_b128 v[218:221], v155 offset:22528
	ds_read_b128 v[222:225], v155 offset:23552
	global_load_lds_dwordx4 v[180:181], off
	s_add_i32 m0, s83, 0x2000
	s_add_u32 s84, s46, 0x80000
	v_lshl_add_u64 v[188:189], s[46:47], 0, v[134:135]
	s_addc_u32 s85, s47, 0
	s_add_i32 s83, s66, s29
	global_load_lds_dwordx4 v[188:189], off
	v_lshl_add_u64 v[226:227], s[84:85], 0, v[130:131]
	s_mov_b32 m0, s83
	v_lshl_add_u64 v[228:229], s[48:49], 0, v[132:133]
	global_load_lds_dwordx4 v[226:227], off
	v_lshl_add_u64 v[226:227], s[84:85], 0, v[134:135]
	s_add_i32 m0, s83, 0x2000
	s_nop 0
	global_load_lds_dwordx4 v[226:227], off
	v_lshl_add_u64 v[226:227], s[48:49], 0, v[128:129]
	s_mov_b32 m0, s35
	s_nop 0
	global_load_lds_dwordx4 v[226:227], off
	s_mov_b32 m0, s43
	s_nop 0
	global_load_lds_dwordx4 v[228:229], off
	s_waitcnt vmcnt(8)
	s_waitcnt lgkmcnt(0)
	s_barrier
; #define PG8_STAGE(bufoff, gbase, voff) do { _Pragma("unroll") for (int _i = 0; _i < 2; ++_i) \
;         __builtin_amdgcn_global_load_lds((const unsigned*)((const char*)(gbase) + (voff)[_i]), (PG8_LAS unsigned*)(lds + (bufoff) + ldsw + _i * 8192), 16, 0, 0); } while (0)
; #define PG8_LDA(dst, b, h) do { _Pragma("unroll") for (int m = 0; m < 4; ++m) _Pragma("unroll") for (int k = 0; k < 2; ++k) dst[m][k] = *(const PG8_LAS bf16x8*)(lds + PG8_SA(b, h) + aoff + m * 2048 + k * 1024); } while (0)
; #define PG8_LDB(dst, b, h) do { _Pragma("unroll") for (int n = 0; n < 2; ++n) _Pragma("unroll") for (int k = 0; k < 2; ++k) dst[n][k] = *(const PG8_LAS bf16x8*)(lds + PG8_SB(b, h) + boff + n * 2048 + k * 1024); } while (0)
; #define PG8_MMA(ai, bj, At, Bt) do { __builtin_amdgcn_s_setprio(1); _Pragma("unroll") for (int m = 0; m < 4; ++m) _Pragma("unroll") for (int n = 0; n < 2; ++n) _Pragma("unroll") for (int k = 0; k < 2; ++k) \
;         acc[ai][bj][m][n] = __builtin_amdgcn_mfma_f32_16x16x32_bf16(Bt[n][k], At[m][k], acc[ai][bj][m][n], 0, 0, 0); __builtin_amdgcn_s_setprio(0); } while (0)
; #define PG8_WAIT_V(n) asm volatile("s_waitcnt vmcnt(" #n ")" ::: "memory")
; #define PG8_WAIT_L(n) asm volatile("s_waitcnt lgkmcnt(" #n ")" ::: "memory")
; #define PG8_BAR __builtin_amdgcn_s_barrier()
; #define PG8_SCHED __builtin_amdgcn_sched_barrier(0)
; template <class Epi, class Sched, bool ALIGN_EPI = false, bool SP2 = false>
; __device__ __forceinline__ void gemm_phase(PG8_LAS unsigned char* lds, const Gemm g, const Sched& S, const Epi& E) {
;     ...
;             PG8_WAIT_V(8); PG8_WAIT_L(0); PG8_BAR; PG8_MMA(1, 0, At, B0); PG8_MMA(1, 1, At, B1); PG8_BAR; PG8_SCHED;
;             PG8_LDB(B0, 1, 0); PG8_LDB(B1, 1, 1); PG8_SCHED; PG8_LDA(At, 1, 0); PG8_STAGE(PG8_SA(0, 1), a2 + hstep, voffA);
;             PG8_WAIT_V(8); PG8_WAIT_L(0); PG8_BAR; PG8_MMA(0, 0, At, B0); PG8_MMA(0, 1, At, B1); PG8_BAR; PG8_SCHED;
;             PG8_LDA(At, 1, 1); PG8_STAGE(PG8_SB(1, 0), b3, voffB); PG8_STAGE(PG8_SB(1, 1), b3 + hstep, voffB); PG8_STAGE(PG8_SA(1, 0), a3, voffA);
	s_setprio 1
	s_waitcnt lgkmcnt(0)
	v_mfma_f32_16x16x32_bf16 v[60:63], v[146:149], v[194:197], v[60:63]
	v_mfma_f32_16x16x32_bf16 v[52:55], v[146:149], v[202:205], v[52:55]
	v_mfma_f32_16x16x32_bf16 v[36:39], v[146:149], v[210:213], v[36:39]
	v_mfma_f32_16x16x32_bf16 v[20:23], v[146:149], v[218:221], v[20:23]
	v_mfma_f32_16x16x32_bf16 v[12:15], v[160:163], v[218:221], v[12:15]
	v_mfma_f32_16x16x32_bf16 v[28:31], v[160:163], v[210:213], v[28:31]
	v_mfma_f32_16x16x32_bf16 v[44:47], v[160:163], v[202:205], v[44:47]
	v_mfma_f32_16x16x32_bf16 v[56:59], v[160:163], v[194:197], v[56:59]
	v_mfma_f32_16x16x32_bf16 v[60:63], v[156:159], v[198:201], v[60:63]
	v_mfma_f32_16x16x32_bf16 v[52:55], v[156:159], v[206:209], v[52:55]
	v_mfma_f32_16x16x32_bf16 v[36:39], v[156:159], v[214:217], v[36:39]
	v_mfma_f32_16x16x32_bf16 v[20:23], v[156:159], v[222:225], v[20:23]
	v_mfma_f32_16x16x32_bf16 v[12:15], v[164:167], v[222:225], v[12:15]
	v_mfma_f32_16x16x32_bf16 v[28:31], v[164:167], v[214:217], v[28:31]
	v_mfma_f32_16x16x32_bf16 v[44:47], v[164:167], v[206:209], v[44:47]
	v_mfma_f32_16x16x32_bf16 v[56:59], v[164:167], v[198:201], v[56:59]
	s_setprio 0
	s_setprio 1
	v_mfma_f32_16x16x32_bf16 v[48:51], v[168:171], v[194:197], v[48:51]
	v_mfma_f32_16x16x32_bf16 v[32:35], v[168:171], v[202:205], v[32:35]
	v_mfma_f32_16x16x32_bf16 v[16:19], v[168:171], v[210:213], v[16:19]
	v_mfma_f32_16x16x32_bf16 v[4:7], v[168:171], v[218:221], v[4:7]
	v_mfma_f32_16x16x32_bf16 v[0:3], v[176:179], v[218:221], v[0:3]
	v_mfma_f32_16x16x32_bf16 v[8:11], v[176:179], v[210:213], v[8:11]
	v_mfma_f32_16x16x32_bf16 v[24:27], v[176:179], v[202:205], v[24:27]
	v_mfma_f32_16x16x32_bf16 v[40:43], v[176:179], v[194:197], v[40:43]
	v_mfma_f32_16x16x32_bf16 v[48:51], v[172:175], v[198:201], v[48:51]
	v_mfma_f32_16x16x32_bf16 v[32:35], v[172:175], v[206:209], v[32:35]
	v_mfma_f32_16x16x32_bf16 v[16:19], v[172:175], v[214:217], v[16:19]
	v_mfma_f32_16x16x32_bf16 v[4:7], v[172:175], v[222:225], v[4:7]
	v_mfma_f32_16x16x32_bf16 v[0:3], v[190:193], v[222:225], v[0:3]
	v_mfma_f32_16x16x32_bf16 v[8:11], v[190:193], v[214:217], v[8:11]
	v_mfma_f32_16x16x32_bf16 v[24:27], v[190:193], v[206:209], v[24:27]
	v_mfma_f32_16x16x32_bf16 v[40:43], v[190:193], v[198:201], v[40:43]
	s_setprio 0
	s_barrier
	s_add_i32 s83, 0, 0x18000
	s_add_i32 s84, 0, 0x1c000
	v_add_u32_e32 v164, s83, v151
	v_add_u32_e32 v190, s84, v151
	ds_read_b128 v[146:149], v164
	ds_read_b128 v[156:159], v164 offset:1024
	ds_read_b128 v[160:163], v164 offset:2048
	ds_read_b128 v[164:167], v164 offset:3072
	ds_read_b128 v[168:171], v190
	ds_read_b128 v[172:175], v190 offset:1024
	ds_read_b128 v[176:179], v190 offset:2048
	ds_read_b128 v[190:193], v190 offset:3072
	s_add_u32 s48, s48, 0x80000
	s_addc_u32 s49, s49, 0
	s_mov_b32 m0, s58
	v_lshl_add_u64 v[230:231], s[48:49], 0, v[128:129]
	ds_read_b128 v[194:197], v155 offset:32768
	ds_read_b128 v[198:201], v155 offset:33792
	ds_read_b128 v[202:205], v155 offset:34816
	ds_read_b128 v[206:209], v155 offset:35840
	ds_read_b128 v[210:213], v155 offset:36864
	ds_read_b128 v[214:217], v155 offset:37888
	ds_read_b128 v[218:221], v155 offset:38912
	ds_read_b128 v[222:225], v155 offset:39936
	global_load_lds_dwordx4 v[230:231], off
	v_lshl_add_u64 v[230:231], s[48:49], 0, v[132:133]
	s_mov_b32 m0, s59
	s_nop 0
	global_load_lds_dwordx4 v[230:231], off
	s_waitcnt vmcnt(8)
	s_waitcnt lgkmcnt(0)
	s_barrier
	s_setprio 1
	s_waitcnt lgkmcnt(0)
	v_mfma_f32_16x16x32_bf16 v[124:127], v[146:149], v[194:197], v[124:127]
	v_mfma_f32_16x16x32_bf16 v[116:119], v[146:149], v[202:205], v[116:119]
	v_mfma_f32_16x16x32_bf16 v[100:103], v[146:149], v[210:213], v[100:103]
	v_mfma_f32_16x16x32_bf16 v[84:87], v[146:149], v[218:221], v[84:87]
	v_mfma_f32_16x16x32_bf16 v[76:79], v[160:163], v[218:221], v[76:79]
	v_mfma_f32_16x16x32_bf16 v[92:95], v[160:163], v[210:213], v[92:95]
	v_mfma_f32_16x16x32_bf16 v[108:111], v[160:163], v[202:205], v[108:111]
	v_mfma_f32_16x16x32_bf16 v[120:123], v[160:163], v[194:197], v[120:123]
	v_mfma_f32_16x16x32_bf16 v[124:127], v[156:159], v[198:201], v[124:127]
	v_mfma_f32_16x16x32_bf16 v[116:119], v[156:159], v[206:209], v[116:119]
	v_mfma_f32_16x16x32_bf16 v[100:103], v[156:159], v[214:217], v[100:103]
	v_mfma_f32_16x16x32_bf16 v[84:87], v[156:159], v[222:225], v[84:87]
	v_mfma_f32_16x16x32_bf16 v[76:79], v[164:167], v[222:225], v[76:79]
	v_mfma_f32_16x16x32_bf16 v[92:95], v[164:167], v[214:217], v[92:95]
	v_mfma_f32_16x16x32_bf16 v[108:111], v[164:167], v[206:209], v[108:111]
	v_mfma_f32_16x16x32_bf16 v[120:123], v[164:167], v[198:201], v[120:123]
	s_setprio 0
	s_setprio 1
	v_mfma_f32_16x16x32_bf16 v[112:115], v[168:171], v[194:197], v[112:115]
	v_mfma_f32_16x16x32_bf16 v[96:99], v[168:171], v[202:205], v[96:99]
	v_mfma_f32_16x16x32_bf16 v[80:83], v[168:171], v[210:213], v[80:83]
	v_mfma_f32_16x16x32_bf16 v[68:71], v[168:171], v[218:221], v[68:71]
	v_mfma_f32_16x16x32_bf16 v[64:67], v[176:179], v[218:221], v[64:67]
	v_mfma_f32_16x16x32_bf16 v[72:75], v[176:179], v[210:213], v[72:75]
	v_mfma_f32_16x16x32_bf16 v[88:91], v[176:179], v[202:205], v[88:91]
	v_mfma_f32_16x16x32_bf16 v[104:107], v[176:179], v[194:197], v[104:107]
	v_mfma_f32_16x16x32_bf16 v[112:115], v[172:175], v[198:201], v[112:115]
	v_mfma_f32_16x16x32_bf16 v[96:99], v[172:175], v[206:209], v[96:99]
	v_mfma_f32_16x16x32_bf16 v[80:83], v[172:175], v[214:217], v[80:83]
	v_mfma_f32_16x16x32_bf16 v[68:71], v[172:175], v[222:225], v[68:71]
	v_mfma_f32_16x16x32_bf16 v[64:67], v[190:193], v[222:225], v[64:67]
	v_mfma_f32_16x16x32_bf16 v[72:75], v[190:193], v[214:217], v[72:75]
	v_mfma_f32_16x16x32_bf16 v[88:91], v[190:193], v[206:209], v[88:91]
	v_mfma_f32_16x16x32_bf16 v[104:107], v[190:193], v[198:201], v[104:107]
	s_setprio 0
	s_barrier
; #define PG8_STAGE(bufoff, gbase, voff) do { _Pragma("unroll") for (int _i = 0; _i < 2; ++_i) \
;         __builtin_amdgcn_global_load_lds((const unsigned*)((const char*)(gbase) + (voff)[_i]), (PG8_LAS unsigned*)(lds + (bufoff) + ldsw + _i * 8192), 16, 0, 0); } while (0)
; #define PG8_LDA(dst, b, h) do { _Pragma("unroll") for (int m = 0; m < 4; ++m) _Pragma("unroll") for (int k = 0; k < 2; ++k) dst[m][k] = *(const PG8_LAS bf16x8*)(lds + PG8_SA(b, h) + aoff + m * 2048 + k * 1024); } while (0)
; #define PG8_WAIT_V(n) asm volatile("s_waitcnt vmcnt(" #n ")" ::: "memory")
; template <class Epi, class Sched, bool ALIGN_EPI = false, bool SP2 = false>
; __device__ __forceinline__ void gemm_phase(PG8_LAS unsigned char* lds, const Gemm g, const Sched& S, const Epi& E) {
;     ...
;             PG8_LDA(At, 1, 1); PG8_STAGE(PG8_SB(1, 0), b3, voffB); PG8_STAGE(PG8_SB(1, 1), b3 + hstep, voffB); PG8_STAGE(PG8_SA(1, 0), a3, voffA);
;             PG8_WAIT_V(8); PG8_WAIT_L(0); PG8_BAR; PG8_MMA(1, 0, At, B0); PG8_MMA(1, 1, At, B1); PG8_BAR; PG8_SCHED;
;             } else {
;             PG8_LDB(B0, 0, 0); PG8_SCHED; PG8_LDA(At, 0, 0); PG8_STAGE(PG8_SA(1, 1), a1 + hstep, voffA);
;             PG8_WAIT_L(8); PG8_BAR; PG8_WAIT_L(0); PG8_MMA(0, 0, At, B0); PG8_BAR; PG8_SCHED;
;             PG8_LDB(B1, 0, 1); PG8_STAGE(PG8_SB(0, 0), b2, voffB);
;             PG8_BAR; PG8_WAIT_L(0); PG8_MMA(0, 1, At, B1); PG8_BAR;
;             PG8_LDA(At, 0, 1); PG8_STAGE(PG8_SA(0, 0), a2, voffA);
;             PG8_BAR; PG8_WAIT_L(0); PG8_MMA(1, 0, At, B0); PG8_BAR; PG8_SCHED;
;             PG8_STAGE(PG8_SB(0, 1), b2 + hstep, voffB);
;             PG8_WAIT_V(6); PG8_BAR; PG8_MMA(1, 1, At, B1); PG8_BAR;
;             PG8_LDB(B0, 1, 0); PG8_SCHED; PG8_LDA(At, 1, 0); PG8_STAGE(PG8_SA(0, 1), a2 + hstep, voffA);
;             PG8_WAIT_L(8); PG8_BAR; PG8_WAIT_L(0); PG8_MMA(0, 0, At, B0); PG8_BAR; PG8_SCHED;
;             PG8_LDB(B1, 1, 1); PG8_STAGE(PG8_SB(1, 0), b3, voffB);
;             PG8_BAR; PG8_WAIT_L(0); PG8_MMA(0, 1, At, B1); PG8_BAR;
;             PG8_LDA(At, 1, 1); PG8_STAGE(PG8_SA(1, 0), a3, voffA);
;             PG8_BAR; PG8_WAIT_L(0); PG8_MMA(1, 0, At, B0); PG8_BAR; PG8_SCHED;
;             PG8_STAGE(PG8_SB(1, 1), b3 + hstep, voffB);
;             PG8_WAIT_V(6); PG8_BAR; PG8_MMA(1, 1, At, B1); PG8_BAR;
;             }
;         }
;         if constexpr (ALIGN_EPI) { if (wr == 0) PG8_BAR; }
	s_add_i32 s48, s83, s29
	v_lshl_add_u64 v[180:181], v[180:181], 0, s[6:7]
	s_mov_b32 m0, s48
	ds_read_b128 v[194:197], v155 offset:49152
	ds_read_b128 v[198:201], v155 offset:50176
	ds_read_b128 v[202:205], v155 offset:51200
	ds_read_b128 v[206:209], v155 offset:52224
	ds_read_b128 v[210:213], v155 offset:53248
	ds_read_b128 v[214:217], v155 offset:54272
	ds_read_b128 v[218:221], v155 offset:55296
	ds_read_b128 v[222:225], v155 offset:56320
	global_load_lds_dwordx4 v[180:181], off
	s_add_i32 m0, s48, 0x2000
	s_add_u32 s46, s46, 0x80080
	v_lshl_add_u64 v[180:181], v[188:189], 0, s[6:7]
	s_addc_u32 s47, s47, 0
	s_add_i32 s48, s84, s29
	global_load_lds_dwordx4 v[180:181], off
	v_lshl_add_u64 v[180:181], s[46:47], 0, v[130:131]
	s_mov_b32 m0, s48
	s_nop 0
	global_load_lds_dwordx4 v[180:181], off
	v_lshl_add_u64 v[180:181], s[46:47], 0, v[134:135]
	s_add_i32 m0, s48, 0x2000
	s_nop 0
	global_load_lds_dwordx4 v[180:181], off
	v_lshl_add_u64 v[180:181], v[226:227], 0, s[6:7]
	s_mov_b32 m0, s62
	s_nop 0
	global_load_lds_dwordx4 v[180:181], off
	v_lshl_add_u64 v[180:181], v[228:229], 0, s[6:7]
	s_mov_b32 m0, s63
	s_nop 0
	global_load_lds_dwordx4 v[180:181], off
	s_waitcnt vmcnt(8)
	s_waitcnt lgkmcnt(0)
	s_barrier
	s_setprio 1
	s_waitcnt lgkmcnt(0)
	v_mfma_f32_16x16x32_bf16 v[60:63], v[146:149], v[194:197], v[60:63]
	v_mfma_f32_16x16x32_bf16 v[52:55], v[146:149], v[202:205], v[52:55]
	v_mfma_f32_16x16x32_bf16 v[36:39], v[146:149], v[210:213], v[36:39]
	v_mfma_f32_16x16x32_bf16 v[20:23], v[146:149], v[218:221], v[20:23]
	v_mfma_f32_16x16x32_bf16 v[12:15], v[160:163], v[218:221], v[12:15]
	v_mfma_f32_16x16x32_bf16 v[28:31], v[160:163], v[210:213], v[28:31]
	v_mfma_f32_16x16x32_bf16 v[44:47], v[160:163], v[202:205], v[44:47]
	v_mfma_f32_16x16x32_bf16 v[56:59], v[160:163], v[194:197], v[56:59]
	v_mfma_f32_16x16x32_bf16 v[60:63], v[156:159], v[198:201], v[60:63]
	v_mfma_f32_16x16x32_bf16 v[52:55], v[156:159], v[206:209], v[52:55]
	v_mfma_f32_16x16x32_bf16 v[36:39], v[156:159], v[214:217], v[36:39]
	v_mfma_f32_16x16x32_bf16 v[20:23], v[156:159], v[222:225], v[20:23]
	v_mfma_f32_16x16x32_bf16 v[12:15], v[164:167], v[222:225], v[12:15]
	v_mfma_f32_16x16x32_bf16 v[28:31], v[164:167], v[214:217], v[28:31]
	v_mfma_f32_16x16x32_bf16 v[44:47], v[164:167], v[206:209], v[44:47]
	v_mfma_f32_16x16x32_bf16 v[56:59], v[164:167], v[198:201], v[56:59]
	s_setprio 0
	s_setprio 1
	v_mfma_f32_16x16x32_bf16 v[48:51], v[168:171], v[194:197], v[48:51]
	v_mfma_f32_16x16x32_bf16 v[32:35], v[168:171], v[202:205], v[32:35]
	v_mfma_f32_16x16x32_bf16 v[16:19], v[168:171], v[210:213], v[16:19]
	v_mfma_f32_16x16x32_bf16 v[4:7], v[168:171], v[218:221], v[4:7]
	v_mfma_f32_16x16x32_bf16 v[0:3], v[176:179], v[218:221], v[0:3]
	v_mfma_f32_16x16x32_bf16 v[8:11], v[176:179], v[210:213], v[8:11]
	v_mfma_f32_16x16x32_bf16 v[24:27], v[176:179], v[202:205], v[24:27]
	v_mfma_f32_16x16x32_bf16 v[40:43], v[176:179], v[194:197], v[40:43]
	v_mfma_f32_16x16x32_bf16 v[48:51], v[172:175], v[198:201], v[48:51]
	v_mfma_f32_16x16x32_bf16 v[32:35], v[172:175], v[206:209], v[32:35]
	v_mfma_f32_16x16x32_bf16 v[16:19], v[172:175], v[214:217], v[16:19]
	v_mfma_f32_16x16x32_bf16 v[4:7], v[172:175], v[222:225], v[4:7]
	v_mfma_f32_16x16x32_bf16 v[0:3], v[190:193], v[222:225], v[0:3]
	v_mfma_f32_16x16x32_bf16 v[8:11], v[190:193], v[214:217], v[8:11]
	v_mfma_f32_16x16x32_bf16 v[24:27], v[190:193], v[206:209], v[24:27]
	v_mfma_f32_16x16x32_bf16 v[40:43], v[190:193], v[198:201], v[40:43]
	s_setprio 0
	s_barrier
	s_add_i32 s82, s82, 2
	s_add_u32 s44, s44, 0x100
	s_addc_u32 s45, s45, 0
	s_add_u32 s80, s80, 0x100
	s_addc_u32 s81, s81, 0
	s_cmp_gt_u32 s82, 29
	s_cbranch_scc0 .LBB0_251
	s_and_b64 vcc, exec, s[8:9]
	s_cbranch_vccz .LBB0_254
	s_barrier

; #define PG8_STAGE(bufoff, gbase, voff) do { _Pragma("unroll") for (int _i = 0; _i < 2; ++_i) \
;         __builtin_amdgcn_global_load_lds((const unsigned*)((const char*)(gbase) + (voff)[_i]), (PG8_LAS unsigned*)(lds + (bufoff) + ldsw + _i * 8192), 16, 0, 0); } while (0)
; #define PG8_LDA(dst, b, h) do { _Pragma("unroll") for (int m = 0; m < 4; ++m) _Pragma("unroll") for (int k = 0; k < 2; ++k) dst[m][k] = *(const PG8_LAS bf16x8*)(lds + PG8_SA(b, h) + aoff + m * 2048 + k * 1024); } while (0)
; #define PG8_LDB(dst, b, h) do { _Pragma("unroll") for (int n = 0; n < 2; ++n) _Pragma("unroll") for (int k = 0; k < 2; ++k) dst[n][k] = *(const PG8_LAS bf16x8*)(lds + PG8_SB(b, h) + boff + n * 2048 + k * 1024); } while (0)
; #define PG8_MMA(ai, bj, At, Bt) do { __builtin_amdgcn_s_setprio(1); _Pragma("unroll") for (int m = 0; m < 4; ++m) _Pragma("unroll") for (int n = 0; n < 2; ++n) _Pragma("unroll") for (int k = 0; k < 2; ++k) \
;         acc[ai][bj][m][n] = __builtin_amdgcn_mfma_f32_16x16x32_bf16(Bt[n][k], At[m][k], acc[ai][bj][m][n], 0, 0, 0); __builtin_amdgcn_s_setprio(0); } while (0)
; #define PG8_WAIT_V(n) asm volatile("s_waitcnt vmcnt(" #n ")" ::: "memory")
; #define PG8_WAIT_L(n) asm volatile("s_waitcnt lgkmcnt(" #n ")" ::: "memory")
; #define PG8_BAR __builtin_amdgcn_s_barrier()
; #define PG8_SCHED __builtin_amdgcn_sched_barrier(0)
; template <class Epi, class Sched, bool ALIGN_EPI = false, bool SP2 = false>
; __device__ __forceinline__ void gemm_phase(PG8_LAS unsigned char* lds, const Gemm g, const Sched& S, const Epi& E) {
;     ...
;             const bool last = (t == nt - 2);
;             const char* a1 = cA + (size_t)(t + 1) * kstep;
;             const char* a2 = last ? nA : cA + (size_t)(t + 2) * kstep; const char* b2 = last ? nB : cB + (size_t)(t + 2) * kstep;
;             const char* a3 = a2 + kstep; const char* b3 = b2 + kstep;
;             if (last && has_next) S.a_ready(nxt);
;             if constexpr (SP2) {
;             PG8_LDB(B0, 0, 0); PG8_LDB(B1, 0, 1); PG8_SCHED; PG8_LDA(At, 0, 0); PG8_STAGE(PG8_SA(1, 1), a1 + hstep, voffA);
;             PG8_WAIT_V(8); PG8_WAIT_L(0); PG8_BAR; PG8_MMA(0, 0, At, B0); PG8_MMA(0, 1, At, B1); PG8_BAR; PG8_SCHED;
;             PG8_LDA(At, 0, 1); PG8_STAGE(PG8_SB(0, 0), b2, voffB); PG8_STAGE(PG8_SB(0, 1), b2 + hstep, voffB); PG8_STAGE(PG8_SA(0, 0), a2, voffA);
.LBB0_560:
	ds_read_b128 v[174:177], v167
	ds_read_b128 v[178:181], v167 offset:1024
	ds_read_b128 v[190:193], v167 offset:2048
	ds_read_b128 v[194:197], v167 offset:3072
	ds_read_b128 v[198:201], v168
	ds_read_b128 v[202:205], v168 offset:1024
	ds_read_b128 v[206:209], v168 offset:2048
	ds_read_b128 v[210:213], v168 offset:3072
	s_add_u32 s50, s10, 0x100
	s_addc_u32 s51, s11, 0
	s_add_u32 s52, s34, s10
	s_addc_u32 s53, s49, s11
	s_cmp_eq_u32 s67, 28
	s_cselect_b32 s54, s18, s52
	s_cselect_b32 s52, 0, s50
	s_cselect_b32 s55, s19, s53
	s_cselect_b32 s53, 0, s51
	s_add_u32 s52, s16, s52
	s_addc_u32 s53, s17, s53
	v_lshl_add_u64 v[246:247], v[142:143], 0, s[10:11]
	s_add_i32 m0, s15, 0xc000
	ds_read_b128 v[214:217], v169
	ds_read_b128 v[218:221], v169 offset:1024
	ds_read_b128 v[222:225], v169 offset:2048
	ds_read_b128 v[226:229], v169 offset:3072
	ds_read_b128 v[230:233], v169 offset:4096
	ds_read_b128 v[234:237], v169 offset:5120
	ds_read_b128 v[238:241], v169 offset:6144
	ds_read_b128 v[242:245], v169 offset:7168
	global_load_lds_dwordx4 v[246:247], off
	v_lshl_add_u64 v[246:247], v[146:147], 0, s[10:11]
	s_add_i32 m0, s15, 0xe000
	s_nop 0
	global_load_lds_dwordx4 v[246:247], off
	s_waitcnt vmcnt(8)
	s_waitcnt lgkmcnt(0)
	s_barrier
	s_setprio 1
	s_waitcnt lgkmcnt(0)
	v_mfma_f32_16x16x32_bf16 v[76:79], v[174:177], v[214:217], v[76:79]
	v_mfma_f32_16x16x32_bf16 v[92:95], v[174:177], v[222:225], v[92:95]
	v_mfma_f32_16x16x32_bf16 v[116:119], v[174:177], v[230:233], v[116:119]
	v_mfma_f32_16x16x32_bf16 v[124:127], v[174:177], v[238:241], v[124:127]
	v_mfma_f32_16x16x32_bf16 v[120:123], v[190:193], v[238:241], v[120:123]
	v_mfma_f32_16x16x32_bf16 v[112:115], v[190:193], v[230:233], v[112:115]
	v_mfma_f32_16x16x32_bf16 v[88:91], v[190:193], v[222:225], v[88:91]
	v_mfma_f32_16x16x32_bf16 v[72:75], v[190:193], v[214:217], v[72:75]
	v_mfma_f32_16x16x32_bf16 v[76:79], v[178:181], v[218:221], v[76:79]
	v_mfma_f32_16x16x32_bf16 v[92:95], v[178:181], v[226:229], v[92:95]
	v_mfma_f32_16x16x32_bf16 v[116:119], v[178:181], v[234:237], v[116:119]
	v_mfma_f32_16x16x32_bf16 v[124:127], v[178:181], v[242:245], v[124:127]
	v_mfma_f32_16x16x32_bf16 v[120:123], v[194:197], v[242:245], v[120:123]
	v_mfma_f32_16x16x32_bf16 v[112:115], v[194:197], v[234:237], v[112:115]
	v_mfma_f32_16x16x32_bf16 v[88:91], v[194:197], v[226:229], v[88:91]
	v_mfma_f32_16x16x32_bf16 v[72:75], v[194:197], v[218:221], v[72:75]
	s_setprio 0
	s_setprio 1
	v_mfma_f32_16x16x32_bf16 v[68:71], v[198:201], v[214:217], v[68:71]
	v_mfma_f32_16x16x32_bf16 v[84:87], v[198:201], v[222:225], v[84:87]
	v_mfma_f32_16x16x32_bf16 v[108:111], v[198:201], v[230:233], v[108:111]
	v_mfma_f32_16x16x32_bf16 v[104:107], v[198:201], v[238:241], v[104:107]
	v_mfma_f32_16x16x32_bf16 v[100:103], v[206:209], v[238:241], v[100:103]
	v_mfma_f32_16x16x32_bf16 v[96:99], v[206:209], v[230:233], v[96:99]
	v_mfma_f32_16x16x32_bf16 v[80:83], v[206:209], v[222:225], v[80:83]
	v_mfma_f32_16x16x32_bf16 v[64:67], v[206:209], v[214:217], v[64:67]
	v_mfma_f32_16x16x32_bf16 v[68:71], v[202:205], v[218:221], v[68:71]
	v_mfma_f32_16x16x32_bf16 v[84:87], v[202:205], v[226:229], v[84:87]
	v_mfma_f32_16x16x32_bf16 v[108:111], v[202:205], v[234:237], v[108:111]
	v_mfma_f32_16x16x32_bf16 v[104:107], v[202:205], v[242:245], v[104:107]
	v_mfma_f32_16x16x32_bf16 v[100:103], v[210:213], v[242:245], v[100:103]
	v_mfma_f32_16x16x32_bf16 v[96:99], v[210:213], v[234:237], v[96:99]
	v_mfma_f32_16x16x32_bf16 v[80:83], v[210:213], v[226:229], v[80:83]
	v_mfma_f32_16x16x32_bf16 v[64:67], v[210:213], v[218:221], v[64:67]
	s_setprio 0
	s_barrier
	s_add_i32 s10, s61, s2
	v_lshl_add_u64 v[246:247], s[52:53], 0, v[128:129]
	s_mov_b32 m0, s10
	ds_read_b128 v[214:217], v169 offset:16384
	ds_read_b128 v[218:221], v169 offset:17408
	ds_read_b128 v[222:225], v169 offset:18432
	ds_read_b128 v[226:229], v169 offset:19456
	ds_read_b128 v[230:233], v169 offset:20480
	ds_read_b128 v[234:237], v169 offset:21504
	ds_read_b128 v[238:241], v169 offset:22528
	ds_read_b128 v[242:245], v169 offset:23552
	global_load_lds_dwordx4 v[246:247], off
	s_add_i32 m0, s10, 0x2000
	s_add_u32 s10, s52, 0x80000
	v_lshl_add_u64 v[248:249], s[52:53], 0, v[130:131]
	s_addc_u32 s11, s53, 0
	s_add_i32 s76, s62, s2
	global_load_lds_dwordx4 v[248:249], off
	v_lshl_add_u64 v[250:251], s[10:11], 0, v[128:129]
	s_mov_b32 m0, s76
	v_lshl_add_u64 v[252:253], s[54:55], 0, v[130:131]
	global_load_lds_dwordx4 v[250:251], off
	v_lshl_add_u64 v[250:251], s[10:11], 0, v[130:131]
	s_add_i32 m0, s76, 0x2000
	s_nop 0
	global_load_lds_dwordx4 v[250:251], off
	v_lshl_add_u64 v[250:251], s[54:55], 0, v[128:129]
	s_mov_b32 m0, s15
	s_nop 0
	global_load_lds_dwordx4 v[250:251], off
	s_mov_b32 m0, s28
	s_nop 0
	global_load_lds_dwordx4 v[252:253], off
	s_waitcnt vmcnt(8)
	s_waitcnt lgkmcnt(0)
	s_barrier
; #define PG8_STAGE(bufoff, gbase, voff) do { _Pragma("unroll") for (int _i = 0; _i < 2; ++_i) \
;         __builtin_amdgcn_global_load_lds((const unsigned*)((const char*)(gbase) + (voff)[_i]), (PG8_LAS unsigned*)(lds + (bufoff) + ldsw + _i * 8192), 16, 0, 0); } while (0)
; #define PG8_LDA(dst, b, h) do { _Pragma("unroll") for (int m = 0; m < 4; ++m) _Pragma("unroll") for (int k = 0; k < 2; ++k) dst[m][k] = *(const PG8_LAS bf16x8*)(lds + PG8_SA(b, h) + aoff + m * 2048 + k * 1024); } while (0)
; #define PG8_LDB(dst, b, h) do { _Pragma("unroll") for (int n = 0; n < 2; ++n) _Pragma("unroll") for (int k = 0; k < 2; ++k) dst[n][k] = *(const PG8_LAS bf16x8*)(lds + PG8_SB(b, h) + boff + n * 2048 + k * 1024); } while (0)
; #define PG8_MMA(ai, bj, At, Bt) do { __builtin_amdgcn_s_setprio(1); _Pragma("unroll") for (int m = 0; m < 4; ++m) _Pragma("unroll") for (int n = 0; n < 2; ++n) _Pragma("unroll") for (int k = 0; k < 2; ++k) \
;         acc[ai][bj][m][n] = __builtin_amdgcn_mfma_f32_16x16x32_bf16(Bt[n][k], At[m][k], acc[ai][bj][m][n], 0, 0, 0); __builtin_amdgcn_s_setprio(0); } while (0)
; #define PG8_WAIT_V(n) asm volatile("s_waitcnt vmcnt(" #n ")" ::: "memory")
; #define PG8_WAIT_L(n) asm volatile("s_waitcnt lgkmcnt(" #n ")" ::: "memory")
; #define PG8_BAR __builtin_amdgcn_s_barrier()
; #define PG8_SCHED __builtin_amdgcn_sched_barrier(0)
; template <class Epi, class Sched, bool ALIGN_EPI = false, bool SP2 = false>
; __device__ __forceinline__ void gemm_phase(PG8_LAS unsigned char* lds, const Gemm g, const Sched& S, const Epi& E) {
;     ...
;             PG8_WAIT_V(8); PG8_WAIT_L(0); PG8_BAR; PG8_MMA(1, 0, At, B0); PG8_MMA(1, 1, At, B1); PG8_BAR; PG8_SCHED;
;             PG8_LDB(B0, 1, 0); PG8_LDB(B1, 1, 1); PG8_SCHED; PG8_LDA(At, 1, 0); PG8_STAGE(PG8_SA(0, 1), a2 + hstep, voffA);
;             PG8_WAIT_V(8); PG8_WAIT_L(0); PG8_BAR; PG8_MMA(0, 0, At, B0); PG8_MMA(0, 1, At, B1); PG8_BAR; PG8_SCHED;
;             PG8_LDA(At, 1, 1); PG8_STAGE(PG8_SB(1, 0), b3, voffB); PG8_STAGE(PG8_SB(1, 1), b3 + hstep, voffB); PG8_STAGE(PG8_SA(1, 0), a3, voffA);
	s_setprio 1
	s_waitcnt lgkmcnt(0)
	v_mfma_f32_16x16x32_bf16 v[60:63], v[174:177], v[214:217], v[60:63]
	v_mfma_f32_16x16x32_bf16 v[44:47], v[174:177], v[222:225], v[44:47]
	v_mfma_f32_16x16x32_bf16 v[28:31], v[174:177], v[230:233], v[28:31]
	v_mfma_f32_16x16x32_bf16 v[12:15], v[174:177], v[238:241], v[12:15]
	v_mfma_f32_16x16x32_bf16 v[8:11], v[190:193], v[238:241], v[8:11]
	v_mfma_f32_16x16x32_bf16 v[24:27], v[190:193], v[230:233], v[24:27]
	v_mfma_f32_16x16x32_bf16 v[40:43], v[190:193], v[222:225], v[40:43]
	v_mfma_f32_16x16x32_bf16 v[56:59], v[190:193], v[214:217], v[56:59]
	v_mfma_f32_16x16x32_bf16 v[60:63], v[178:181], v[218:221], v[60:63]
	v_mfma_f32_16x16x32_bf16 v[44:47], v[178:181], v[226:229], v[44:47]
	v_mfma_f32_16x16x32_bf16 v[28:31], v[178:181], v[234:237], v[28:31]
	v_mfma_f32_16x16x32_bf16 v[12:15], v[178:181], v[242:245], v[12:15]
	v_mfma_f32_16x16x32_bf16 v[8:11], v[194:197], v[242:245], v[8:11]
	v_mfma_f32_16x16x32_bf16 v[24:27], v[194:197], v[234:237], v[24:27]
	v_mfma_f32_16x16x32_bf16 v[40:43], v[194:197], v[226:229], v[40:43]
	v_mfma_f32_16x16x32_bf16 v[56:59], v[194:197], v[218:221], v[56:59]
	s_setprio 0
	s_setprio 1
	v_mfma_f32_16x16x32_bf16 v[52:55], v[198:201], v[214:217], v[52:55]
	v_mfma_f32_16x16x32_bf16 v[36:39], v[198:201], v[222:225], v[36:39]
	v_mfma_f32_16x16x32_bf16 v[20:23], v[198:201], v[230:233], v[20:23]
	v_mfma_f32_16x16x32_bf16 v[4:7], v[198:201], v[238:241], v[4:7]
	v_mfma_f32_16x16x32_bf16 v[0:3], v[206:209], v[238:241], v[0:3]
	v_mfma_f32_16x16x32_bf16 v[16:19], v[206:209], v[230:233], v[16:19]
	v_mfma_f32_16x16x32_bf16 v[32:35], v[206:209], v[222:225], v[32:35]
	v_mfma_f32_16x16x32_bf16 v[48:51], v[206:209], v[214:217], v[48:51]
	v_mfma_f32_16x16x32_bf16 v[52:55], v[202:205], v[218:221], v[52:55]
	v_mfma_f32_16x16x32_bf16 v[36:39], v[202:205], v[226:229], v[36:39]
	v_mfma_f32_16x16x32_bf16 v[20:23], v[202:205], v[234:237], v[20:23]
	v_mfma_f32_16x16x32_bf16 v[4:7], v[202:205], v[242:245], v[4:7]
	v_mfma_f32_16x16x32_bf16 v[0:3], v[210:213], v[242:245], v[0:3]
	v_mfma_f32_16x16x32_bf16 v[16:19], v[210:213], v[234:237], v[16:19]
	v_mfma_f32_16x16x32_bf16 v[32:35], v[210:213], v[226:229], v[32:35]
	v_mfma_f32_16x16x32_bf16 v[48:51], v[210:213], v[218:221], v[48:51]
	s_setprio 0
	s_barrier
	s_add_i32 s76, 0, 0x18000
	v_add_u32_e32 v188, s76, v149
	s_add_i32 s77, 0, 0x1c000
	ds_read_b128 v[174:177], v188
	ds_read_b128 v[178:181], v188 offset:1024
	ds_read_b128 v[190:193], v188 offset:2048
	ds_read_b128 v[194:197], v188 offset:3072
	v_add_u32_e32 v188, s77, v149
	ds_read_b128 v[198:201], v188
	ds_read_b128 v[202:205], v188 offset:1024
	ds_read_b128 v[206:209], v188 offset:2048
	ds_read_b128 v[210:213], v188 offset:3072
	s_add_u32 s10, s54, 0x80000
	s_addc_u32 s11, s55, 0
	s_mov_b32 m0, s29
	v_lshl_add_u64 v[188:189], s[10:11], 0, v[128:129]
	ds_read_b128 v[214:217], v169 offset:32768
	ds_read_b128 v[218:221], v169 offset:33792
	ds_read_b128 v[222:225], v169 offset:34816
	ds_read_b128 v[226:229], v169 offset:35840
	ds_read_b128 v[230:233], v169 offset:36864
	ds_read_b128 v[234:237], v169 offset:37888
	ds_read_b128 v[238:241], v169 offset:38912
	ds_read_b128 v[242:245], v169 offset:39936
	global_load_lds_dwordx4 v[188:189], off
	v_lshl_add_u64 v[188:189], s[10:11], 0, v[130:131]
	s_mov_b32 m0, s56
	s_nop 0
	global_load_lds_dwordx4 v[188:189], off
	s_waitcnt vmcnt(8)
	s_waitcnt lgkmcnt(0)
	s_barrier
	s_setprio 1
	s_waitcnt lgkmcnt(0)
	v_mfma_f32_16x16x32_bf16 v[76:79], v[174:177], v[214:217], v[76:79]
	v_mfma_f32_16x16x32_bf16 v[92:95], v[174:177], v[222:225], v[92:95]
	v_mfma_f32_16x16x32_bf16 v[116:119], v[174:177], v[230:233], v[116:119]
	v_mfma_f32_16x16x32_bf16 v[124:127], v[174:177], v[238:241], v[124:127]
	v_mfma_f32_16x16x32_bf16 v[120:123], v[190:193], v[238:241], v[120:123]
	v_mfma_f32_16x16x32_bf16 v[112:115], v[190:193], v[230:233], v[112:115]
	v_mfma_f32_16x16x32_bf16 v[88:91], v[190:193], v[222:225], v[88:91]
	v_mfma_f32_16x16x32_bf16 v[72:75], v[190:193], v[214:217], v[72:75]
	v_mfma_f32_16x16x32_bf16 v[76:79], v[178:181], v[218:221], v[76:79]
	v_mfma_f32_16x16x32_bf16 v[92:95], v[178:181], v[226:229], v[92:95]
	v_mfma_f32_16x16x32_bf16 v[116:119], v[178:181], v[234:237], v[116:119]
	v_mfma_f32_16x16x32_bf16 v[124:127], v[178:181], v[242:245], v[124:127]
	v_mfma_f32_16x16x32_bf16 v[120:123], v[194:197], v[242:245], v[120:123]
	v_mfma_f32_16x16x32_bf16 v[112:115], v[194:197], v[234:237], v[112:115]
	v_mfma_f32_16x16x32_bf16 v[88:91], v[194:197], v[226:229], v[88:91]
	v_mfma_f32_16x16x32_bf16 v[72:75], v[194:197], v[218:221], v[72:75]
	s_setprio 0
	s_setprio 1
	v_mfma_f32_16x16x32_bf16 v[68:71], v[198:201], v[214:217], v[68:71]
	v_mfma_f32_16x16x32_bf16 v[84:87], v[198:201], v[222:225], v[84:87]
	v_mfma_f32_16x16x32_bf16 v[108:111], v[198:201], v[230:233], v[108:111]
	v_mfma_f32_16x16x32_bf16 v[104:107], v[198:201], v[238:241], v[104:107]
	v_mfma_f32_16x16x32_bf16 v[100:103], v[206:209], v[238:241], v[100:103]
	v_mfma_f32_16x16x32_bf16 v[96:99], v[206:209], v[230:233], v[96:99]
	v_mfma_f32_16x16x32_bf16 v[80:83], v[206:209], v[222:225], v[80:83]
	v_mfma_f32_16x16x32_bf16 v[64:67], v[206:209], v[214:217], v[64:67]
	v_mfma_f32_16x16x32_bf16 v[68:71], v[202:205], v[218:221], v[68:71]
	v_mfma_f32_16x16x32_bf16 v[84:87], v[202:205], v[226:229], v[84:87]
	v_mfma_f32_16x16x32_bf16 v[108:111], v[202:205], v[234:237], v[108:111]
	v_mfma_f32_16x16x32_bf16 v[104:107], v[202:205], v[242:245], v[104:107]
	v_mfma_f32_16x16x32_bf16 v[100:103], v[210:213], v[242:245], v[100:103]
	v_mfma_f32_16x16x32_bf16 v[96:99], v[210:213], v[234:237], v[96:99]
	v_mfma_f32_16x16x32_bf16 v[80:83], v[210:213], v[226:229], v[80:83]
	v_mfma_f32_16x16x32_bf16 v[64:67], v[210:213], v[218:221], v[64:67]
	s_setprio 0
	s_barrier
; #define PG8_STAGE(bufoff, gbase, voff) do { _Pragma("unroll") for (int _i = 0; _i < 2; ++_i) \
;         __builtin_amdgcn_global_load_lds((const unsigned*)((const char*)(gbase) + (voff)[_i]), (PG8_LAS unsigned*)(lds + (bufoff) + ldsw + _i * 8192), 16, 0, 0); } while (0)
; #define PG8_LDA(dst, b, h) do { _Pragma("unroll") for (int m = 0; m < 4; ++m) _Pragma("unroll") for (int k = 0; k < 2; ++k) dst[m][k] = *(const PG8_LAS bf16x8*)(lds + PG8_SA(b, h) + aoff + m * 2048 + k * 1024); } while (0)
; #define PG8_WAIT_V(n) asm volatile("s_waitcnt vmcnt(" #n ")" ::: "memory")
; template <class Epi, class Sched, bool ALIGN_EPI = false, bool SP2 = false>
; __device__ __forceinline__ void gemm_phase(PG8_LAS unsigned char* lds, const Gemm g, const Sched& S, const Epi& E) {
;     ...
;             PG8_LDA(At, 1, 1); PG8_STAGE(PG8_SB(1, 0), b3, voffB); PG8_STAGE(PG8_SB(1, 1), b3 + hstep, voffB); PG8_STAGE(PG8_SA(1, 0), a3, voffA);
;             PG8_WAIT_V(8); PG8_WAIT_L(0); PG8_BAR; PG8_MMA(1, 0, At, B0); PG8_MMA(1, 1, At, B1); PG8_BAR; PG8_SCHED;
;             } else {
;             PG8_LDB(B0, 0, 0); PG8_SCHED; PG8_LDA(At, 0, 0); PG8_STAGE(PG8_SA(1, 1), a1 + hstep, voffA);
;             PG8_WAIT_L(8); PG8_BAR; PG8_WAIT_L(0); PG8_MMA(0, 0, At, B0); PG8_BAR; PG8_SCHED;
;             PG8_LDB(B1, 0, 1); PG8_STAGE(PG8_SB(0, 0), b2, voffB);
;             PG8_BAR; PG8_WAIT_L(0); PG8_MMA(0, 1, At, B1); PG8_BAR;
;             PG8_LDA(At, 0, 1); PG8_STAGE(PG8_SA(0, 0), a2, voffA);
;             PG8_BAR; PG8_WAIT_L(0); PG8_MMA(1, 0, At, B0); PG8_BAR; PG8_SCHED;
;             PG8_STAGE(PG8_SB(0, 1), b2 + hstep, voffB);
;             PG8_WAIT_V(6); PG8_BAR; PG8_MMA(1, 1, At, B1); PG8_BAR;
;             PG8_LDB(B0, 1, 0); PG8_SCHED; PG8_LDA(At, 1, 0); PG8_STAGE(PG8_SA(0, 1), a2 + hstep, voffA);
;             PG8_WAIT_L(8); PG8_BAR; PG8_WAIT_L(0); PG8_MMA(0, 0, At, B0); PG8_BAR; PG8_SCHED;
;             PG8_LDB(B1, 1, 1); PG8_STAGE(PG8_SB(1, 0), b3, voffB);
;             PG8_BAR; PG8_WAIT_L(0); PG8_MMA(0, 1, At, B1); PG8_BAR;
;             PG8_LDA(At, 1, 1); PG8_STAGE(PG8_SA(1, 0), a3, voffA);
;             PG8_BAR; PG8_WAIT_L(0); PG8_MMA(1, 0, At, B0); PG8_BAR; PG8_SCHED;
;             PG8_STAGE(PG8_SB(1, 1), b3 + hstep, voffB);
;             PG8_WAIT_V(6); PG8_BAR; PG8_MMA(1, 1, At, B1); PG8_BAR;
;             }
;         }
;         if constexpr (ALIGN_EPI) { if (wr == 0) PG8_BAR; }
	s_add_i32 s10, s76, s2
	v_lshl_add_u64 v[188:189], v[246:247], 0, s[38:39]
	s_mov_b32 m0, s10
	ds_read_b128 v[214:217], v169 offset:49152
	ds_read_b128 v[218:221], v169 offset:50176
	ds_read_b128 v[222:225], v169 offset:51200
	ds_read_b128 v[226:229], v169 offset:52224
	ds_read_b128 v[230:233], v169 offset:53248
	ds_read_b128 v[234:237], v169 offset:54272
	ds_read_b128 v[238:241], v169 offset:55296
	ds_read_b128 v[242:245], v169 offset:56320
	global_load_lds_dwordx4 v[188:189], off
	s_add_i32 m0, s10, 0x2000
	s_add_u32 s10, s52, 0x80080
	v_lshl_add_u64 v[188:189], v[248:249], 0, s[38:39]
	s_addc_u32 s11, s53, 0
	s_add_i32 s52, s77, s2
	global_load_lds_dwordx4 v[188:189], off
	v_lshl_add_u64 v[188:189], s[10:11], 0, v[128:129]
	s_mov_b32 m0, s52
	s_nop 0
	global_load_lds_dwordx4 v[188:189], off
	v_lshl_add_u64 v[188:189], s[10:11], 0, v[130:131]
	s_add_i32 m0, s52, 0x2000
	s_nop 0
	global_load_lds_dwordx4 v[188:189], off
	v_lshl_add_u64 v[188:189], v[250:251], 0, s[38:39]
	s_mov_b32 m0, s59
	s_nop 0
	global_load_lds_dwordx4 v[188:189], off
	v_lshl_add_u64 v[188:189], v[252:253], 0, s[38:39]
	s_mov_b32 m0, s60
	s_nop 0
	global_load_lds_dwordx4 v[188:189], off
	s_waitcnt vmcnt(8)
	s_waitcnt lgkmcnt(0)
	s_barrier
	s_setprio 1
	s_waitcnt lgkmcnt(0)
	v_mfma_f32_16x16x32_bf16 v[60:63], v[174:177], v[214:217], v[60:63]
	v_mfma_f32_16x16x32_bf16 v[44:47], v[174:177], v[222:225], v[44:47]
	v_mfma_f32_16x16x32_bf16 v[28:31], v[174:177], v[230:233], v[28:31]
	v_mfma_f32_16x16x32_bf16 v[12:15], v[174:177], v[238:241], v[12:15]
	v_mfma_f32_16x16x32_bf16 v[8:11], v[190:193], v[238:241], v[8:11]
	v_mfma_f32_16x16x32_bf16 v[24:27], v[190:193], v[230:233], v[24:27]
	v_mfma_f32_16x16x32_bf16 v[40:43], v[190:193], v[222:225], v[40:43]
	v_mfma_f32_16x16x32_bf16 v[56:59], v[190:193], v[214:217], v[56:59]
	v_mfma_f32_16x16x32_bf16 v[60:63], v[178:181], v[218:221], v[60:63]
	v_mfma_f32_16x16x32_bf16 v[44:47], v[178:181], v[226:229], v[44:47]
	v_mfma_f32_16x16x32_bf16 v[28:31], v[178:181], v[234:237], v[28:31]
	v_mfma_f32_16x16x32_bf16 v[12:15], v[178:181], v[242:245], v[12:15]
	v_mfma_f32_16x16x32_bf16 v[8:11], v[194:197], v[242:245], v[8:11]
	v_mfma_f32_16x16x32_bf16 v[24:27], v[194:197], v[234:237], v[24:27]
	v_mfma_f32_16x16x32_bf16 v[40:43], v[194:197], v[226:229], v[40:43]
	v_mfma_f32_16x16x32_bf16 v[56:59], v[194:197], v[218:221], v[56:59]
	s_setprio 0
	s_setprio 1
	v_mfma_f32_16x16x32_bf16 v[52:55], v[198:201], v[214:217], v[52:55]
	v_mfma_f32_16x16x32_bf16 v[36:39], v[198:201], v[222:225], v[36:39]
	v_mfma_f32_16x16x32_bf16 v[20:23], v[198:201], v[230:233], v[20:23]
	v_mfma_f32_16x16x32_bf16 v[4:7], v[198:201], v[238:241], v[4:7]
	v_mfma_f32_16x16x32_bf16 v[0:3], v[206:209], v[238:241], v[0:3]
	v_mfma_f32_16x16x32_bf16 v[16:19], v[206:209], v[230:233], v[16:19]
	v_mfma_f32_16x16x32_bf16 v[32:35], v[206:209], v[222:225], v[32:35]
	v_mfma_f32_16x16x32_bf16 v[48:51], v[206:209], v[214:217], v[48:51]
	v_mfma_f32_16x16x32_bf16 v[52:55], v[202:205], v[218:221], v[52:55]
	v_mfma_f32_16x16x32_bf16 v[36:39], v[202:205], v[226:229], v[36:39]
	v_mfma_f32_16x16x32_bf16 v[20:23], v[202:205], v[234:237], v[20:23]
	v_mfma_f32_16x16x32_bf16 v[4:7], v[202:205], v[242:245], v[4:7]
	v_mfma_f32_16x16x32_bf16 v[0:3], v[210:213], v[242:245], v[0:3]
	v_mfma_f32_16x16x32_bf16 v[16:19], v[210:213], v[234:237], v[16:19]
	v_mfma_f32_16x16x32_bf16 v[32:35], v[210:213], v[226:229], v[32:35]
	v_mfma_f32_16x16x32_bf16 v[48:51], v[210:213], v[218:221], v[48:51]
	s_setprio 0
	s_barrier
	s_add_i32 s67, s67, 2
	s_cmp_gt_u32 s67, 29
	s_mov_b64 s[10:11], s[50:51]
	s_cbranch_scc0 .LBB0_560
	s_and_b64 vcc, exec, s[40:41]
	s_cbranch_vccz .LBB0_563
	s_barrier

; #define PG8_STAGE(bufoff, gbase, voff) do { _Pragma("unroll") for (int _i = 0; _i < 2; ++_i) \
;         __builtin_amdgcn_global_load_lds((const unsigned*)((const char*)(gbase) + (voff)[_i]), (PG8_LAS unsigned*)(lds + (bufoff) + ldsw + _i * 8192), 16, 0, 0); } while (0)
; #define PG8_LDA(dst, b, h) do { _Pragma("unroll") for (int m = 0; m < 4; ++m) _Pragma("unroll") for (int k = 0; k < 2; ++k) dst[m][k] = *(const PG8_LAS bf16x8*)(lds + PG8_SA(b, h) + aoff + m * 2048 + k * 1024); } while (0)
; #define PG8_LDB(dst, b, h) do { _Pragma("unroll") for (int n = 0; n < 2; ++n) _Pragma("unroll") for (int k = 0; k < 2; ++k) dst[n][k] = *(const PG8_LAS bf16x8*)(lds + PG8_SB(b, h) + boff + n * 2048 + k * 1024); } while (0)
; #define PG8_MMA(ai, bj, At, Bt) do { __builtin_amdgcn_s_setprio(1); _Pragma("unroll") for (int m = 0; m < 4; ++m) _Pragma("unroll") for (int n = 0; n < 2; ++n) _Pragma("unroll") for (int k = 0; k < 2; ++k) \
;         acc[ai][bj][m][n] = __builtin_amdgcn_mfma_f32_16x16x32_bf16(Bt[n][k], At[m][k], acc[ai][bj][m][n], 0, 0, 0); __builtin_amdgcn_s_setprio(0); } while (0)
; #define PG8_WAIT_V(n) asm volatile("s_waitcnt vmcnt(" #n ")" ::: "memory")
; #define PG8_WAIT_L(n) asm volatile("s_waitcnt lgkmcnt(" #n ")" ::: "memory")
; #define PG8_BAR __builtin_amdgcn_s_barrier()
; #define PG8_SCHED __builtin_amdgcn_sched_barrier(0)
; template <class Epi, class Sched, bool ALIGN_EPI = false, bool SP2 = false>
; __device__ __forceinline__ void gemm_phase(PG8_LAS unsigned char* lds, const Gemm g, const Sched& S, const Epi& E) {
;     ...
;             const bool last = (t == nt - 2);
;             const char* a1 = cA + (size_t)(t + 1) * kstep;
;             const char* a2 = last ? nA : cA + (size_t)(t + 2) * kstep; const char* b2 = last ? nB : cB + (size_t)(t + 2) * kstep;
;             const char* a3 = a2 + kstep; const char* b3 = b2 + kstep;
;             if (last && has_next) S.a_ready(nxt);
;             if constexpr (SP2) {
;             PG8_LDB(B0, 0, 0); PG8_LDB(B1, 0, 1); PG8_SCHED; PG8_LDA(At, 0, 0); PG8_STAGE(PG8_SA(1, 1), a1 + hstep, voffA);
;             PG8_WAIT_V(8); PG8_WAIT_L(0); PG8_BAR; PG8_MMA(0, 0, At, B0); PG8_MMA(0, 1, At, B1); PG8_BAR; PG8_SCHED;
;             PG8_LDA(At, 0, 1); PG8_STAGE(PG8_SB(0, 0), b2, voffB); PG8_STAGE(PG8_SB(0, 1), b2 + hstep, voffB); PG8_STAGE(PG8_SA(0, 0), a2, voffA);
.LBB0_621:
	ds_read_b128 v[146:149], v153
	ds_read_b128 v[156:159], v153 offset:1024
	ds_read_b128 v[160:163], v153 offset:2048
	ds_read_b128 v[164:167], v153 offset:3072
	ds_read_b128 v[168:171], v154
	ds_read_b128 v[172:175], v154 offset:1024
	ds_read_b128 v[176:179], v154 offset:2048
	ds_read_b128 v[190:193], v154 offset:3072
	s_add_u32 s34, s30, 0xfff80080
	s_addc_u32 s35, s31, -1
	s_cmp_eq_u32 s50, 28
	s_cselect_b32 s37, s15, s35
	s_cselect_b32 s36, s46, s34
	s_cselect_b32 s35, s13, s49
	s_cselect_b32 s34, s47, s48
	v_lshl_add_u64 v[180:181], s[30:31], 0, v[136:137]
	s_add_i32 m0, s23, 0xc000
	ds_read_b128 v[194:197], v155
	ds_read_b128 v[198:201], v155 offset:1024
	ds_read_b128 v[202:205], v155 offset:2048
	ds_read_b128 v[206:209], v155 offset:3072
	ds_read_b128 v[210:213], v155 offset:4096
	ds_read_b128 v[214:217], v155 offset:5120
	ds_read_b128 v[218:221], v155 offset:6144
	ds_read_b128 v[222:225], v155 offset:7168
	global_load_lds_dwordx4 v[180:181], off
	v_lshl_add_u64 v[180:181], s[30:31], 0, v[138:139]
	s_add_i32 m0, s23, 0xe000
	s_nop 0
	global_load_lds_dwordx4 v[180:181], off
	s_waitcnt vmcnt(8)
	s_waitcnt lgkmcnt(0)
	s_barrier
	s_setprio 1
	s_waitcnt lgkmcnt(0)
	v_mfma_f32_16x16x32_bf16 v[124:127], v[146:149], v[194:197], v[124:127]
	v_mfma_f32_16x16x32_bf16 v[108:111], v[146:149], v[202:205], v[108:111]
	v_mfma_f32_16x16x32_bf16 v[92:95], v[146:149], v[210:213], v[92:95]
	v_mfma_f32_16x16x32_bf16 v[76:79], v[146:149], v[218:221], v[76:79]
	v_mfma_f32_16x16x32_bf16 v[72:75], v[160:163], v[218:221], v[72:75]
	v_mfma_f32_16x16x32_bf16 v[88:91], v[160:163], v[210:213], v[88:91]
	v_mfma_f32_16x16x32_bf16 v[104:107], v[160:163], v[202:205], v[104:107]
	v_mfma_f32_16x16x32_bf16 v[120:123], v[160:163], v[194:197], v[120:123]
	v_mfma_f32_16x16x32_bf16 v[124:127], v[156:159], v[198:201], v[124:127]
	v_mfma_f32_16x16x32_bf16 v[108:111], v[156:159], v[206:209], v[108:111]
	v_mfma_f32_16x16x32_bf16 v[92:95], v[156:159], v[214:217], v[92:95]
	v_mfma_f32_16x16x32_bf16 v[76:79], v[156:159], v[222:225], v[76:79]
	v_mfma_f32_16x16x32_bf16 v[72:75], v[164:167], v[222:225], v[72:75]
	v_mfma_f32_16x16x32_bf16 v[88:91], v[164:167], v[214:217], v[88:91]
	v_mfma_f32_16x16x32_bf16 v[104:107], v[164:167], v[206:209], v[104:107]
	v_mfma_f32_16x16x32_bf16 v[120:123], v[164:167], v[198:201], v[120:123]
	s_setprio 0
	s_setprio 1
	v_mfma_f32_16x16x32_bf16 v[116:119], v[168:171], v[194:197], v[116:119]
	v_mfma_f32_16x16x32_bf16 v[100:103], v[168:171], v[202:205], v[100:103]
	v_mfma_f32_16x16x32_bf16 v[84:87], v[168:171], v[210:213], v[84:87]
	v_mfma_f32_16x16x32_bf16 v[68:71], v[168:171], v[218:221], v[68:71]
	v_mfma_f32_16x16x32_bf16 v[64:67], v[176:179], v[218:221], v[64:67]
	v_mfma_f32_16x16x32_bf16 v[80:83], v[176:179], v[210:213], v[80:83]
	v_mfma_f32_16x16x32_bf16 v[96:99], v[176:179], v[202:205], v[96:99]
	v_mfma_f32_16x16x32_bf16 v[112:115], v[176:179], v[194:197], v[112:115]
	v_mfma_f32_16x16x32_bf16 v[116:119], v[172:175], v[198:201], v[116:119]
	v_mfma_f32_16x16x32_bf16 v[100:103], v[172:175], v[206:209], v[100:103]
	v_mfma_f32_16x16x32_bf16 v[84:87], v[172:175], v[214:217], v[84:87]
	v_mfma_f32_16x16x32_bf16 v[68:71], v[172:175], v[222:225], v[68:71]
	v_mfma_f32_16x16x32_bf16 v[64:67], v[190:193], v[222:225], v[64:67]
	v_mfma_f32_16x16x32_bf16 v[80:83], v[190:193], v[214:217], v[80:83]
	v_mfma_f32_16x16x32_bf16 v[96:99], v[190:193], v[206:209], v[96:99]
	v_mfma_f32_16x16x32_bf16 v[112:115], v[190:193], v[198:201], v[112:115]
	s_setprio 0
	s_barrier
	s_add_i32 s51, s42, s2
	v_lshl_add_u64 v[180:181], s[34:35], 0, v[132:133]
	s_mov_b32 m0, s51
	ds_read_b128 v[194:197], v155 offset:16384
	ds_read_b128 v[198:201], v155 offset:17408
	ds_read_b128 v[202:205], v155 offset:18432
	ds_read_b128 v[206:209], v155 offset:19456
	ds_read_b128 v[210:213], v155 offset:20480
	ds_read_b128 v[214:217], v155 offset:21504
	ds_read_b128 v[218:221], v155 offset:22528
	ds_read_b128 v[222:225], v155 offset:23552
	global_load_lds_dwordx4 v[180:181], off
	s_add_i32 m0, s51, 0x2000
	s_add_u32 s52, s34, 0x80000
	v_lshl_add_u64 v[188:189], s[34:35], 0, v[128:129]
	s_addc_u32 s53, s35, 0
	s_add_i32 s51, s43, s2
	global_load_lds_dwordx4 v[188:189], off
	v_lshl_add_u64 v[226:227], s[52:53], 0, v[132:133]
	s_mov_b32 m0, s51
	v_lshl_add_u64 v[228:229], s[36:37], 0, v[130:131]
	global_load_lds_dwordx4 v[226:227], off
	v_lshl_add_u64 v[226:227], s[52:53], 0, v[128:129]
	s_add_i32 m0, s51, 0x2000
	s_nop 0
	global_load_lds_dwordx4 v[226:227], off
	v_lshl_add_u64 v[226:227], s[36:37], 0, v[134:135]
	s_mov_b32 m0, s23
	s_nop 0
	global_load_lds_dwordx4 v[226:227], off
	s_mov_b32 m0, s28
	s_nop 0
	global_load_lds_dwordx4 v[228:229], off
	s_waitcnt vmcnt(8)
	s_waitcnt lgkmcnt(0)
	s_barrier
; #define PG8_STAGE(bufoff, gbase, voff) do { _Pragma("unroll") for (int _i = 0; _i < 2; ++_i) \
;         __builtin_amdgcn_global_load_lds((const unsigned*)((const char*)(gbase) + (voff)[_i]), (PG8_LAS unsigned*)(lds + (bufoff) + ldsw + _i * 8192), 16, 0, 0); } while (0)
; #define PG8_LDA(dst, b, h) do { _Pragma("unroll") for (int m = 0; m < 4; ++m) _Pragma("unroll") for (int k = 0; k < 2; ++k) dst[m][k] = *(const PG8_LAS bf16x8*)(lds + PG8_SA(b, h) + aoff + m * 2048 + k * 1024); } while (0)
; #define PG8_LDB(dst, b, h) do { _Pragma("unroll") for (int n = 0; n < 2; ++n) _Pragma("unroll") for (int k = 0; k < 2; ++k) dst[n][k] = *(const PG8_LAS bf16x8*)(lds + PG8_SB(b, h) + boff + n * 2048 + k * 1024); } while (0)
; #define PG8_MMA(ai, bj, At, Bt) do { __builtin_amdgcn_s_setprio(1); _Pragma("unroll") for (int m = 0; m < 4; ++m) _Pragma("unroll") for (int n = 0; n < 2; ++n) _Pragma("unroll") for (int k = 0; k < 2; ++k) \
;         acc[ai][bj][m][n] = __builtin_amdgcn_mfma_f32_16x16x32_bf16(Bt[n][k], At[m][k], acc[ai][bj][m][n], 0, 0, 0); __builtin_amdgcn_s_setprio(0); } while (0)
; #define PG8_WAIT_V(n) asm volatile("s_waitcnt vmcnt(" #n ")" ::: "memory")
; #define PG8_WAIT_L(n) asm volatile("s_waitcnt lgkmcnt(" #n ")" ::: "memory")
; #define PG8_BAR __builtin_amdgcn_s_barrier()
; #define PG8_SCHED __builtin_amdgcn_sched_barrier(0)
; template <class Epi, class Sched, bool ALIGN_EPI = false, bool SP2 = false>
; __device__ __forceinline__ void gemm_phase(PG8_LAS unsigned char* lds, const Gemm g, const Sched& S, const Epi& E) {
;     ...
;             PG8_WAIT_V(8); PG8_WAIT_L(0); PG8_BAR; PG8_MMA(1, 0, At, B0); PG8_MMA(1, 1, At, B1); PG8_BAR; PG8_SCHED;
;             PG8_LDB(B0, 1, 0); PG8_LDB(B1, 1, 1); PG8_SCHED; PG8_LDA(At, 1, 0); PG8_STAGE(PG8_SA(0, 1), a2 + hstep, voffA);
;             PG8_WAIT_V(8); PG8_WAIT_L(0); PG8_BAR; PG8_MMA(0, 0, At, B0); PG8_MMA(0, 1, At, B1); PG8_BAR; PG8_SCHED;
	s_setprio 1
	s_waitcnt lgkmcnt(0)
	v_mfma_f32_16x16x32_bf16 v[60:63], v[146:149], v[194:197], v[60:63]
	v_mfma_f32_16x16x32_bf16 v[44:47], v[146:149], v[202:205], v[44:47]
	v_mfma_f32_16x16x32_bf16 v[28:31], v[146:149], v[210:213], v[28:31]
	v_mfma_f32_16x16x32_bf16 v[12:15], v[146:149], v[218:221], v[12:15]
	v_mfma_f32_16x16x32_bf16 v[8:11], v[160:163], v[218:221], v[8:11]
	v_mfma_f32_16x16x32_bf16 v[24:27], v[160:163], v[210:213], v[24:27]
	v_mfma_f32_16x16x32_bf16 v[40:43], v[160:163], v[202:205], v[40:43]
	v_mfma_f32_16x16x32_bf16 v[56:59], v[160:163], v[194:197], v[56:59]
	v_mfma_f32_16x16x32_bf16 v[60:63], v[156:159], v[198:201], v[60:63]
	v_mfma_f32_16x16x32_bf16 v[44:47], v[156:159], v[206:209], v[44:47]
	v_mfma_f32_16x16x32_bf16 v[28:31], v[156:159], v[214:217], v[28:31]
	v_mfma_f32_16x16x32_bf16 v[12:15], v[156:159], v[222:225], v[12:15]
	v_mfma_f32_16x16x32_bf16 v[8:11], v[164:167], v[222:225], v[8:11]
	v_mfma_f32_16x16x32_bf16 v[24:27], v[164:167], v[214:217], v[24:27]
	v_mfma_f32_16x16x32_bf16 v[40:43], v[164:167], v[206:209], v[40:43]
	v_mfma_f32_16x16x32_bf16 v[56:59], v[164:167], v[198:201], v[56:59]
	s_setprio 0
	s_setprio 1
	v_mfma_f32_16x16x32_bf16 v[52:55], v[168:171], v[194:197], v[52:55]
	v_mfma_f32_16x16x32_bf16 v[36:39], v[168:171], v[202:205], v[36:39]
	v_mfma_f32_16x16x32_bf16 v[20:23], v[168:171], v[210:213], v[20:23]
	v_mfma_f32_16x16x32_bf16 v[4:7], v[168:171], v[218:221], v[4:7]
	v_mfma_f32_16x16x32_bf16 v[0:3], v[176:179], v[218:221], v[0:3]
	v_mfma_f32_16x16x32_bf16 v[16:19], v[176:179], v[210:213], v[16:19]
	v_mfma_f32_16x16x32_bf16 v[32:35], v[176:179], v[202:205], v[32:35]
	v_mfma_f32_16x16x32_bf16 v[48:51], v[176:179], v[194:197], v[48:51]
	v_mfma_f32_16x16x32_bf16 v[52:55], v[172:175], v[198:201], v[52:55]
	v_mfma_f32_16x16x32_bf16 v[36:39], v[172:175], v[206:209], v[36:39]
	v_mfma_f32_16x16x32_bf16 v[20:23], v[172:175], v[214:217], v[20:23]
	v_mfma_f32_16x16x32_bf16 v[4:7], v[172:175], v[222:225], v[4:7]
	v_mfma_f32_16x16x32_bf16 v[0:3], v[190:193], v[222:225], v[0:3]
	v_mfma_f32_16x16x32_bf16 v[16:19], v[190:193], v[214:217], v[16:19]
	v_mfma_f32_16x16x32_bf16 v[32:35], v[190:193], v[206:209], v[32:35]
	v_mfma_f32_16x16x32_bf16 v[48:51], v[190:193], v[198:201], v[48:51]
	s_setprio 0
	s_barrier
	s_add_i32 s51, 0, 0x18000
	s_add_i32 s52, 0, 0x1c000
	v_add_u32_e32 v164, s51, v151
	v_add_u32_e32 v190, s52, v151
	ds_read_b128 v[146:149], v164
	ds_read_b128 v[156:159], v164 offset:1024
	ds_read_b128 v[160:163], v164 offset:2048
	ds_read_b128 v[164:167], v164 offset:3072
	ds_read_b128 v[168:171], v190
	ds_read_b128 v[172:175], v190 offset:1024
	ds_read_b128 v[176:179], v190 offset:2048
	ds_read_b128 v[190:193], v190 offset:3072
	s_add_u32 s36, s36, 0x80000
	s_addc_u32 s37, s37, 0
	s_mov_b32 m0, s29
	v_lshl_add_u64 v[230:231], s[36:37], 0, v[134:135]
	ds_read_b128 v[194:197], v155 offset:32768
	ds_read_b128 v[198:201], v155 offset:33792
	ds_read_b128 v[202:205], v155 offset:34816
	ds_read_b128 v[206:209], v155 offset:35840
	ds_read_b128 v[210:213], v155 offset:36864
	ds_read_b128 v[214:217], v155 offset:37888
	ds_read_b128 v[218:221], v155 offset:38912
	ds_read_b128 v[222:225], v155 offset:39936
	global_load_lds_dwordx4 v[230:231], off
	v_lshl_add_u64 v[230:231], s[36:37], 0, v[130:131]
	s_mov_b32 m0, s38
	s_nop 0
	global_load_lds_dwordx4 v[230:231], off
	s_waitcnt vmcnt(8)
	s_waitcnt lgkmcnt(0)
	s_barrier
	s_setprio 1
	s_waitcnt lgkmcnt(0)
	v_mfma_f32_16x16x32_bf16 v[124:127], v[146:149], v[194:197], v[124:127]
	v_mfma_f32_16x16x32_bf16 v[108:111], v[146:149], v[202:205], v[108:111]
	v_mfma_f32_16x16x32_bf16 v[92:95], v[146:149], v[210:213], v[92:95]
	v_mfma_f32_16x16x32_bf16 v[76:79], v[146:149], v[218:221], v[76:79]
	v_mfma_f32_16x16x32_bf16 v[72:75], v[160:163], v[218:221], v[72:75]
	v_mfma_f32_16x16x32_bf16 v[88:91], v[160:163], v[210:213], v[88:91]
	v_mfma_f32_16x16x32_bf16 v[104:107], v[160:163], v[202:205], v[104:107]
	v_mfma_f32_16x16x32_bf16 v[120:123], v[160:163], v[194:197], v[120:123]
	v_mfma_f32_16x16x32_bf16 v[124:127], v[156:159], v[198:201], v[124:127]
	v_mfma_f32_16x16x32_bf16 v[108:111], v[156:159], v[206:209], v[108:111]
	v_mfma_f32_16x16x32_bf16 v[92:95], v[156:159], v[214:217], v[92:95]
	v_mfma_f32_16x16x32_bf16 v[76:79], v[156:159], v[222:225], v[76:79]
	v_mfma_f32_16x16x32_bf16 v[72:75], v[164:167], v[222:225], v[72:75]
	v_mfma_f32_16x16x32_bf16 v[88:91], v[164:167], v[214:217], v[88:91]
	v_mfma_f32_16x16x32_bf16 v[104:107], v[164:167], v[206:209], v[104:107]
	v_mfma_f32_16x16x32_bf16 v[120:123], v[164:167], v[198:201], v[120:123]
	s_setprio 0
	s_setprio 1
	v_mfma_f32_16x16x32_bf16 v[116:119], v[168:171], v[194:197], v[116:119]
	v_mfma_f32_16x16x32_bf16 v[100:103], v[168:171], v[202:205], v[100:103]
	v_mfma_f32_16x16x32_bf16 v[84:87], v[168:171], v[210:213], v[84:87]
	v_mfma_f32_16x16x32_bf16 v[68:71], v[168:171], v[218:221], v[68:71]
	v_mfma_f32_16x16x32_bf16 v[64:67], v[176:179], v[218:221], v[64:67]
	v_mfma_f32_16x16x32_bf16 v[80:83], v[176:179], v[210:213], v[80:83]
	v_mfma_f32_16x16x32_bf16 v[96:99], v[176:179], v[202:205], v[96:99]
	v_mfma_f32_16x16x32_bf16 v[112:115], v[176:179], v[194:197], v[112:115]
	v_mfma_f32_16x16x32_bf16 v[116:119], v[172:175], v[198:201], v[116:119]
	v_mfma_f32_16x16x32_bf16 v[100:103], v[172:175], v[206:209], v[100:103]
	v_mfma_f32_16x16x32_bf16 v[84:87], v[172:175], v[214:217], v[84:87]
	v_mfma_f32_16x16x32_bf16 v[68:71], v[172:175], v[222:225], v[68:71]
	v_mfma_f32_16x16x32_bf16 v[64:67], v[190:193], v[222:225], v[64:67]
	v_mfma_f32_16x16x32_bf16 v[80:83], v[190:193], v[214:217], v[80:83]
	v_mfma_f32_16x16x32_bf16 v[96:99], v[190:193], v[206:209], v[96:99]
	v_mfma_f32_16x16x32_bf16 v[112:115], v[190:193], v[198:201], v[112:115]
	s_setprio 0
	s_barrier
; #define PG8_STAGE(bufoff, gbase, voff) do { _Pragma("unroll") for (int _i = 0; _i < 2; ++_i) \
;         __builtin_amdgcn_global_load_lds((const unsigned*)((const char*)(gbase) + (voff)[_i]), (PG8_LAS unsigned*)(lds + (bufoff) + ldsw + _i * 8192), 16, 0, 0); } while (0)
; #define PG8_LDA(dst, b, h) do { _Pragma("unroll") for (int m = 0; m < 4; ++m) _Pragma("unroll") for (int k = 0; k < 2; ++k) dst[m][k] = *(const PG8_LAS bf16x8*)(lds + PG8_SA(b, h) + aoff + m * 2048 + k * 1024); } while (0)
; #define PG8_MMA(ai, bj, At, Bt) do { __builtin_amdgcn_s_setprio(1); _Pragma("unroll") for (int m = 0; m < 4; ++m) _Pragma("unroll") for (int n = 0; n < 2; ++n) _Pragma("unroll") for (int k = 0; k < 2; ++k) \
;         acc[ai][bj][m][n] = __builtin_amdgcn_mfma_f32_16x16x32_bf16(Bt[n][k], At[m][k], acc[ai][bj][m][n], 0, 0, 0); __builtin_amdgcn_s_setprio(0); } while (0)
; #define PG8_WAIT_V(n) asm volatile("s_waitcnt vmcnt(" #n ")" ::: "memory")
; #define PG8_WAIT_L(n) asm volatile("s_waitcnt lgkmcnt(" #n ")" ::: "memory")
; #define PG8_BAR __builtin_amdgcn_s_barrier()
; #define PG8_SCHED __builtin_amdgcn_sched_barrier(0)
; template <class Epi, class Sched, bool ALIGN_EPI = false, bool SP2 = false>
; __device__ __forceinline__ void gemm_phase(PG8_LAS unsigned char* lds, const Gemm g, const Sched& S, const Epi& E) {
;     ...
;             PG8_LDA(At, 1, 1); PG8_STAGE(PG8_SB(1, 0), b3, voffB); PG8_STAGE(PG8_SB(1, 1), b3 + hstep, voffB); PG8_STAGE(PG8_SA(1, 0), a3, voffA);
;             PG8_WAIT_V(8); PG8_WAIT_L(0); PG8_BAR; PG8_MMA(1, 0, At, B0); PG8_MMA(1, 1, At, B1); PG8_BAR; PG8_SCHED;
	s_add_i32 s36, s51, s2
	v_lshl_add_u64 v[180:181], v[180:181], 0, s[8:9]
	s_mov_b32 m0, s36
	ds_read_b128 v[194:197], v155 offset:49152
	ds_read_b128 v[198:201], v155 offset:50176
	ds_read_b128 v[202:205], v155 offset:51200
	ds_read_b128 v[206:209], v155 offset:52224
	ds_read_b128 v[210:213], v155 offset:53248
	ds_read_b128 v[214:217], v155 offset:54272
	ds_read_b128 v[218:221], v155 offset:55296
	ds_read_b128 v[222:225], v155 offset:56320
	global_load_lds_dwordx4 v[180:181], off
	s_add_i32 m0, s36, 0x2000
	s_add_u32 s34, s34, 0x80080
	v_lshl_add_u64 v[180:181], v[188:189], 0, s[8:9]
	s_addc_u32 s35, s35, 0
	s_add_i32 s36, s52, s2
	global_load_lds_dwordx4 v[180:181], off
	v_lshl_add_u64 v[180:181], s[34:35], 0, v[132:133]
	s_mov_b32 m0, s36
	s_nop 0
	global_load_lds_dwordx4 v[180:181], off
	v_lshl_add_u64 v[180:181], s[34:35], 0, v[128:129]
	s_add_i32 m0, s36, 0x2000
	s_nop 0
	global_load_lds_dwordx4 v[180:181], off
	v_lshl_add_u64 v[180:181], v[226:227], 0, s[8:9]
	s_mov_b32 m0, s40
	s_nop 0
	global_load_lds_dwordx4 v[180:181], off
	v_lshl_add_u64 v[180:181], v[228:229], 0, s[8:9]
	s_mov_b32 m0, s41
	s_nop 0
	global_load_lds_dwordx4 v[180:181], off
	s_waitcnt vmcnt(8)
	s_waitcnt lgkmcnt(0)
	s_barrier
	s_setprio 1
	s_waitcnt lgkmcnt(0)
	v_mfma_f32_16x16x32_bf16 v[60:63], v[146:149], v[194:197], v[60:63]
	v_mfma_f32_16x16x32_bf16 v[44:47], v[146:149], v[202:205], v[44:47]
	v_mfma_f32_16x16x32_bf16 v[28:31], v[146:149], v[210:213], v[28:31]
	v_mfma_f32_16x16x32_bf16 v[12:15], v[146:149], v[218:221], v[12:15]
	v_mfma_f32_16x16x32_bf16 v[8:11], v[160:163], v[218:221], v[8:11]
	v_mfma_f32_16x16x32_bf16 v[24:27], v[160:163], v[210:213], v[24:27]
	v_mfma_f32_16x16x32_bf16 v[40:43], v[160:163], v[202:205], v[40:43]
	v_mfma_f32_16x16x32_bf16 v[56:59], v[160:163], v[194:197], v[56:59]
	v_mfma_f32_16x16x32_bf16 v[60:63], v[156:159], v[198:201], v[60:63]
	v_mfma_f32_16x16x32_bf16 v[44:47], v[156:159], v[206:209], v[44:47]
	v_mfma_f32_16x16x32_bf16 v[28:31], v[156:159], v[214:217], v[28:31]
	v_mfma_f32_16x16x32_bf16 v[12:15], v[156:159], v[222:225], v[12:15]
	v_mfma_f32_16x16x32_bf16 v[8:11], v[164:167], v[222:225], v[8:11]
	v_mfma_f32_16x16x32_bf16 v[24:27], v[164:167], v[214:217], v[24:27]
	v_mfma_f32_16x16x32_bf16 v[40:43], v[164:167], v[206:209], v[40:43]
	v_mfma_f32_16x16x32_bf16 v[56:59], v[164:167], v[198:201], v[56:59]
	s_setprio 0
	s_setprio 1
	v_mfma_f32_16x16x32_bf16 v[52:55], v[168:171], v[194:197], v[52:55]
	v_mfma_f32_16x16x32_bf16 v[36:39], v[168:171], v[202:205], v[36:39]
	v_mfma_f32_16x16x32_bf16 v[20:23], v[168:171], v[210:213], v[20:23]
	v_mfma_f32_16x16x32_bf16 v[4:7], v[168:171], v[218:221], v[4:7]
	v_mfma_f32_16x16x32_bf16 v[0:3], v[176:179], v[218:221], v[0:3]
	v_mfma_f32_16x16x32_bf16 v[16:19], v[176:179], v[210:213], v[16:19]
	v_mfma_f32_16x16x32_bf16 v[32:35], v[176:179], v[202:205], v[32:35]
	v_mfma_f32_16x16x32_bf16 v[48:51], v[176:179], v[194:197], v[48:51]
	v_mfma_f32_16x16x32_bf16 v[52:55], v[172:175], v[198:201], v[52:55]
	v_mfma_f32_16x16x32_bf16 v[36:39], v[172:175], v[206:209], v[36:39]
	v_mfma_f32_16x16x32_bf16 v[20:23], v[172:175], v[214:217], v[20:23]
	v_mfma_f32_16x16x32_bf16 v[4:7], v[172:175], v[222:225], v[4:7]
	v_mfma_f32_16x16x32_bf16 v[0:3], v[190:193], v[222:225], v[0:3]
	v_mfma_f32_16x16x32_bf16 v[16:19], v[190:193], v[214:217], v[16:19]
	v_mfma_f32_16x16x32_bf16 v[32:35], v[190:193], v[206:209], v[32:35]
	v_mfma_f32_16x16x32_bf16 v[48:51], v[190:193], v[198:201], v[48:51]
	s_setprio 0
	s_barrier
	s_add_i32 s50, s50, 2
	s_add_u32 s30, s30, 0x100
	s_addc_u32 s31, s31, 0
	s_add_u32 s48, s48, 0x100
	s_addc_u32 s49, s49, 0
	s_cmp_gt_u32 s50, 29
	s_cbranch_scc0 .LBB0_621
	s_and_b64 vcc, exec, s[10:11]
	s_cbranch_vccz .LBB0_624
	s_barrier

; #define PG8_STAGE(bufoff, gbase, voff) do { _Pragma("unroll") for (int _i = 0; _i < 2; ++_i) \
;         __builtin_amdgcn_global_load_lds((const unsigned*)((const char*)(gbase) + (voff)[_i]), (PG8_LAS unsigned*)(lds + (bufoff) + ldsw + _i * 8192), 16, 0, 0); } while (0)
; #define PG8_LDA(dst, b, h) do { _Pragma("unroll") for (int m = 0; m < 4; ++m) _Pragma("unroll") for (int k = 0; k < 2; ++k) dst[m][k] = *(const PG8_LAS bf16x8*)(lds + PG8_SA(b, h) + aoff + m * 2048 + k * 1024); } while (0)
; #define PG8_LDB(dst, b, h) do { _Pragma("unroll") for (int n = 0; n < 2; ++n) _Pragma("unroll") for (int k = 0; k < 2; ++k) dst[n][k] = *(const PG8_LAS bf16x8*)(lds + PG8_SB(b, h) + boff + n * 2048 + k * 1024); } while (0)
; #define PG8_MMA(ai, bj, At, Bt) do { __builtin_amdgcn_s_setprio(1); _Pragma("unroll") for (int m = 0; m < 4; ++m) _Pragma("unroll") for (int n = 0; n < 2; ++n) _Pragma("unroll") for (int k = 0; k < 2; ++k) \
;         acc[ai][bj][m][n] = __builtin_amdgcn_mfma_f32_16x16x32_bf16(Bt[n][k], At[m][k], acc[ai][bj][m][n], 0, 0, 0); __builtin_amdgcn_s_setprio(0); } while (0)
; #define PG8_WAIT_V(n) asm volatile("s_waitcnt vmcnt(" #n ")" ::: "memory")
; #define PG8_WAIT_L(n) asm volatile("s_waitcnt lgkmcnt(" #n ")" ::: "memory")
; #define PG8_BAR __builtin_amdgcn_s_barrier()
; #define PG8_SCHED __builtin_amdgcn_sched_barrier(0)
; template <class Epi, class Sched, bool ALIGN_EPI = false, bool SP2 = false>
; __device__ __forceinline__ void gemm_phase(PG8_LAS unsigned char* lds, const Gemm g, const Sched& S, const Epi& E) {
;     ...
;             const bool last = (t == nt - 2);
;             const char* a1 = cA + (size_t)(t + 1) * kstep;
;             const char* a2 = last ? nA : cA + (size_t)(t + 2) * kstep; const char* b2 = last ? nB : cB + (size_t)(t + 2) * kstep;
;             const char* a3 = a2 + kstep; const char* b3 = b2 + kstep;
;             if (last && has_next) S.a_ready(nxt);
;             if constexpr (SP2) {
;             PG8_LDB(B0, 0, 0); PG8_LDB(B1, 0, 1); PG8_SCHED; PG8_LDA(At, 0, 0); PG8_STAGE(PG8_SA(1, 1), a1 + hstep, voffA);
;             PG8_WAIT_V(8); PG8_WAIT_L(0); PG8_BAR; PG8_MMA(0, 0, At, B0); PG8_MMA(0, 1, At, B1); PG8_BAR; PG8_SCHED;
;             PG8_LDA(At, 0, 1); PG8_STAGE(PG8_SB(0, 0), b2, voffB); PG8_STAGE(PG8_SB(0, 1), b2 + hstep, voffB); PG8_STAGE(PG8_SA(0, 0), a2, voffA);
.LBB0_649:
	ds_read_b128 v[140:143], v165
	ds_read_b128 v[176:179], v165 offset:1024
	ds_read_b128 v[180:183], v165 offset:2048
	ds_read_b128 v[184:187], v165 offset:3072
	ds_read_b128 v[188:191], v166
	ds_read_b128 v[192:195], v166 offset:1024
	ds_read_b128 v[196:199], v166 offset:2048
	ds_read_b128 v[200:203], v166 offset:3072
	s_add_u32 s40, s8, 0xffea0080
	s_addc_u32 s41, s9, -1
	s_cmpk_eq_i32 s65, 0x54
	s_cselect_b32 s43, s37, s41
	s_cselect_b32 s42, s36, s40
	s_cselect_b32 s41, s11, s39
	s_cselect_b32 s40, s10, s38
	s_mov_b32 m0, s54
	v_lshl_add_u64 v[144:145], s[8:9], 0, v[136:137]
	ds_read_b128 v[204:207], v167
	ds_read_b128 v[208:211], v167 offset:1024
	ds_read_b128 v[212:215], v167 offset:2048
	ds_read_b128 v[216:219], v167 offset:3072
	ds_read_b128 v[220:223], v167 offset:4096
	ds_read_b128 v[224:227], v167 offset:5120
	ds_read_b128 v[228:231], v167 offset:6144
	ds_read_b128 v[232:235], v167 offset:7168
	global_load_lds_dwordx4 v[144:145], off
	v_lshl_add_u64 v[144:145], s[8:9], 0, v[138:139]
	s_mov_b32 m0, s55
	s_nop 0
	global_load_lds_dwordx4 v[144:145], off
	s_waitcnt vmcnt(8)
	s_waitcnt lgkmcnt(0)
	s_barrier
	s_setprio 1
	s_waitcnt lgkmcnt(0)
	v_mfma_f32_16x16x32_bf16 v[124:127], v[140:143], v[204:207], v[124:127]
	v_mfma_f32_16x16x32_bf16 v[108:111], v[140:143], v[212:215], v[108:111]
	v_mfma_f32_16x16x32_bf16 v[92:95], v[140:143], v[220:223], v[92:95]
	v_mfma_f32_16x16x32_bf16 v[76:79], v[140:143], v[228:231], v[76:79]
	v_mfma_f32_16x16x32_bf16 v[72:75], v[180:183], v[228:231], v[72:75]
	v_mfma_f32_16x16x32_bf16 v[88:91], v[180:183], v[220:223], v[88:91]
	v_mfma_f32_16x16x32_bf16 v[104:107], v[180:183], v[212:215], v[104:107]
	v_mfma_f32_16x16x32_bf16 v[120:123], v[180:183], v[204:207], v[120:123]
	v_mfma_f32_16x16x32_bf16 v[124:127], v[176:179], v[208:211], v[124:127]
	v_mfma_f32_16x16x32_bf16 v[108:111], v[176:179], v[216:219], v[108:111]
	v_mfma_f32_16x16x32_bf16 v[92:95], v[176:179], v[224:227], v[92:95]
	v_mfma_f32_16x16x32_bf16 v[76:79], v[176:179], v[232:235], v[76:79]
	v_mfma_f32_16x16x32_bf16 v[72:75], v[184:187], v[232:235], v[72:75]
	v_mfma_f32_16x16x32_bf16 v[88:91], v[184:187], v[224:227], v[88:91]
	v_mfma_f32_16x16x32_bf16 v[104:107], v[184:187], v[216:219], v[104:107]
	v_mfma_f32_16x16x32_bf16 v[120:123], v[184:187], v[208:211], v[120:123]
	s_setprio 0
	s_setprio 1
	v_mfma_f32_16x16x32_bf16 v[116:119], v[188:191], v[204:207], v[116:119]
	v_mfma_f32_16x16x32_bf16 v[100:103], v[188:191], v[212:215], v[100:103]
	v_mfma_f32_16x16x32_bf16 v[84:87], v[188:191], v[220:223], v[84:87]
	v_mfma_f32_16x16x32_bf16 v[68:71], v[188:191], v[228:231], v[68:71]
	v_mfma_f32_16x16x32_bf16 v[64:67], v[196:199], v[228:231], v[64:67]
	v_mfma_f32_16x16x32_bf16 v[80:83], v[196:199], v[220:223], v[80:83]
	v_mfma_f32_16x16x32_bf16 v[96:99], v[196:199], v[212:215], v[96:99]
	v_mfma_f32_16x16x32_bf16 v[112:115], v[196:199], v[204:207], v[112:115]
	v_mfma_f32_16x16x32_bf16 v[116:119], v[192:195], v[208:211], v[116:119]
	v_mfma_f32_16x16x32_bf16 v[100:103], v[192:195], v[216:219], v[100:103]
	v_mfma_f32_16x16x32_bf16 v[84:87], v[192:195], v[224:227], v[84:87]
	v_mfma_f32_16x16x32_bf16 v[68:71], v[192:195], v[232:235], v[68:71]
	v_mfma_f32_16x16x32_bf16 v[64:67], v[200:203], v[232:235], v[64:67]
	v_mfma_f32_16x16x32_bf16 v[80:83], v[200:203], v[224:227], v[80:83]
	v_mfma_f32_16x16x32_bf16 v[96:99], v[200:203], v[216:219], v[96:99]
	v_mfma_f32_16x16x32_bf16 v[112:115], v[200:203], v[208:211], v[112:115]
	s_setprio 0
	s_barrier
	s_mov_b32 m0, s56
	v_lshl_add_u64 v[144:145], s[40:41], 0, v[128:129]
	s_add_u32 s66, s40, 0x160000
	ds_read_b128 v[204:207], v167 offset:16384
	ds_read_b128 v[208:211], v167 offset:17408
	ds_read_b128 v[212:215], v167 offset:18432
	ds_read_b128 v[216:219], v167 offset:19456
	ds_read_b128 v[220:223], v167 offset:20480
	ds_read_b128 v[224:227], v167 offset:21504
	ds_read_b128 v[228:231], v167 offset:22528
	ds_read_b128 v[232:235], v167 offset:23552
	global_load_lds_dwordx4 v[144:145], off
	v_lshl_add_u64 v[236:237], s[40:41], 0, v[130:131]
	s_mov_b32 m0, s57
	s_addc_u32 s67, s41, 0
	global_load_lds_dwordx4 v[236:237], off
	v_lshl_add_u64 v[238:239], s[66:67], 0, v[128:129]
	s_mov_b32 m0, s58
	v_lshl_add_u64 v[240:241], s[42:43], 0, v[130:131]
	global_load_lds_dwordx4 v[238:239], off
	v_lshl_add_u64 v[238:239], s[66:67], 0, v[130:131]
	s_mov_b32 m0, s59
	s_nop 0
	global_load_lds_dwordx4 v[238:239], off
	v_lshl_add_u64 v[238:239], s[42:43], 0, v[128:129]
	s_mov_b32 m0, s33
	s_nop 0
	global_load_lds_dwordx4 v[238:239], off
	s_mov_b32 m0, s46
	s_nop 0
	global_load_lds_dwordx4 v[240:241], off
	s_waitcnt vmcnt(8)
	s_waitcnt lgkmcnt(0)
	s_barrier
; #define PG8_STAGE(bufoff, gbase, voff) do { _Pragma("unroll") for (int _i = 0; _i < 2; ++_i) \
;         __builtin_amdgcn_global_load_lds((const unsigned*)((const char*)(gbase) + (voff)[_i]), (PG8_LAS unsigned*)(lds + (bufoff) + ldsw + _i * 8192), 16, 0, 0); } while (0)
; #define PG8_LDA(dst, b, h) do { _Pragma("unroll") for (int m = 0; m < 4; ++m) _Pragma("unroll") for (int k = 0; k < 2; ++k) dst[m][k] = *(const PG8_LAS bf16x8*)(lds + PG8_SA(b, h) + aoff + m * 2048 + k * 1024); } while (0)
; #define PG8_LDB(dst, b, h) do { _Pragma("unroll") for (int n = 0; n < 2; ++n) _Pragma("unroll") for (int k = 0; k < 2; ++k) dst[n][k] = *(const PG8_LAS bf16x8*)(lds + PG8_SB(b, h) + boff + n * 2048 + k * 1024); } while (0)
; #define PG8_MMA(ai, bj, At, Bt) do { __builtin_amdgcn_s_setprio(1); _Pragma("unroll") for (int m = 0; m < 4; ++m) _Pragma("unroll") for (int n = 0; n < 2; ++n) _Pragma("unroll") for (int k = 0; k < 2; ++k) \
;         acc[ai][bj][m][n] = __builtin_amdgcn_mfma_f32_16x16x32_bf16(Bt[n][k], At[m][k], acc[ai][bj][m][n], 0, 0, 0); __builtin_amdgcn_s_setprio(0); } while (0)
; #define PG8_WAIT_V(n) asm volatile("s_waitcnt vmcnt(" #n ")" ::: "memory")
; #define PG8_WAIT_L(n) asm volatile("s_waitcnt lgkmcnt(" #n ")" ::: "memory")
; #define PG8_BAR __builtin_amdgcn_s_barrier()
; #define PG8_SCHED __builtin_amdgcn_sched_barrier(0)
; template <class Epi, class Sched, bool ALIGN_EPI = false, bool SP2 = false>
; __device__ __forceinline__ void gemm_phase(PG8_LAS unsigned char* lds, const Gemm g, const Sched& S, const Epi& E) {
;     ...
;             PG8_WAIT_V(8); PG8_WAIT_L(0); PG8_BAR; PG8_MMA(1, 0, At, B0); PG8_MMA(1, 1, At, B1); PG8_BAR; PG8_SCHED;
;             PG8_LDB(B0, 1, 0); PG8_LDB(B1, 1, 1); PG8_SCHED; PG8_LDA(At, 1, 0); PG8_STAGE(PG8_SA(0, 1), a2 + hstep, voffA);
;             PG8_WAIT_V(8); PG8_WAIT_L(0); PG8_BAR; PG8_MMA(0, 0, At, B0); PG8_MMA(0, 1, At, B1); PG8_BAR; PG8_SCHED;
	s_setprio 1
	s_waitcnt lgkmcnt(0)
	v_mfma_f32_16x16x32_bf16 v[60:63], v[140:143], v[204:207], v[60:63]
	v_mfma_f32_16x16x32_bf16 v[44:47], v[140:143], v[212:215], v[44:47]
	v_mfma_f32_16x16x32_bf16 v[28:31], v[140:143], v[220:223], v[28:31]
	v_mfma_f32_16x16x32_bf16 v[12:15], v[140:143], v[228:231], v[12:15]
	v_mfma_f32_16x16x32_bf16 v[8:11], v[180:183], v[228:231], v[8:11]
	v_mfma_f32_16x16x32_bf16 v[24:27], v[180:183], v[220:223], v[24:27]
	v_mfma_f32_16x16x32_bf16 v[40:43], v[180:183], v[212:215], v[40:43]
	v_mfma_f32_16x16x32_bf16 v[56:59], v[180:183], v[204:207], v[56:59]
	v_mfma_f32_16x16x32_bf16 v[60:63], v[176:179], v[208:211], v[60:63]
	v_mfma_f32_16x16x32_bf16 v[44:47], v[176:179], v[216:219], v[44:47]
	v_mfma_f32_16x16x32_bf16 v[28:31], v[176:179], v[224:227], v[28:31]
	v_mfma_f32_16x16x32_bf16 v[12:15], v[176:179], v[232:235], v[12:15]
	v_mfma_f32_16x16x32_bf16 v[8:11], v[184:187], v[232:235], v[8:11]
	v_mfma_f32_16x16x32_bf16 v[24:27], v[184:187], v[224:227], v[24:27]
	v_mfma_f32_16x16x32_bf16 v[40:43], v[184:187], v[216:219], v[40:43]
	v_mfma_f32_16x16x32_bf16 v[56:59], v[184:187], v[208:211], v[56:59]
	s_setprio 0
	s_setprio 1
	v_mfma_f32_16x16x32_bf16 v[52:55], v[188:191], v[204:207], v[52:55]
	v_mfma_f32_16x16x32_bf16 v[36:39], v[188:191], v[212:215], v[36:39]
	v_mfma_f32_16x16x32_bf16 v[20:23], v[188:191], v[220:223], v[20:23]
	v_mfma_f32_16x16x32_bf16 v[4:7], v[188:191], v[228:231], v[4:7]
	v_mfma_f32_16x16x32_bf16 v[0:3], v[196:199], v[228:231], v[0:3]
	v_mfma_f32_16x16x32_bf16 v[16:19], v[196:199], v[220:223], v[16:19]
	v_mfma_f32_16x16x32_bf16 v[32:35], v[196:199], v[212:215], v[32:35]
	v_mfma_f32_16x16x32_bf16 v[48:51], v[196:199], v[204:207], v[48:51]
	v_mfma_f32_16x16x32_bf16 v[52:55], v[192:195], v[208:211], v[52:55]
	v_mfma_f32_16x16x32_bf16 v[36:39], v[192:195], v[216:219], v[36:39]
	v_mfma_f32_16x16x32_bf16 v[20:23], v[192:195], v[224:227], v[20:23]
	v_mfma_f32_16x16x32_bf16 v[4:7], v[192:195], v[232:235], v[4:7]
	v_mfma_f32_16x16x32_bf16 v[0:3], v[200:203], v[232:235], v[0:3]
	v_mfma_f32_16x16x32_bf16 v[16:19], v[200:203], v[224:227], v[16:19]
	v_mfma_f32_16x16x32_bf16 v[32:35], v[200:203], v[216:219], v[32:35]
	v_mfma_f32_16x16x32_bf16 v[48:51], v[200:203], v[208:211], v[48:51]
	s_setprio 0
	s_barrier
	s_add_i32 s66, 0, 0x1c000
	v_add_u32_e32 v175, s66, v147
	ds_read_b128 v[140:143], v173
	ds_read_b128 v[176:179], v173 offset:1024
	ds_read_b128 v[180:183], v173 offset:2048
	ds_read_b128 v[184:187], v173 offset:3072
	ds_read_b128 v[188:191], v175
	ds_read_b128 v[192:195], v175 offset:1024
	ds_read_b128 v[196:199], v175 offset:2048
	ds_read_b128 v[200:203], v175 offset:3072
	s_add_u32 s42, s42, 0x160000
	s_addc_u32 s43, s43, 0
	s_mov_b32 m0, s47
	v_lshl_add_u64 v[242:243], s[42:43], 0, v[128:129]
	ds_read_b128 v[204:207], v167 offset:32768
	ds_read_b128 v[208:211], v167 offset:33792
	ds_read_b128 v[212:215], v167 offset:34816
	ds_read_b128 v[216:219], v167 offset:35840
	ds_read_b128 v[220:223], v167 offset:36864
	ds_read_b128 v[224:227], v167 offset:37888
	ds_read_b128 v[228:231], v167 offset:38912
	ds_read_b128 v[232:235], v167 offset:39936
	global_load_lds_dwordx4 v[242:243], off
	v_lshl_add_u64 v[242:243], s[42:43], 0, v[130:131]
	s_mov_b32 m0, s48
	s_nop 0
	global_load_lds_dwordx4 v[242:243], off
	s_waitcnt vmcnt(8)
	s_waitcnt lgkmcnt(0)
	s_barrier
	s_setprio 1
	s_waitcnt lgkmcnt(0)
	v_mfma_f32_16x16x32_bf16 v[124:127], v[140:143], v[204:207], v[124:127]
	v_mfma_f32_16x16x32_bf16 v[108:111], v[140:143], v[212:215], v[108:111]
	v_mfma_f32_16x16x32_bf16 v[92:95], v[140:143], v[220:223], v[92:95]
	v_mfma_f32_16x16x32_bf16 v[76:79], v[140:143], v[228:231], v[76:79]
	v_mfma_f32_16x16x32_bf16 v[72:75], v[180:183], v[228:231], v[72:75]
	v_mfma_f32_16x16x32_bf16 v[88:91], v[180:183], v[220:223], v[88:91]
	v_mfma_f32_16x16x32_bf16 v[104:107], v[180:183], v[212:215], v[104:107]
	v_mfma_f32_16x16x32_bf16 v[120:123], v[180:183], v[204:207], v[120:123]
	v_mfma_f32_16x16x32_bf16 v[124:127], v[176:179], v[208:211], v[124:127]
	v_mfma_f32_16x16x32_bf16 v[108:111], v[176:179], v[216:219], v[108:111]
	v_mfma_f32_16x16x32_bf16 v[92:95], v[176:179], v[224:227], v[92:95]
	v_mfma_f32_16x16x32_bf16 v[76:79], v[176:179], v[232:235], v[76:79]
	v_mfma_f32_16x16x32_bf16 v[72:75], v[184:187], v[232:235], v[72:75]
	v_mfma_f32_16x16x32_bf16 v[88:91], v[184:187], v[224:227], v[88:91]
	v_mfma_f32_16x16x32_bf16 v[104:107], v[184:187], v[216:219], v[104:107]
	v_mfma_f32_16x16x32_bf16 v[120:123], v[184:187], v[208:211], v[120:123]
	s_setprio 0
	s_setprio 1
	v_mfma_f32_16x16x32_bf16 v[116:119], v[188:191], v[204:207], v[116:119]
	v_mfma_f32_16x16x32_bf16 v[100:103], v[188:191], v[212:215], v[100:103]
	v_mfma_f32_16x16x32_bf16 v[84:87], v[188:191], v[220:223], v[84:87]
	v_mfma_f32_16x16x32_bf16 v[68:71], v[188:191], v[228:231], v[68:71]
	v_mfma_f32_16x16x32_bf16 v[64:67], v[196:199], v[228:231], v[64:67]
	v_mfma_f32_16x16x32_bf16 v[80:83], v[196:199], v[220:223], v[80:83]
	v_mfma_f32_16x16x32_bf16 v[96:99], v[196:199], v[212:215], v[96:99]
	v_mfma_f32_16x16x32_bf16 v[112:115], v[196:199], v[204:207], v[112:115]
	v_mfma_f32_16x16x32_bf16 v[116:119], v[192:195], v[208:211], v[116:119]
	v_mfma_f32_16x16x32_bf16 v[100:103], v[192:195], v[216:219], v[100:103]
	v_mfma_f32_16x16x32_bf16 v[84:87], v[192:195], v[224:227], v[84:87]
	v_mfma_f32_16x16x32_bf16 v[68:71], v[192:195], v[232:235], v[68:71]
	v_mfma_f32_16x16x32_bf16 v[64:67], v[200:203], v[232:235], v[64:67]
	v_mfma_f32_16x16x32_bf16 v[80:83], v[200:203], v[224:227], v[80:83]
	v_mfma_f32_16x16x32_bf16 v[96:99], v[200:203], v[216:219], v[96:99]
	v_mfma_f32_16x16x32_bf16 v[112:115], v[200:203], v[208:211], v[112:115]
	s_setprio 0
	s_barrier
; #define PG8_STAGE(bufoff, gbase, voff) do { _Pragma("unroll") for (int _i = 0; _i < 2; ++_i) \
;         __builtin_amdgcn_global_load_lds((const unsigned*)((const char*)(gbase) + (voff)[_i]), (PG8_LAS unsigned*)(lds + (bufoff) + ldsw + _i * 8192), 16, 0, 0); } while (0)
; #define PG8_LDA(dst, b, h) do { _Pragma("unroll") for (int m = 0; m < 4; ++m) _Pragma("unroll") for (int k = 0; k < 2; ++k) dst[m][k] = *(const PG8_LAS bf16x8*)(lds + PG8_SA(b, h) + aoff + m * 2048 + k * 1024); } while (0)
; #define PG8_MMA(ai, bj, At, Bt) do { __builtin_amdgcn_s_setprio(1); _Pragma("unroll") for (int m = 0; m < 4; ++m) _Pragma("unroll") for (int n = 0; n < 2; ++n) _Pragma("unroll") for (int k = 0; k < 2; ++k) \
;         acc[ai][bj][m][n] = __builtin_amdgcn_mfma_f32_16x16x32_bf16(Bt[n][k], At[m][k], acc[ai][bj][m][n], 0, 0, 0); __builtin_amdgcn_s_setprio(0); } while (0)
; #define PG8_WAIT_V(n) asm volatile("s_waitcnt vmcnt(" #n ")" ::: "memory")
; #define PG8_WAIT_L(n) asm volatile("s_waitcnt lgkmcnt(" #n ")" ::: "memory")
; #define PG8_BAR __builtin_amdgcn_s_barrier()
; #define PG8_SCHED __builtin_amdgcn_sched_barrier(0)
; template <class Epi, class Sched, bool ALIGN_EPI = false, bool SP2 = false>
; __device__ __forceinline__ void gemm_phase(PG8_LAS unsigned char* lds, const Gemm g, const Sched& S, const Epi& E) {
;     ...
;             PG8_LDA(At, 1, 1); PG8_STAGE(PG8_SB(1, 0), b3, voffB); PG8_STAGE(PG8_SB(1, 1), b3 + hstep, voffB); PG8_STAGE(PG8_SA(1, 0), a3, voffA);
;             PG8_WAIT_V(8); PG8_WAIT_L(0); PG8_BAR; PG8_MMA(1, 0, At, B0); PG8_MMA(1, 1, At, B1); PG8_BAR; PG8_SCHED;
	s_add_i32 s42, s60, s45
	v_lshl_add_u64 v[144:145], v[144:145], 0, s[18:19]
	s_mov_b32 m0, s42
	ds_read_b128 v[204:207], v167 offset:49152
	ds_read_b128 v[208:211], v167 offset:50176
	ds_read_b128 v[212:215], v167 offset:51200
	ds_read_b128 v[216:219], v167 offset:52224
	ds_read_b128 v[220:223], v167 offset:53248
	ds_read_b128 v[224:227], v167 offset:54272
	ds_read_b128 v[228:231], v167 offset:55296
	ds_read_b128 v[232:235], v167 offset:56320
	global_load_lds_dwordx4 v[144:145], off
	s_add_i32 m0, s42, 0x2000
	s_add_u32 s40, s40, 0x160080
	v_lshl_add_u64 v[144:145], v[236:237], 0, s[18:19]
	s_addc_u32 s41, s41, 0
	s_add_i32 s42, s66, s45
	global_load_lds_dwordx4 v[144:145], off
	v_lshl_add_u64 v[144:145], s[40:41], 0, v[128:129]
	s_mov_b32 m0, s42
	s_nop 0
	global_load_lds_dwordx4 v[144:145], off
	v_lshl_add_u64 v[144:145], s[40:41], 0, v[130:131]
	s_add_i32 m0, s42, 0x2000
	s_nop 0
	global_load_lds_dwordx4 v[144:145], off
	v_lshl_add_u64 v[144:145], v[238:239], 0, s[18:19]
	s_mov_b32 m0, s51
	s_nop 0
	global_load_lds_dwordx4 v[144:145], off
	v_lshl_add_u64 v[144:145], v[240:241], 0, s[18:19]
	s_mov_b32 m0, s52
	s_nop 0
	global_load_lds_dwordx4 v[144:145], off
	s_waitcnt vmcnt(8)
	s_waitcnt lgkmcnt(0)
	s_barrier
	s_setprio 1
	s_waitcnt lgkmcnt(0)
	v_mfma_f32_16x16x32_bf16 v[60:63], v[140:143], v[204:207], v[60:63]
	v_mfma_f32_16x16x32_bf16 v[44:47], v[140:143], v[212:215], v[44:47]
	v_mfma_f32_16x16x32_bf16 v[28:31], v[140:143], v[220:223], v[28:31]
	v_mfma_f32_16x16x32_bf16 v[12:15], v[140:143], v[228:231], v[12:15]
	v_mfma_f32_16x16x32_bf16 v[8:11], v[180:183], v[228:231], v[8:11]
	v_mfma_f32_16x16x32_bf16 v[24:27], v[180:183], v[220:223], v[24:27]
	v_mfma_f32_16x16x32_bf16 v[40:43], v[180:183], v[212:215], v[40:43]
	v_mfma_f32_16x16x32_bf16 v[56:59], v[180:183], v[204:207], v[56:59]
	v_mfma_f32_16x16x32_bf16 v[60:63], v[176:179], v[208:211], v[60:63]
	v_mfma_f32_16x16x32_bf16 v[44:47], v[176:179], v[216:219], v[44:47]
	v_mfma_f32_16x16x32_bf16 v[28:31], v[176:179], v[224:227], v[28:31]
	v_mfma_f32_16x16x32_bf16 v[12:15], v[176:179], v[232:235], v[12:15]
	v_mfma_f32_16x16x32_bf16 v[8:11], v[184:187], v[232:235], v[8:11]
	v_mfma_f32_16x16x32_bf16 v[24:27], v[184:187], v[224:227], v[24:27]
	v_mfma_f32_16x16x32_bf16 v[40:43], v[184:187], v[216:219], v[40:43]
	v_mfma_f32_16x16x32_bf16 v[56:59], v[184:187], v[208:211], v[56:59]
	s_setprio 0
	s_setprio 1
	v_mfma_f32_16x16x32_bf16 v[52:55], v[188:191], v[204:207], v[52:55]
	v_mfma_f32_16x16x32_bf16 v[36:39], v[188:191], v[212:215], v[36:39]
	v_mfma_f32_16x16x32_bf16 v[20:23], v[188:191], v[220:223], v[20:23]
	v_mfma_f32_16x16x32_bf16 v[4:7], v[188:191], v[228:231], v[4:7]
	v_mfma_f32_16x16x32_bf16 v[0:3], v[196:199], v[228:231], v[0:3]
	v_mfma_f32_16x16x32_bf16 v[16:19], v[196:199], v[220:223], v[16:19]
	v_mfma_f32_16x16x32_bf16 v[32:35], v[196:199], v[212:215], v[32:35]
	v_mfma_f32_16x16x32_bf16 v[48:51], v[196:199], v[204:207], v[48:51]
	v_mfma_f32_16x16x32_bf16 v[52:55], v[192:195], v[208:211], v[52:55]
	v_mfma_f32_16x16x32_bf16 v[36:39], v[192:195], v[216:219], v[36:39]
	v_mfma_f32_16x16x32_bf16 v[20:23], v[192:195], v[224:227], v[20:23]
	v_mfma_f32_16x16x32_bf16 v[4:7], v[192:195], v[232:235], v[4:7]
	v_mfma_f32_16x16x32_bf16 v[0:3], v[200:203], v[232:235], v[0:3]
	v_mfma_f32_16x16x32_bf16 v[16:19], v[200:203], v[224:227], v[16:19]
	v_mfma_f32_16x16x32_bf16 v[32:35], v[200:203], v[216:219], v[32:35]
	v_mfma_f32_16x16x32_bf16 v[48:51], v[200:203], v[208:211], v[48:51]
	s_setprio 0
	s_barrier
	s_add_i32 s65, s65, 2
	s_add_u32 s8, s8, 0x100
	s_addc_u32 s9, s9, 0
	s_add_u32 s38, s38, 0x100
	s_addc_u32 s39, s39, 0
	s_cmpk_gt_u32 s65, 0x55
	s_cbranch_scc0 .LBB0_649
	s_and_b64 vcc, exec, s[22:23]
	s_cbranch_vccz .LBB0_652
	s_barrier
